# merge gate/branch GEMM loops: second MFMA group of each k-step at s_setprio 2
# baseline (speedup 1.0000x reference)
; DEVI f32x4 mfma16(bf16x8 a, bf16x8 b, f32x4 c) { return __builtin_amdgcn_mfma_f32_16x16x32_bf16(a, b, c, 0, 0, 0); }
; template <int NTW, bool SPLIT = false, bool HALFA = false>
; DEVI void gemm_core2(f32x4 (&acc)[4][NTW], const bf* __restrict__ A, int lda, const bf* __restrict__ Bt, int ldb, int K, char* smem) {
;     ...
;       for (int ks = 0; ks < 2; ++ks) {
;         const int swz = ks ? sw1 : sw0;
;         bf16x8 af[4], bfr[NTW];
; #pragma unroll
;         for (int m = 0; m < 4; ++m) af[m] = *reinterpret_cast<const bf16x8*>(abase + so + m * 16 * 128 + swz);
; #pragma unroll
;         for (int n = 0; n < NTW; ++n) bfr[n] = *reinterpret_cast<const bf16x8*>(bbase + so + n * 16 * 128 + swz);
;         if (ks == 1) {
; #pragma unroll
;           for (int i = 0; i < 4; ++i) glds16(Ap + i * sa + k1, dbase + sn + i * 4096);
; #pragma unroll
;           for (int i = 0; i < NBL; ++i) glds16(Bp + i * sb + k1, dbase + sn + ASZ + i * 4096);
;         }
;         __builtin_amdgcn_s_setprio(1);
; #pragma unroll
;         for (int m = 0; m < 4; ++m)
; #pragma unroll
;           for (int n = 0; n < NTW; ++n) acc[m][n] = mfma16(af[m], bfr[n], acc[m][n]);
;         __builtin_amdgcn_s_setprio(0);
;       }
;     }
;     __builtin_amdgcn_s_setprio(0);
;     __syncthreads();
.LBB0_215:
	s_add_i32 s20, s17, 0x8000
	s_and_b32 s17, s17, 0x8000
	v_or_b32_e32 v192, s17, v73
	v_add_u32_e32 v193, s17, v2
	v_add_u32_e32 v88, v192, v74
	v_add_u32_e32 v170, v193, v74
	ds_read_b128 v[76:79], v88 offset:22528
	ds_read_b128 v[80:83], v88 offset:20480
	ds_read_b128 v[84:87], v88 offset:18432
	ds_read_b128 v[88:91], v88 offset:16384
	ds_read_b128 v[158:161], v170 offset:6144
	ds_read_b128 v[162:165], v170 offset:4096
	ds_read_b128 v[166:169], v170 offset:2048
	ds_read_b128 v[170:173], v170
	s_min_u32 s18, s13, 0x3c0
	s_and_b32 s21, s20, 0x8000
	s_lshl_b32 s96, s18, 1
	v_add_u32_e32 v194, s21, v72
	v_lshl_add_u64 v[174:175], v[68:69], 0, s[96:97]
	v_lshl_add_u64 v[176:177], v[70:71], 0, s[96:97]
	v_add_u32_e32 v195, 0x4000, v194
	s_setprio 1
	s_waitcnt lgkmcnt(0)
	v_mfma_f32_16x16x32_bf16 v[64:67], v[170:173], v[88:91], v[64:67]
	v_mfma_f32_16x16x32_bf16 v[60:63], v[170:173], v[84:87], v[60:63]
	v_mfma_f32_16x16x32_bf16 v[56:59], v[170:173], v[80:83], v[56:59]
	v_mfma_f32_16x16x32_bf16 v[52:55], v[170:173], v[76:79], v[52:55]
	v_mfma_f32_16x16x32_bf16 v[48:51], v[166:169], v[88:91], v[48:51]
	v_mfma_f32_16x16x32_bf16 v[44:47], v[166:169], v[84:87], v[44:47]
	v_mfma_f32_16x16x32_bf16 v[40:43], v[166:169], v[80:83], v[40:43]
	v_mfma_f32_16x16x32_bf16 v[36:39], v[166:169], v[76:79], v[36:39]
	v_mfma_f32_16x16x32_bf16 v[32:35], v[162:165], v[88:91], v[32:35]
	v_mfma_f32_16x16x32_bf16 v[28:31], v[162:165], v[84:87], v[28:31]
	v_mfma_f32_16x16x32_bf16 v[24:27], v[162:165], v[80:83], v[24:27]
	v_mfma_f32_16x16x32_bf16 v[20:23], v[162:165], v[76:79], v[20:23]
	v_mfma_f32_16x16x32_bf16 v[16:19], v[158:161], v[88:91], v[16:19]
	v_mfma_f32_16x16x32_bf16 v[12:15], v[158:161], v[84:87], v[12:15]
	v_mfma_f32_16x16x32_bf16 v[8:11], v[158:161], v[80:83], v[8:11]
	v_mfma_f32_16x16x32_bf16 v[4:7], v[158:161], v[76:79], v[4:7]
	s_setprio 0
	v_readfirstlane_b32 s17, v194
	v_add_u32_e32 v196, 0x1000, v194
	v_add_u32_e32 v88, v193, v75
	v_add_u32_e32 v170, v192, v75
	s_mov_b32 m0, s17
	v_readfirstlane_b32 s17, v196
	v_add_u32_e32 v196, 0x2000, v194
	ds_read_b128 v[76:79], v88
	ds_read_b128 v[80:83], v88 offset:2048
	ds_read_b128 v[84:87], v88 offset:4096
	ds_read_b128 v[88:91], v88 offset:6144
	ds_read_b128 v[158:161], v170 offset:16384
	ds_read_b128 v[162:165], v170 offset:18432
	ds_read_b128 v[166:169], v170 offset:20480
	ds_read_b128 v[170:173], v170 offset:22528
	global_load_lds_dwordx4 v[174:175], off
	v_lshl_add_u64 v[192:193], v[174:175], 0, s[14:15]
	s_mov_b32 m0, s17
	v_readfirstlane_b32 s17, v196
	global_load_lds_dwordx4 v[192:193], off
	v_lshl_add_u64 v[192:193], v[174:175], 0, s[4:5]
	s_mov_b32 m0, s17
	v_lshl_add_u64 v[174:175], v[174:175], 0, s[94:95]
	global_load_lds_dwordx4 v[192:193], off
	v_add_u32_e32 v192, 0x3000, v194
	s_nop 0
	v_readfirstlane_b32 s17, v192
	s_mov_b32 m0, s17
	v_readfirstlane_b32 s17, v195
	v_add_u32_e32 v192, 0x5000, v194
	global_load_lds_dwordx4 v[174:175], off
	s_mov_b32 m0, s17
	v_readfirstlane_b32 s17, v192
	v_add_u32_e32 v192, 0x6000, v194
	global_load_lds_dwordx4 v[176:177], off
	v_lshl_add_u64 v[174:175], v[176:177], 0, s[14:15]
	s_mov_b32 m0, s17
	v_readfirstlane_b32 s17, v192
	global_load_lds_dwordx4 v[174:175], off
	v_lshl_add_u64 v[174:175], v[176:177], 0, s[4:5]
	s_mov_b32 m0, s17
	s_nop 0
	global_load_lds_dwordx4 v[174:175], off
	v_lshl_add_u64 v[174:175], v[176:177], 0, s[94:95]
	v_add_u32_e32 v176, 0x7000, v194
	s_nop 0
	v_readfirstlane_b32 s17, v176
	s_mov_b32 m0, s17
	s_nop 0
	global_load_lds_dwordx4 v[174:175], off
	s_setprio 2
	s_waitcnt lgkmcnt(0)
	v_mfma_f32_16x16x32_bf16 v[64:67], v[76:79], v[158:161], v[64:67]
	v_mfma_f32_16x16x32_bf16 v[60:63], v[76:79], v[162:165], v[60:63]
	v_mfma_f32_16x16x32_bf16 v[56:59], v[76:79], v[166:169], v[56:59]
	v_mfma_f32_16x16x32_bf16 v[52:55], v[76:79], v[170:173], v[52:55]
	v_mfma_f32_16x16x32_bf16 v[48:51], v[80:83], v[158:161], v[48:51]
	v_mfma_f32_16x16x32_bf16 v[44:47], v[80:83], v[162:165], v[44:47]
	v_mfma_f32_16x16x32_bf16 v[40:43], v[80:83], v[166:169], v[40:43]
	v_mfma_f32_16x16x32_bf16 v[36:39], v[80:83], v[170:173], v[36:39]
	v_mfma_f32_16x16x32_bf16 v[32:35], v[84:87], v[158:161], v[32:35]
	v_mfma_f32_16x16x32_bf16 v[28:31], v[84:87], v[162:165], v[28:31]
	v_mfma_f32_16x16x32_bf16 v[24:27], v[84:87], v[166:169], v[24:27]
	v_mfma_f32_16x16x32_bf16 v[20:23], v[84:87], v[170:173], v[20:23]
	v_mfma_f32_16x16x32_bf16 v[16:19], v[88:91], v[158:161], v[16:19]
	v_mfma_f32_16x16x32_bf16 v[12:15], v[88:91], v[162:165], v[12:15]
	v_mfma_f32_16x16x32_bf16 v[8:11], v[88:91], v[166:169], v[8:11]
	v_mfma_f32_16x16x32_bf16 v[4:7], v[88:91], v[170:173], v[4:7]
	s_setprio 0
	s_setprio 0
	s_add_i32 s13, s13, 64
	s_cmp_lg_u32 s20, 0x80000
	s_mov_b32 s17, s20
	s_waitcnt vmcnt(0)
	s_barrier
	s_cbranch_scc1 .LBB0_215
; DEVI unsigned pack2(float a, float b) { f32x2_t v = {a, b}; bf16x2_t r = __builtin_convertvector(v, bf16x2_t); return *reinterpret_cast<unsigned*>(&r); }
; DEVI float sigm(float x) { return 1.f / (1.f + __expf(-x)); }
; template <int NTW>
; DEVI void merge_tile(const P& p, long row0, int n0, char* smem) {
;     ...
; #pragma unroll
;       for (int m = 0; m < 4; ++m)
; #pragma unroll
;         for (int n = 0; n < NTW; ++n) {
;           pg[m][n][0] = pack2(sigm(accT[m][n][0]), sigm(accT[m][n][1]));
;           pg[m][n][1] = pack2(sigm(accT[m][n][2]), sigm(accT[m][n][3]));
;         }
	v_mul_f32_e32 v2, 0xbfb8aa3b, v64
	v_exp_f32_e32 v64, v2
	v_mul_f32_e32 v2, 0xbfb8aa3b, v65
	v_exp_f32_e32 v65, v2
	s_lshl_b32 s13, s3, 9
	v_readlane_b32 s48, v252, 27
	v_readlane_b32 s54, v252, 33
	v_pk_add_f32 v[64:65], v[64:65], 1.0 op_sel_hi:[1,0]
	v_readlane_b32 s55, v252, 34
	v_div_scale_f32 v2, s[20:21], v65, v65, 1.0
	v_rcp_f32_e32 v68, v2
	v_readlane_b32 s50, v252, 29
	v_readlane_b32 s49, v252, 28
	v_readlane_b32 s52, v252, 31
	v_fma_f32 v69, -v2, v68, 1.0
	v_fmac_f32_e32 v68, v69, v68
	v_div_scale_f32 v69, vcc, 1.0, v65, 1.0
	v_mul_f32_e32 v70, v69, v68
	v_fma_f32 v71, -v2, v70, v69
	v_fmac_f32_e32 v70, v71, v68
	v_fma_f32 v2, -v2, v70, v69
	v_div_fmas_f32 v2, v2, v68, v70
	v_div_fixup_f32 v2, v2, v65, 1.0
	v_div_scale_f32 v65, s[20:21], v64, v64, 1.0
	v_rcp_f32_e32 v68, v65
	v_readlane_b32 s53, v252, 32
	v_readlane_b32 s51, v252, 30
	v_readlane_b32 s56, v252, 35
	v_fma_f32 v69, -v65, v68, 1.0
	v_fmac_f32_e32 v68, v69, v68
	v_div_scale_f32 v69, vcc, 1.0, v64, 1.0
	v_mul_f32_e32 v70, v69, v68
	v_fma_f32 v71, -v65, v70, v69
	v_fmac_f32_e32 v70, v71, v68
	v_fma_f32 v65, -v65, v70, v69
	v_div_fmas_f32 v65, v65, v68, v70
	v_div_fixup_f32 v64, v65, v64, 1.0
	v_cvt_pk_bf16_f32 v166, v64, v2
	v_mul_f32_e32 v2, 0xbfb8aa3b, v66
	v_exp_f32_e32 v64, v2
	v_mul_f32_e32 v2, 0xbfb8aa3b, v67
	v_exp_f32_e32 v65, v2
	v_readlane_b32 s57, v252, 36
	v_readlane_b32 s58, v252, 37
	v_readlane_b32 s59, v252, 38
	v_pk_add_f32 v[64:65], v[64:65], 1.0 op_sel_hi:[1,0]
	v_readlane_b32 s60, v252, 39
	v_div_scale_f32 v2, s[20:21], v65, v65, 1.0
	v_rcp_f32_e32 v66, v2
	v_readlane_b32 s61, v252, 40
	v_readlane_b32 s62, v252, 41
	v_readlane_b32 s63, v252, 42
	v_fma_f32 v67, -v2, v66, 1.0
	v_fmac_f32_e32 v66, v67, v66
	v_div_scale_f32 v67, vcc, 1.0, v65, 1.0
	v_mul_f32_e32 v68, v67, v66
	v_fma_f32 v69, -v2, v68, v67
	v_fmac_f32_e32 v68, v69, v66
	v_fma_f32 v2, -v2, v68, v67
	v_div_fmas_f32 v2, v2, v66, v68
	v_div_fixup_f32 v2, v2, v65, 1.0
	v_div_scale_f32 v65, s[20:21], v64, v64, 1.0
	v_rcp_f32_e32 v66, v65
	s_nop 0
	v_fma_f32 v67, -v65, v66, 1.0
	v_fmac_f32_e32 v66, v67, v66
	v_div_scale_f32 v67, vcc, 1.0, v64, 1.0
	v_mul_f32_e32 v68, v67, v66
	v_fma_f32 v69, -v65, v68, v67
	v_fmac_f32_e32 v68, v69, v66
	v_fma_f32 v65, -v65, v68, v67
	v_div_fmas_f32 v65, v65, v66, v68
	v_div_fixup_f32 v64, v65, v64, 1.0
	v_cvt_pk_bf16_f32 v167, v64, v2
	v_mul_f32_e32 v2, 0xbfb8aa3b, v60
	v_exp_f32_e32 v60, v2
	v_mul_f32_e32 v2, 0xbfb8aa3b, v61
	v_exp_f32_e32 v61, v2
	s_nop 0
	v_pk_add_f32 v[60:61], v[60:61], 1.0 op_sel_hi:[1,0]
	s_nop 0
	v_div_scale_f32 v2, s[20:21], v61, v61, 1.0
	v_rcp_f32_e32 v64, v2
	s_nop 0
	v_fma_f32 v65, -v2, v64, 1.0
	v_fmac_f32_e32 v64, v65, v64
	v_div_scale_f32 v65, vcc, 1.0, v61, 1.0
	v_mul_f32_e32 v66, v65, v64
	v_fma_f32 v67, -v2, v66, v65
	v_fmac_f32_e32 v66, v67, v64
	v_fma_f32 v2, -v2, v66, v65
	v_div_fmas_f32 v2, v2, v64, v66
	v_div_fixup_f32 v2, v2, v61, 1.0
	v_div_scale_f32 v61, s[20:21], v60, v60, 1.0
	v_rcp_f32_e32 v64, v61
	s_nop 0
	v_fma_f32 v65, -v61, v64, 1.0
	v_fmac_f32_e32 v64, v65, v64
	v_div_scale_f32 v65, vcc, 1.0, v60, 1.0
	v_mul_f32_e32 v66, v65, v64
	v_fma_f32 v67, -v61, v66, v65
	v_fmac_f32_e32 v66, v67, v64
	v_fma_f32 v61, -v61, v66, v65
	v_div_fmas_f32 v61, v61, v64, v66
	v_div_fixup_f32 v60, v61, v60, 1.0
	v_cvt_pk_bf16_f32 v168, v60, v2
	v_mul_f32_e32 v2, 0xbfb8aa3b, v62
	v_exp_f32_e32 v60, v2
	v_mul_f32_e32 v2, 0xbfb8aa3b, v63
	v_exp_f32_e32 v61, v2
	s_nop 0
	v_pk_add_f32 v[60:61], v[60:61], 1.0 op_sel_hi:[1,0]
	s_nop 0
	v_div_scale_f32 v2, s[20:21], v61, v61, 1.0
	v_rcp_f32_e32 v62, v2
	s_nop 0
	v_fma_f32 v63, -v2, v62, 1.0
	v_fmac_f32_e32 v62, v63, v62
	v_div_scale_f32 v63, vcc, 1.0, v61, 1.0
	v_mul_f32_e32 v64, v63, v62
	v_fma_f32 v65, -v2, v64, v63
	v_fmac_f32_e32 v64, v65, v62
	v_fma_f32 v2, -v2, v64, v63
	v_div_fmas_f32 v2, v2, v62, v64
	v_div_fixup_f32 v2, v2, v61, 1.0
	v_div_scale_f32 v61, s[20:21], v60, v60, 1.0
	v_rcp_f32_e32 v62, v61
	s_nop 0
	v_fma_f32 v63, -v61, v62, 1.0
	v_fmac_f32_e32 v62, v63, v62
	v_div_scale_f32 v63, vcc, 1.0, v60, 1.0
	v_mul_f32_e32 v64, v63, v62
	v_fma_f32 v65, -v61, v64, v63
	v_fmac_f32_e32 v64, v65, v62
	v_fma_f32 v61, -v61, v64, v63
	v_div_fmas_f32 v61, v61, v62, v64
	v_div_fixup_f32 v60, v61, v60, 1.0
	v_cvt_pk_bf16_f32 v169, v60, v2
	v_mul_f32_e32 v2, 0xbfb8aa3b, v56
	v_exp_f32_e32 v56, v2
	v_mul_f32_e32 v2, 0xbfb8aa3b, v57
	v_exp_f32_e32 v57, v2
	s_nop 0
	v_pk_add_f32 v[56:57], v[56:57], 1.0 op_sel_hi:[1,0]
	s_nop 0
	v_div_scale_f32 v2, s[20:21], v57, v57, 1.0
	v_rcp_f32_e32 v60, v2
	s_nop 0
	v_fma_f32 v61, -v2, v60, 1.0
	v_fmac_f32_e32 v60, v61, v60
	v_div_scale_f32 v61, vcc, 1.0, v57, 1.0
	v_mul_f32_e32 v62, v61, v60
	v_fma_f32 v63, -v2, v62, v61
	v_fmac_f32_e32 v62, v63, v60
	v_fma_f32 v2, -v2, v62, v61
	v_div_fmas_f32 v2, v2, v60, v62
	v_div_fixup_f32 v2, v2, v57, 1.0
	v_div_scale_f32 v57, s[20:21], v56, v56, 1.0
	v_rcp_f32_e32 v60, v57
	s_nop 0
	v_fma_f32 v61, -v57, v60, 1.0
	v_fmac_f32_e32 v60, v61, v60
	v_div_scale_f32 v61, vcc, 1.0, v56, 1.0
	v_mul_f32_e32 v62, v61, v60
	v_fma_f32 v63, -v57, v62, v61
	v_fmac_f32_e32 v62, v63, v60
	v_fma_f32 v57, -v57, v62, v61
	v_div_fmas_f32 v57, v57, v60, v62
	v_div_fixup_f32 v56, v57, v56, 1.0
	v_cvt_pk_bf16_f32 v170, v56, v2
	v_mul_f32_e32 v2, 0xbfb8aa3b, v58
	v_exp_f32_e32 v56, v2
	v_mul_f32_e32 v2, 0xbfb8aa3b, v59
	v_exp_f32_e32 v57, v2
	s_nop 0
	v_pk_add_f32 v[56:57], v[56:57], 1.0 op_sel_hi:[1,0]
	s_nop 0
	v_div_scale_f32 v2, s[20:21], v57, v57, 1.0
	v_rcp_f32_e32 v58, v2
	s_nop 0
	v_fma_f32 v59, -v2, v58, 1.0
	v_fmac_f32_e32 v58, v59, v58
	v_div_scale_f32 v59, vcc, 1.0, v57, 1.0
	v_mul_f32_e32 v60, v59, v58
	v_fma_f32 v61, -v2, v60, v59
; DEVI unsigned pack2(float a, float b) { f32x2_t v = {a, b}; bf16x2_t r = __builtin_convertvector(v, bf16x2_t); return *reinterpret_cast<unsigned*>(&r); }
; DEVI float sigm(float x) { return 1.f / (1.f + __expf(-x)); }
; template <int NTW>
; DEVI void merge_tile(const P& p, long row0, int n0, char* smem) {
;     ...
; #pragma unroll
;       for (int m = 0; m < 4; ++m)
; #pragma unroll
;         for (int n = 0; n < NTW; ++n) {
;           pg[m][n][0] = pack2(sigm(accT[m][n][0]), sigm(accT[m][n][1]));
;           pg[m][n][1] = pack2(sigm(accT[m][n][2]), sigm(accT[m][n][3]));
;         }
	v_fmac_f32_e32 v60, v61, v58
	v_fma_f32 v2, -v2, v60, v59
	v_div_fmas_f32 v2, v2, v58, v60
	v_div_fixup_f32 v2, v2, v57, 1.0
	v_div_scale_f32 v57, s[20:21], v56, v56, 1.0
	v_rcp_f32_e32 v58, v57
	s_nop 0
	v_fma_f32 v59, -v57, v58, 1.0
	v_fmac_f32_e32 v58, v59, v58
	v_div_scale_f32 v59, vcc, 1.0, v56, 1.0
	v_mul_f32_e32 v60, v59, v58
	v_fma_f32 v61, -v57, v60, v59
	v_fmac_f32_e32 v60, v61, v58
	v_fma_f32 v57, -v57, v60, v59
	v_div_fmas_f32 v57, v57, v58, v60
	v_div_fixup_f32 v56, v57, v56, 1.0
	v_cvt_pk_bf16_f32 v171, v56, v2
	v_mul_f32_e32 v2, 0xbfb8aa3b, v52
	v_exp_f32_e32 v52, v2
	v_mul_f32_e32 v2, 0xbfb8aa3b, v53
	v_exp_f32_e32 v53, v2
	s_nop 0
	v_pk_add_f32 v[52:53], v[52:53], 1.0 op_sel_hi:[1,0]
	s_nop 0
	v_div_scale_f32 v2, s[20:21], v53, v53, 1.0
	v_rcp_f32_e32 v56, v2
	s_nop 0
	v_fma_f32 v57, -v2, v56, 1.0
	v_fmac_f32_e32 v56, v57, v56
	v_div_scale_f32 v57, vcc, 1.0, v53, 1.0
	v_mul_f32_e32 v58, v57, v56
	v_fma_f32 v59, -v2, v58, v57
	v_fmac_f32_e32 v58, v59, v56
	v_fma_f32 v2, -v2, v58, v57
	v_div_fmas_f32 v2, v2, v56, v58
	v_div_fixup_f32 v2, v2, v53, 1.0
	v_div_scale_f32 v53, s[20:21], v52, v52, 1.0
	v_rcp_f32_e32 v56, v53
	s_nop 0
	v_fma_f32 v57, -v53, v56, 1.0
	v_fmac_f32_e32 v56, v57, v56
	v_div_scale_f32 v57, vcc, 1.0, v52, 1.0
	v_mul_f32_e32 v58, v57, v56
	v_fma_f32 v59, -v53, v58, v57
	v_fmac_f32_e32 v58, v59, v56
	v_fma_f32 v53, -v53, v58, v57
	v_div_fmas_f32 v53, v53, v56, v58
	v_div_fixup_f32 v52, v53, v52, 1.0
	v_cvt_pk_bf16_f32 v172, v52, v2
	v_mul_f32_e32 v2, 0xbfb8aa3b, v54
	v_exp_f32_e32 v52, v2
	v_mul_f32_e32 v2, 0xbfb8aa3b, v55
	v_exp_f32_e32 v53, v2
	s_nop 0
	v_pk_add_f32 v[52:53], v[52:53], 1.0 op_sel_hi:[1,0]
	s_nop 0
	v_div_scale_f32 v2, s[20:21], v53, v53, 1.0
	v_rcp_f32_e32 v54, v2
	s_nop 0
	v_fma_f32 v55, -v2, v54, 1.0
	v_fmac_f32_e32 v54, v55, v54
	v_div_scale_f32 v55, vcc, 1.0, v53, 1.0
	v_mul_f32_e32 v56, v55, v54
	v_fma_f32 v57, -v2, v56, v55
	v_fmac_f32_e32 v56, v57, v54
	v_fma_f32 v2, -v2, v56, v55
	v_div_fmas_f32 v2, v2, v54, v56
	v_div_fixup_f32 v2, v2, v53, 1.0
	v_div_scale_f32 v53, s[20:21], v52, v52, 1.0
	v_rcp_f32_e32 v54, v53
	s_nop 0
	v_fma_f32 v55, -v53, v54, 1.0
	v_fmac_f32_e32 v54, v55, v54
	v_div_scale_f32 v55, vcc, 1.0, v52, 1.0
	v_mul_f32_e32 v56, v55, v54
	v_fma_f32 v57, -v53, v56, v55
	v_fmac_f32_e32 v56, v57, v54
	v_fma_f32 v53, -v53, v56, v55
	v_div_fmas_f32 v53, v53, v54, v56
	v_div_fixup_f32 v52, v53, v52, 1.0
	v_cvt_pk_bf16_f32 v173, v52, v2
	v_mul_f32_e32 v2, 0xbfb8aa3b, v48
	v_exp_f32_e32 v48, v2
	v_mul_f32_e32 v2, 0xbfb8aa3b, v49
	v_exp_f32_e32 v49, v2
	s_nop 0
	v_pk_add_f32 v[48:49], v[48:49], 1.0 op_sel_hi:[1,0]
	s_nop 0
	v_div_scale_f32 v2, s[20:21], v49, v49, 1.0
	v_rcp_f32_e32 v52, v2
	s_nop 0
	v_fma_f32 v53, -v2, v52, 1.0
	v_fmac_f32_e32 v52, v53, v52
	v_div_scale_f32 v53, vcc, 1.0, v49, 1.0
	v_mul_f32_e32 v54, v53, v52
	v_fma_f32 v55, -v2, v54, v53
	v_fmac_f32_e32 v54, v55, v52
	v_fma_f32 v2, -v2, v54, v53
	v_div_fmas_f32 v2, v2, v52, v54
	v_div_fixup_f32 v2, v2, v49, 1.0
	v_div_scale_f32 v49, s[20:21], v48, v48, 1.0
	v_rcp_f32_e32 v52, v49
	s_nop 0
	v_fma_f32 v53, -v49, v52, 1.0
	v_fmac_f32_e32 v52, v53, v52
	v_div_scale_f32 v53, vcc, 1.0, v48, 1.0
	v_mul_f32_e32 v54, v53, v52
	v_fma_f32 v55, -v49, v54, v53
	v_fmac_f32_e32 v54, v55, v52
	v_fma_f32 v49, -v49, v54, v53
	v_div_fmas_f32 v49, v49, v52, v54
	v_div_fixup_f32 v48, v49, v48, 1.0
	v_cvt_pk_bf16_f32 v174, v48, v2
	v_mul_f32_e32 v2, 0xbfb8aa3b, v50
	v_exp_f32_e32 v48, v2
	v_mul_f32_e32 v2, 0xbfb8aa3b, v51
	v_exp_f32_e32 v49, v2
	s_nop 0
	v_pk_add_f32 v[48:49], v[48:49], 1.0 op_sel_hi:[1,0]
	s_nop 0
	v_div_scale_f32 v2, s[20:21], v49, v49, 1.0
	v_rcp_f32_e32 v50, v2
	s_nop 0
	v_fma_f32 v51, -v2, v50, 1.0
	v_fmac_f32_e32 v50, v51, v50
	v_div_scale_f32 v51, vcc, 1.0, v49, 1.0
	v_mul_f32_e32 v52, v51, v50
	v_fma_f32 v53, -v2, v52, v51
	v_fmac_f32_e32 v52, v53, v50
	v_fma_f32 v2, -v2, v52, v51
	v_div_fmas_f32 v2, v2, v50, v52
	v_div_fixup_f32 v2, v2, v49, 1.0
	v_div_scale_f32 v49, s[20:21], v48, v48, 1.0
	v_rcp_f32_e32 v50, v49
	s_nop 0
	v_fma_f32 v51, -v49, v50, 1.0
	v_fmac_f32_e32 v50, v51, v50
	v_div_scale_f32 v51, vcc, 1.0, v48, 1.0
	v_mul_f32_e32 v52, v51, v50
	v_fma_f32 v53, -v49, v52, v51
	v_fmac_f32_e32 v52, v53, v50
	v_fma_f32 v49, -v49, v52, v51
	v_div_fmas_f32 v49, v49, v50, v52
	v_div_fixup_f32 v48, v49, v48, 1.0
	v_cvt_pk_bf16_f32 v175, v48, v2
	v_mul_f32_e32 v2, 0xbfb8aa3b, v44
	v_exp_f32_e32 v44, v2
	v_mul_f32_e32 v2, 0xbfb8aa3b, v45
	v_exp_f32_e32 v45, v2
	s_nop 0
	v_pk_add_f32 v[44:45], v[44:45], 1.0 op_sel_hi:[1,0]
	s_nop 0
	v_div_scale_f32 v2, s[20:21], v45, v45, 1.0
	v_rcp_f32_e32 v48, v2
	s_nop 0
	v_fma_f32 v49, -v2, v48, 1.0
	v_fmac_f32_e32 v48, v49, v48
	v_div_scale_f32 v49, vcc, 1.0, v45, 1.0
	v_mul_f32_e32 v50, v49, v48
	v_fma_f32 v51, -v2, v50, v49
	v_fmac_f32_e32 v50, v51, v48
	v_fma_f32 v2, -v2, v50, v49
	v_div_fmas_f32 v2, v2, v48, v50
	v_div_fixup_f32 v2, v2, v45, 1.0
	v_div_scale_f32 v45, s[20:21], v44, v44, 1.0
	v_rcp_f32_e32 v48, v45
	s_nop 0
	v_fma_f32 v49, -v45, v48, 1.0
	v_fmac_f32_e32 v48, v49, v48
	v_div_scale_f32 v49, vcc, 1.0, v44, 1.0
	v_mul_f32_e32 v50, v49, v48
	v_fma_f32 v51, -v45, v50, v49
	v_fmac_f32_e32 v50, v51, v48
	v_fma_f32 v45, -v45, v50, v49
	v_div_fmas_f32 v45, v45, v48, v50
	v_div_fixup_f32 v44, v45, v44, 1.0
	v_cvt_pk_bf16_f32 v176, v44, v2
	v_mul_f32_e32 v2, 0xbfb8aa3b, v46
	v_exp_f32_e32 v44, v2
	v_mul_f32_e32 v2, 0xbfb8aa3b, v47
	v_exp_f32_e32 v45, v2
	s_nop 0
	v_pk_add_f32 v[44:45], v[44:45], 1.0 op_sel_hi:[1,0]
	s_nop 0
	v_div_scale_f32 v2, s[20:21], v45, v45, 1.0
	v_rcp_f32_e32 v46, v2
	s_nop 0
	v_fma_f32 v47, -v2, v46, 1.0
	v_fmac_f32_e32 v46, v47, v46
; DEVI unsigned pack2(float a, float b) { f32x2_t v = {a, b}; bf16x2_t r = __builtin_convertvector(v, bf16x2_t); return *reinterpret_cast<unsigned*>(&r); }
; DEVI float sigm(float x) { return 1.f / (1.f + __expf(-x)); }
; template <int NTW>
; DEVI void merge_tile(const P& p, long row0, int n0, char* smem) {
;     ...
; #pragma unroll
;       for (int m = 0; m < 4; ++m)
; #pragma unroll
;         for (int n = 0; n < NTW; ++n) {
;           pg[m][n][0] = pack2(sigm(accT[m][n][0]), sigm(accT[m][n][1]));
;           pg[m][n][1] = pack2(sigm(accT[m][n][2]), sigm(accT[m][n][3]));
;         }
	v_div_scale_f32 v47, vcc, 1.0, v45, 1.0
	v_mul_f32_e32 v48, v47, v46
	v_fma_f32 v49, -v2, v48, v47
	v_fmac_f32_e32 v48, v49, v46
	v_fma_f32 v2, -v2, v48, v47
	v_div_fmas_f32 v2, v2, v46, v48
	v_div_fixup_f32 v2, v2, v45, 1.0
	v_div_scale_f32 v45, s[20:21], v44, v44, 1.0
	v_rcp_f32_e32 v46, v45
	s_nop 0
	v_fma_f32 v47, -v45, v46, 1.0
	v_fmac_f32_e32 v46, v47, v46
	v_div_scale_f32 v47, vcc, 1.0, v44, 1.0
	v_mul_f32_e32 v48, v47, v46
	v_fma_f32 v49, -v45, v48, v47
	v_fmac_f32_e32 v48, v49, v46
	v_fma_f32 v45, -v45, v48, v47
	v_div_fmas_f32 v45, v45, v46, v48
	v_div_fixup_f32 v44, v45, v44, 1.0
	v_cvt_pk_bf16_f32 v177, v44, v2
	v_mul_f32_e32 v2, 0xbfb8aa3b, v40
	v_exp_f32_e32 v40, v2
	v_mul_f32_e32 v2, 0xbfb8aa3b, v41
	v_exp_f32_e32 v41, v2
	s_nop 0
	v_pk_add_f32 v[40:41], v[40:41], 1.0 op_sel_hi:[1,0]
	s_nop 0
	v_div_scale_f32 v2, s[20:21], v41, v41, 1.0
	v_rcp_f32_e32 v44, v2
	s_nop 0
	v_fma_f32 v45, -v2, v44, 1.0
	v_fmac_f32_e32 v44, v45, v44
	v_div_scale_f32 v45, vcc, 1.0, v41, 1.0
	v_mul_f32_e32 v46, v45, v44
	v_fma_f32 v47, -v2, v46, v45
	v_fmac_f32_e32 v46, v47, v44
	v_fma_f32 v2, -v2, v46, v45
	v_div_fmas_f32 v2, v2, v44, v46
	v_div_fixup_f32 v2, v2, v41, 1.0
	v_div_scale_f32 v41, s[20:21], v40, v40, 1.0
	v_rcp_f32_e32 v44, v41
	s_nop 0
	v_fma_f32 v45, -v41, v44, 1.0
	v_fmac_f32_e32 v44, v45, v44
	v_div_scale_f32 v45, vcc, 1.0, v40, 1.0
	v_mul_f32_e32 v46, v45, v44
	v_fma_f32 v47, -v41, v46, v45
	v_fmac_f32_e32 v46, v47, v44
	v_fma_f32 v41, -v41, v46, v45
	v_div_fmas_f32 v41, v41, v44, v46
	v_div_fixup_f32 v40, v41, v40, 1.0
	v_cvt_pk_bf16_f32 v204, v40, v2
	v_mul_f32_e32 v2, 0xbfb8aa3b, v42
	v_exp_f32_e32 v40, v2
	v_mul_f32_e32 v2, 0xbfb8aa3b, v43
	v_exp_f32_e32 v41, v2
	s_nop 0
	v_pk_add_f32 v[40:41], v[40:41], 1.0 op_sel_hi:[1,0]
	s_nop 0
	v_div_scale_f32 v2, s[20:21], v41, v41, 1.0
	v_rcp_f32_e32 v42, v2
	s_nop 0
	v_fma_f32 v43, -v2, v42, 1.0
	v_fmac_f32_e32 v42, v43, v42
	v_div_scale_f32 v43, vcc, 1.0, v41, 1.0
	v_mul_f32_e32 v44, v43, v42
	v_fma_f32 v45, -v2, v44, v43
	v_fmac_f32_e32 v44, v45, v42
	v_fma_f32 v2, -v2, v44, v43
	v_div_fmas_f32 v2, v2, v42, v44
	v_div_fixup_f32 v2, v2, v41, 1.0
	v_div_scale_f32 v41, s[20:21], v40, v40, 1.0
	v_rcp_f32_e32 v42, v41
	s_nop 0
	v_fma_f32 v43, -v41, v42, 1.0
	v_fmac_f32_e32 v42, v43, v42
	v_div_scale_f32 v43, vcc, 1.0, v40, 1.0
	v_mul_f32_e32 v44, v43, v42
	v_fma_f32 v45, -v41, v44, v43
	v_fmac_f32_e32 v44, v45, v42
	v_fma_f32 v41, -v41, v44, v43
	v_div_fmas_f32 v41, v41, v42, v44
	v_div_fixup_f32 v40, v41, v40, 1.0
	v_cvt_pk_bf16_f32 v205, v40, v2
	v_mul_f32_e32 v2, 0xbfb8aa3b, v36
	v_exp_f32_e32 v36, v2
	v_mul_f32_e32 v2, 0xbfb8aa3b, v37
	v_exp_f32_e32 v37, v2
	s_nop 0
	v_pk_add_f32 v[36:37], v[36:37], 1.0 op_sel_hi:[1,0]
	s_nop 0
	v_div_scale_f32 v2, s[20:21], v37, v37, 1.0
	v_rcp_f32_e32 v40, v2
	s_nop 0
	v_fma_f32 v41, -v2, v40, 1.0
	v_fmac_f32_e32 v40, v41, v40
	v_div_scale_f32 v41, vcc, 1.0, v37, 1.0
	v_mul_f32_e32 v42, v41, v40
	v_fma_f32 v43, -v2, v42, v41
	v_fmac_f32_e32 v42, v43, v40
	v_fma_f32 v2, -v2, v42, v41
	v_div_fmas_f32 v2, v2, v40, v42
	v_div_fixup_f32 v2, v2, v37, 1.0
	v_div_scale_f32 v37, s[20:21], v36, v36, 1.0
	v_rcp_f32_e32 v40, v37
	s_nop 0
	v_fma_f32 v41, -v37, v40, 1.0
	v_fmac_f32_e32 v40, v41, v40
	v_div_scale_f32 v41, vcc, 1.0, v36, 1.0
	v_mul_f32_e32 v42, v41, v40
	v_fma_f32 v43, -v37, v42, v41
	v_fmac_f32_e32 v42, v43, v40
	v_fma_f32 v37, -v37, v42, v41
	v_div_fmas_f32 v37, v37, v40, v42
	v_div_fixup_f32 v36, v37, v36, 1.0
	v_cvt_pk_bf16_f32 v206, v36, v2
	v_mul_f32_e32 v2, 0xbfb8aa3b, v38
	v_exp_f32_e32 v36, v2
	v_mul_f32_e32 v2, 0xbfb8aa3b, v39
	v_exp_f32_e32 v37, v2
	s_nop 0
	v_pk_add_f32 v[36:37], v[36:37], 1.0 op_sel_hi:[1,0]
	s_nop 0
	v_div_scale_f32 v2, s[20:21], v37, v37, 1.0
	v_rcp_f32_e32 v38, v2
	s_nop 0
	v_fma_f32 v39, -v2, v38, 1.0
	v_fmac_f32_e32 v38, v39, v38
	v_div_scale_f32 v39, vcc, 1.0, v37, 1.0
	v_mul_f32_e32 v40, v39, v38
	v_fma_f32 v41, -v2, v40, v39
	v_fmac_f32_e32 v40, v41, v38
	v_fma_f32 v2, -v2, v40, v39
	v_div_fmas_f32 v2, v2, v38, v40
	v_div_fixup_f32 v2, v2, v37, 1.0
	v_div_scale_f32 v37, s[20:21], v36, v36, 1.0
	v_rcp_f32_e32 v38, v37
	s_nop 0
	v_fma_f32 v39, -v37, v38, 1.0
	v_fmac_f32_e32 v38, v39, v38
	v_div_scale_f32 v39, vcc, 1.0, v36, 1.0
	v_mul_f32_e32 v40, v39, v38
	v_fma_f32 v41, -v37, v40, v39
	v_fmac_f32_e32 v40, v41, v38
	v_fma_f32 v37, -v37, v40, v39
	v_div_fmas_f32 v37, v37, v38, v40
	v_div_fixup_f32 v36, v37, v36, 1.0
	v_cvt_pk_bf16_f32 v207, v36, v2
	v_mul_f32_e32 v2, 0xbfb8aa3b, v32
	v_exp_f32_e32 v32, v2
	v_mul_f32_e32 v2, 0xbfb8aa3b, v33
	v_exp_f32_e32 v33, v2
	s_nop 0
	v_pk_add_f32 v[32:33], v[32:33], 1.0 op_sel_hi:[1,0]
	s_nop 0
	v_div_scale_f32 v2, s[20:21], v33, v33, 1.0
	v_rcp_f32_e32 v36, v2
	s_nop 0
	v_fma_f32 v37, -v2, v36, 1.0
	v_fmac_f32_e32 v36, v37, v36
	v_div_scale_f32 v37, vcc, 1.0, v33, 1.0
	v_mul_f32_e32 v38, v37, v36
	v_fma_f32 v39, -v2, v38, v37
	v_fmac_f32_e32 v38, v39, v36
	v_fma_f32 v2, -v2, v38, v37
	v_div_fmas_f32 v2, v2, v36, v38
	v_div_fixup_f32 v2, v2, v33, 1.0
	v_div_scale_f32 v33, s[20:21], v32, v32, 1.0
	v_rcp_f32_e32 v36, v33
	s_nop 0
	v_fma_f32 v37, -v33, v36, 1.0
	v_fmac_f32_e32 v36, v37, v36
	v_div_scale_f32 v37, vcc, 1.0, v32, 1.0
	v_mul_f32_e32 v38, v37, v36
	v_fma_f32 v39, -v33, v38, v37
	v_fmac_f32_e32 v38, v39, v36
	v_fma_f32 v33, -v33, v38, v37
	v_div_fmas_f32 v33, v33, v36, v38
	v_div_fixup_f32 v32, v33, v32, 1.0
	v_cvt_pk_bf16_f32 v208, v32, v2
	v_mul_f32_e32 v2, 0xbfb8aa3b, v34
	v_exp_f32_e32 v32, v2
	v_mul_f32_e32 v2, 0xbfb8aa3b, v35
	v_exp_f32_e32 v33, v2
	s_nop 0
	v_pk_add_f32 v[32:33], v[32:33], 1.0 op_sel_hi:[1,0]
	s_nop 0
	v_div_scale_f32 v2, s[20:21], v33, v33, 1.0
; DEVI unsigned pack2(float a, float b) { f32x2_t v = {a, b}; bf16x2_t r = __builtin_convertvector(v, bf16x2_t); return *reinterpret_cast<unsigned*>(&r); }
; DEVI float sigm(float x) { return 1.f / (1.f + __expf(-x)); }
; template <int NTW>
; DEVI void merge_tile(const P& p, long row0, int n0, char* smem) {
;     ...
; #pragma unroll
;       for (int m = 0; m < 4; ++m)
; #pragma unroll
;         for (int n = 0; n < NTW; ++n) {
;           pg[m][n][0] = pack2(sigm(accT[m][n][0]), sigm(accT[m][n][1]));
;           pg[m][n][1] = pack2(sigm(accT[m][n][2]), sigm(accT[m][n][3]));
;         }
	v_rcp_f32_e32 v34, v2
	s_nop 0
	v_fma_f32 v35, -v2, v34, 1.0
	v_fmac_f32_e32 v34, v35, v34
	v_div_scale_f32 v35, vcc, 1.0, v33, 1.0
	v_mul_f32_e32 v36, v35, v34
	v_fma_f32 v37, -v2, v36, v35
	v_fmac_f32_e32 v36, v37, v34
	v_fma_f32 v2, -v2, v36, v35
	v_div_fmas_f32 v2, v2, v34, v36
	v_div_fixup_f32 v2, v2, v33, 1.0
	v_div_scale_f32 v33, s[20:21], v32, v32, 1.0
	v_rcp_f32_e32 v34, v33
	s_nop 0
	v_fma_f32 v35, -v33, v34, 1.0
	v_fmac_f32_e32 v34, v35, v34
	v_div_scale_f32 v35, vcc, 1.0, v32, 1.0
	v_mul_f32_e32 v36, v35, v34
	v_fma_f32 v37, -v33, v36, v35
	v_fmac_f32_e32 v36, v37, v34
	v_fma_f32 v33, -v33, v36, v35
	v_div_fmas_f32 v33, v33, v34, v36
	v_div_fixup_f32 v32, v33, v32, 1.0
	v_cvt_pk_bf16_f32 v209, v32, v2
	v_mul_f32_e32 v2, 0xbfb8aa3b, v28
	v_exp_f32_e32 v28, v2
	v_mul_f32_e32 v2, 0xbfb8aa3b, v29
	v_exp_f32_e32 v29, v2
	s_nop 0
	v_pk_add_f32 v[28:29], v[28:29], 1.0 op_sel_hi:[1,0]
	s_nop 0
	v_div_scale_f32 v2, s[20:21], v29, v29, 1.0
	v_rcp_f32_e32 v32, v2
	s_nop 0
	v_fma_f32 v33, -v2, v32, 1.0
	v_fmac_f32_e32 v32, v33, v32
	v_div_scale_f32 v33, vcc, 1.0, v29, 1.0
	v_mul_f32_e32 v34, v33, v32
	v_fma_f32 v35, -v2, v34, v33
	v_fmac_f32_e32 v34, v35, v32
	v_fma_f32 v2, -v2, v34, v33
	v_div_fmas_f32 v2, v2, v32, v34
	v_div_fixup_f32 v2, v2, v29, 1.0
	v_div_scale_f32 v29, s[20:21], v28, v28, 1.0
	v_rcp_f32_e32 v32, v29
	s_nop 0
	v_fma_f32 v33, -v29, v32, 1.0
	v_fmac_f32_e32 v32, v33, v32
	v_div_scale_f32 v33, vcc, 1.0, v28, 1.0
	v_mul_f32_e32 v34, v33, v32
	v_fma_f32 v35, -v29, v34, v33
	v_fmac_f32_e32 v34, v35, v32
	v_fma_f32 v29, -v29, v34, v33
	v_div_fmas_f32 v29, v29, v32, v34
	v_div_fixup_f32 v28, v29, v28, 1.0
	v_cvt_pk_bf16_f32 v210, v28, v2
	v_mul_f32_e32 v2, 0xbfb8aa3b, v30
	v_exp_f32_e32 v28, v2
	v_mul_f32_e32 v2, 0xbfb8aa3b, v31
	v_exp_f32_e32 v29, v2
	s_nop 0
	v_pk_add_f32 v[28:29], v[28:29], 1.0 op_sel_hi:[1,0]
	s_nop 0
	v_div_scale_f32 v2, s[20:21], v29, v29, 1.0
	v_rcp_f32_e32 v30, v2
	s_nop 0
	v_fma_f32 v31, -v2, v30, 1.0
	v_fmac_f32_e32 v30, v31, v30
	v_div_scale_f32 v31, vcc, 1.0, v29, 1.0
	v_mul_f32_e32 v32, v31, v30
	v_fma_f32 v33, -v2, v32, v31
	v_fmac_f32_e32 v32, v33, v30
	v_fma_f32 v2, -v2, v32, v31
	v_div_fmas_f32 v2, v2, v30, v32
	v_div_fixup_f32 v2, v2, v29, 1.0
	v_div_scale_f32 v29, s[20:21], v28, v28, 1.0
	v_rcp_f32_e32 v30, v29
	s_nop 0
	v_fma_f32 v31, -v29, v30, 1.0
	v_fmac_f32_e32 v30, v31, v30
	v_div_scale_f32 v31, vcc, 1.0, v28, 1.0
	v_mul_f32_e32 v32, v31, v30
	v_fma_f32 v33, -v29, v32, v31
	v_fmac_f32_e32 v32, v33, v30
	v_fma_f32 v29, -v29, v32, v31
	v_div_fmas_f32 v29, v29, v30, v32
	v_div_fixup_f32 v28, v29, v28, 1.0
	v_cvt_pk_bf16_f32 v211, v28, v2
	v_mul_f32_e32 v2, 0xbfb8aa3b, v24
	v_exp_f32_e32 v24, v2
	v_mul_f32_e32 v2, 0xbfb8aa3b, v25
	v_exp_f32_e32 v25, v2
	s_nop 0
	v_pk_add_f32 v[24:25], v[24:25], 1.0 op_sel_hi:[1,0]
	s_nop 0
	v_div_scale_f32 v2, s[20:21], v25, v25, 1.0
	v_rcp_f32_e32 v28, v2
	s_nop 0
	v_fma_f32 v29, -v2, v28, 1.0
	v_fmac_f32_e32 v28, v29, v28
	v_div_scale_f32 v29, vcc, 1.0, v25, 1.0
	v_mul_f32_e32 v30, v29, v28
	v_fma_f32 v31, -v2, v30, v29
	v_fmac_f32_e32 v30, v31, v28
	v_fma_f32 v2, -v2, v30, v29
	v_div_fmas_f32 v2, v2, v28, v30
	v_div_fixup_f32 v2, v2, v25, 1.0
	v_div_scale_f32 v25, s[20:21], v24, v24, 1.0
	v_rcp_f32_e32 v28, v25
	s_nop 0
	v_fma_f32 v29, -v25, v28, 1.0
	v_fmac_f32_e32 v28, v29, v28
	v_div_scale_f32 v29, vcc, 1.0, v24, 1.0
	v_mul_f32_e32 v30, v29, v28
	v_fma_f32 v31, -v25, v30, v29
	v_fmac_f32_e32 v30, v31, v28
	v_fma_f32 v25, -v25, v30, v29
	v_div_fmas_f32 v25, v25, v28, v30
	v_div_fixup_f32 v24, v25, v24, 1.0
	v_cvt_pk_bf16_f32 v212, v24, v2
	v_mul_f32_e32 v2, 0xbfb8aa3b, v26
	v_exp_f32_e32 v24, v2
	v_mul_f32_e32 v2, 0xbfb8aa3b, v27
	v_exp_f32_e32 v25, v2
	s_nop 0
	v_pk_add_f32 v[24:25], v[24:25], 1.0 op_sel_hi:[1,0]
	s_nop 0
	v_div_scale_f32 v2, s[20:21], v25, v25, 1.0
	v_rcp_f32_e32 v26, v2
	s_nop 0
	v_fma_f32 v27, -v2, v26, 1.0
	v_fmac_f32_e32 v26, v27, v26
	v_div_scale_f32 v27, vcc, 1.0, v25, 1.0
	v_mul_f32_e32 v28, v27, v26
	v_fma_f32 v29, -v2, v28, v27
	v_fmac_f32_e32 v28, v29, v26
	v_fma_f32 v2, -v2, v28, v27
	v_div_fmas_f32 v2, v2, v26, v28
	v_div_fixup_f32 v2, v2, v25, 1.0
	v_div_scale_f32 v25, s[20:21], v24, v24, 1.0
	v_rcp_f32_e32 v26, v25
	s_nop 0
	v_fma_f32 v27, -v25, v26, 1.0
	v_fmac_f32_e32 v26, v27, v26
	v_div_scale_f32 v27, vcc, 1.0, v24, 1.0
	v_mul_f32_e32 v28, v27, v26
	v_fma_f32 v29, -v25, v28, v27
	v_fmac_f32_e32 v28, v29, v26
	v_fma_f32 v25, -v25, v28, v27
	v_div_fmas_f32 v25, v25, v26, v28
	v_div_fixup_f32 v24, v25, v24, 1.0
	v_cvt_pk_bf16_f32 v213, v24, v2
	v_mul_f32_e32 v2, 0xbfb8aa3b, v20
	v_exp_f32_e32 v20, v2
	v_mul_f32_e32 v2, 0xbfb8aa3b, v21
	v_exp_f32_e32 v21, v2
	s_nop 0
	v_pk_add_f32 v[20:21], v[20:21], 1.0 op_sel_hi:[1,0]
	s_nop 0
	v_div_scale_f32 v2, s[20:21], v21, v21, 1.0
	v_rcp_f32_e32 v24, v2
	s_nop 0
	v_fma_f32 v25, -v2, v24, 1.0
	v_fmac_f32_e32 v24, v25, v24
	v_div_scale_f32 v25, vcc, 1.0, v21, 1.0
	v_mul_f32_e32 v26, v25, v24
	v_fma_f32 v27, -v2, v26, v25
	v_fmac_f32_e32 v26, v27, v24
	v_fma_f32 v2, -v2, v26, v25
	v_div_fmas_f32 v2, v2, v24, v26
	v_div_fixup_f32 v2, v2, v21, 1.0
	v_div_scale_f32 v21, s[20:21], v20, v20, 1.0
	v_rcp_f32_e32 v24, v21
	s_nop 0
	v_fma_f32 v25, -v21, v24, 1.0
	v_fmac_f32_e32 v24, v25, v24
	v_div_scale_f32 v25, vcc, 1.0, v20, 1.0
	v_mul_f32_e32 v26, v25, v24
	v_fma_f32 v27, -v21, v26, v25
	v_fmac_f32_e32 v26, v27, v24
	v_fma_f32 v21, -v21, v26, v25
	v_div_fmas_f32 v21, v21, v24, v26
	v_div_fixup_f32 v20, v21, v20, 1.0
	v_cvt_pk_bf16_f32 v214, v20, v2
	v_mul_f32_e32 v2, 0xbfb8aa3b, v22
	v_exp_f32_e32 v20, v2
	v_mul_f32_e32 v2, 0xbfb8aa3b, v23
	v_exp_f32_e32 v21, v2
	s_nop 0
; DEVI unsigned pack2(float a, float b) { f32x2_t v = {a, b}; bf16x2_t r = __builtin_convertvector(v, bf16x2_t); return *reinterpret_cast<unsigned*>(&r); }
; DEVI float sigm(float x) { return 1.f / (1.f + __expf(-x)); }
; template <int NTW>
; DEVI void merge_tile(const P& p, long row0, int n0, char* smem) {
;     ...
; #pragma unroll
;       for (int m = 0; m < 4; ++m)
; #pragma unroll
;         for (int n = 0; n < NTW; ++n) {
;           pg[m][n][0] = pack2(sigm(accT[m][n][0]), sigm(accT[m][n][1]));
;           pg[m][n][1] = pack2(sigm(accT[m][n][2]), sigm(accT[m][n][3]));
;         }
	v_pk_add_f32 v[20:21], v[20:21], 1.0 op_sel_hi:[1,0]
	s_nop 0
	v_div_scale_f32 v2, s[20:21], v21, v21, 1.0
	v_rcp_f32_e32 v22, v2
	s_nop 0
	v_fma_f32 v23, -v2, v22, 1.0
	v_fmac_f32_e32 v22, v23, v22
	v_div_scale_f32 v23, vcc, 1.0, v21, 1.0
	v_mul_f32_e32 v24, v23, v22
	v_fma_f32 v25, -v2, v24, v23
	v_fmac_f32_e32 v24, v25, v22
	v_fma_f32 v2, -v2, v24, v23
	v_div_fmas_f32 v2, v2, v22, v24
	v_div_fixup_f32 v2, v2, v21, 1.0
	v_div_scale_f32 v21, s[20:21], v20, v20, 1.0
	v_rcp_f32_e32 v22, v21
	s_nop 0
	v_fma_f32 v23, -v21, v22, 1.0
	v_fmac_f32_e32 v22, v23, v22
	v_div_scale_f32 v23, vcc, 1.0, v20, 1.0
	v_mul_f32_e32 v24, v23, v22
	v_fma_f32 v25, -v21, v24, v23
	v_fmac_f32_e32 v24, v25, v22
	v_fma_f32 v21, -v21, v24, v23
	v_div_fmas_f32 v21, v21, v22, v24
	v_div_fixup_f32 v20, v21, v20, 1.0
	v_cvt_pk_bf16_f32 v215, v20, v2
	v_mul_f32_e32 v2, 0xbfb8aa3b, v16
	v_exp_f32_e32 v16, v2
	v_mul_f32_e32 v2, 0xbfb8aa3b, v17
	v_exp_f32_e32 v17, v2
	s_nop 0
	v_pk_add_f32 v[16:17], v[16:17], 1.0 op_sel_hi:[1,0]
	s_nop 0
	v_div_scale_f32 v2, s[20:21], v17, v17, 1.0
	v_rcp_f32_e32 v20, v2
	s_nop 0
	v_fma_f32 v21, -v2, v20, 1.0
	v_fmac_f32_e32 v20, v21, v20
	v_div_scale_f32 v21, vcc, 1.0, v17, 1.0
	v_mul_f32_e32 v22, v21, v20
	v_fma_f32 v23, -v2, v22, v21
	v_fmac_f32_e32 v22, v23, v20
	v_fma_f32 v2, -v2, v22, v21
	v_div_fmas_f32 v2, v2, v20, v22
	v_div_fixup_f32 v2, v2, v17, 1.0
	v_div_scale_f32 v17, s[20:21], v16, v16, 1.0
	v_rcp_f32_e32 v20, v17
	s_nop 0
	v_fma_f32 v21, -v17, v20, 1.0
	v_fmac_f32_e32 v20, v21, v20
	v_div_scale_f32 v21, vcc, 1.0, v16, 1.0
	v_mul_f32_e32 v22, v21, v20
	v_fma_f32 v23, -v17, v22, v21
	v_fmac_f32_e32 v22, v23, v20
	v_fma_f32 v17, -v17, v22, v21
	v_div_fmas_f32 v17, v17, v20, v22
	v_div_fixup_f32 v16, v17, v16, 1.0
	v_cvt_pk_bf16_f32 v216, v16, v2
	v_mul_f32_e32 v2, 0xbfb8aa3b, v18
	v_exp_f32_e32 v16, v2
	v_mul_f32_e32 v2, 0xbfb8aa3b, v19
	v_exp_f32_e32 v17, v2
	s_nop 0
	v_pk_add_f32 v[16:17], v[16:17], 1.0 op_sel_hi:[1,0]
	s_nop 0
	v_div_scale_f32 v2, s[20:21], v17, v17, 1.0
	v_rcp_f32_e32 v18, v2
	s_nop 0
	v_fma_f32 v19, -v2, v18, 1.0
	v_fmac_f32_e32 v18, v19, v18
	v_div_scale_f32 v19, vcc, 1.0, v17, 1.0
	v_mul_f32_e32 v20, v19, v18
	v_fma_f32 v21, -v2, v20, v19
	v_fmac_f32_e32 v20, v21, v18
	v_fma_f32 v2, -v2, v20, v19
	v_div_fmas_f32 v2, v2, v18, v20
	v_div_fixup_f32 v2, v2, v17, 1.0
	v_div_scale_f32 v17, s[20:21], v16, v16, 1.0
	v_rcp_f32_e32 v18, v17
	s_nop 0
	v_fma_f32 v19, -v17, v18, 1.0
	v_fmac_f32_e32 v18, v19, v18
	v_div_scale_f32 v19, vcc, 1.0, v16, 1.0
	v_mul_f32_e32 v20, v19, v18
	v_fma_f32 v21, -v17, v20, v19
	v_fmac_f32_e32 v20, v21, v18
	v_fma_f32 v17, -v17, v20, v19
	v_div_fmas_f32 v17, v17, v18, v20
	v_div_fixup_f32 v16, v17, v16, 1.0
	v_cvt_pk_bf16_f32 v217, v16, v2
	v_mul_f32_e32 v2, 0xbfb8aa3b, v12
	v_exp_f32_e32 v12, v2
	v_mul_f32_e32 v2, 0xbfb8aa3b, v13
	v_exp_f32_e32 v13, v2
	s_nop 0
	v_pk_add_f32 v[12:13], v[12:13], 1.0 op_sel_hi:[1,0]
	s_nop 0
	v_div_scale_f32 v2, s[20:21], v13, v13, 1.0
	v_rcp_f32_e32 v16, v2
	s_nop 0
	v_fma_f32 v17, -v2, v16, 1.0
	v_fmac_f32_e32 v16, v17, v16
	v_div_scale_f32 v17, vcc, 1.0, v13, 1.0
	v_mul_f32_e32 v18, v17, v16
	v_fma_f32 v19, -v2, v18, v17
	v_fmac_f32_e32 v18, v19, v16
	v_fma_f32 v2, -v2, v18, v17
	v_div_fmas_f32 v2, v2, v16, v18
	v_div_fixup_f32 v2, v2, v13, 1.0
	v_div_scale_f32 v13, s[20:21], v12, v12, 1.0
	v_rcp_f32_e32 v16, v13
	s_nop 0
	v_fma_f32 v17, -v13, v16, 1.0
	v_fmac_f32_e32 v16, v17, v16
	v_div_scale_f32 v17, vcc, 1.0, v12, 1.0
	v_mul_f32_e32 v18, v17, v16
	v_fma_f32 v19, -v13, v18, v17
	v_fmac_f32_e32 v18, v19, v16
	v_fma_f32 v13, -v13, v18, v17
	v_div_fmas_f32 v13, v13, v16, v18
	v_div_fixup_f32 v12, v13, v12, 1.0
	v_cvt_pk_bf16_f32 v218, v12, v2
	v_mul_f32_e32 v2, 0xbfb8aa3b, v14
	v_exp_f32_e32 v12, v2
	v_mul_f32_e32 v2, 0xbfb8aa3b, v15
	v_exp_f32_e32 v13, v2
	s_nop 0
	v_pk_add_f32 v[12:13], v[12:13], 1.0 op_sel_hi:[1,0]
	s_nop 0
	v_div_scale_f32 v2, s[20:21], v13, v13, 1.0
	v_rcp_f32_e32 v14, v2
	s_nop 0
	v_fma_f32 v15, -v2, v14, 1.0
	v_fmac_f32_e32 v14, v15, v14
	v_div_scale_f32 v15, vcc, 1.0, v13, 1.0
	v_mul_f32_e32 v16, v15, v14
	v_fma_f32 v17, -v2, v16, v15
	v_fmac_f32_e32 v16, v17, v14
	v_fma_f32 v2, -v2, v16, v15
	v_div_fmas_f32 v2, v2, v14, v16
	v_div_fixup_f32 v2, v2, v13, 1.0
	v_div_scale_f32 v13, s[20:21], v12, v12, 1.0
	v_rcp_f32_e32 v14, v13
	s_nop 0
	v_fma_f32 v15, -v13, v14, 1.0
	v_fmac_f32_e32 v14, v15, v14
	v_div_scale_f32 v15, vcc, 1.0, v12, 1.0
	v_mul_f32_e32 v16, v15, v14
	v_fma_f32 v17, -v13, v16, v15
	v_fmac_f32_e32 v16, v17, v14
	v_fma_f32 v13, -v13, v16, v15
	v_div_fmas_f32 v13, v13, v14, v16
	v_div_fixup_f32 v12, v13, v12, 1.0
	v_cvt_pk_bf16_f32 v219, v12, v2
	v_mul_f32_e32 v2, 0xbfb8aa3b, v8
	v_exp_f32_e32 v8, v2
	v_mul_f32_e32 v2, 0xbfb8aa3b, v9
	v_exp_f32_e32 v9, v2
	s_nop 0
	v_pk_add_f32 v[8:9], v[8:9], 1.0 op_sel_hi:[1,0]
	s_nop 0
	v_div_scale_f32 v2, s[20:21], v9, v9, 1.0
	v_rcp_f32_e32 v12, v2
	s_nop 0
	v_fma_f32 v13, -v2, v12, 1.0
	v_fmac_f32_e32 v12, v13, v12
	v_div_scale_f32 v13, vcc, 1.0, v9, 1.0
	v_mul_f32_e32 v14, v13, v12
	v_fma_f32 v15, -v2, v14, v13
	v_fmac_f32_e32 v14, v15, v12
	v_fma_f32 v2, -v2, v14, v13
	v_div_fmas_f32 v2, v2, v12, v14
	v_div_fixup_f32 v2, v2, v9, 1.0
	v_div_scale_f32 v9, s[20:21], v8, v8, 1.0
	v_rcp_f32_e32 v12, v9
	s_nop 0
	v_fma_f32 v13, -v9, v12, 1.0
	v_fmac_f32_e32 v12, v13, v12
	v_div_scale_f32 v13, vcc, 1.0, v8, 1.0
	v_mul_f32_e32 v14, v13, v12
	v_fma_f32 v15, -v9, v14, v13
	v_fmac_f32_e32 v14, v15, v12
	v_fma_f32 v9, -v9, v14, v13
	v_div_fmas_f32 v9, v9, v12, v14
	v_div_fixup_f32 v8, v9, v8, 1.0
	v_cvt_pk_bf16_f32 v220, v8, v2
	v_mul_f32_e32 v2, 0xbfb8aa3b, v10
	v_exp_f32_e32 v8, v2
; DEVI unsigned pack2(float a, float b) { f32x2_t v = {a, b}; bf16x2_t r = __builtin_convertvector(v, bf16x2_t); return *reinterpret_cast<unsigned*>(&r); }
; DEVI float sigm(float x) { return 1.f / (1.f + __expf(-x)); }
; DEVI int get_tid() { int t = threadIdx.x; asm volatile("" : "+v"(t)); return t; }
; template <int NTW, bool SPLIT = false, bool HALFA = false>
; DEVI void gemm_core2(f32x4 (&acc)[4][NTW], const bf* __restrict__ A, int lda, const bf* __restrict__ Bt, int ldb, int K, char* smem) {
;     ...
;   const int tid = get_tid(), lane = tid & 63, w = tid >> 6, wr = w >> 1, wc = w & 1, l15 = lane & 15, quad = lane >> 4;
;   const int lr = tid >> 3, pch = tid & 7;
;   const int lch = pch ^ (lr & 7);
;   const int nk = K >> 6;
;   const bf* Ap = A + (long)lr * lda + lch * 8;
;   const bf* Bp = Bt + (long)lr * ldb + lch * 8;
;   const long sa = (long)32 * lda, sb = (long)32 * ldb;
;   char* dbase = smem + tid * 16;
;   const int sw0 = ((quad ^ (l15 & 7)) << 4), sw1 = (((4 + quad) ^ (l15 & 7)) << 4);
;   const char* abase = smem + (wr * 64 + l15) * 128;
;   const char* bbase = smem + ASZ + (wc * 16 * NTW + l15) * 128;
; #pragma unroll
;   for (int i = 0; i < 4; ++i) glds16(Ap + i * sa, dbase + i * 4096);
; #pragma unroll
;   for (int i = 0; i < NBL; ++i) glds16(Bp + i * sb, dbase + ASZ + i * 4096);
;   __syncthreads();
; template <int NTW>
; DEVI void merge_tile(const P& p, long row0, int n0, char* smem) {
;     ...
;           pg[m][n][0] = pack2(sigm(accT[m][n][0]), sigm(accT[m][n][1]));
;           pg[m][n][1] = pack2(sigm(accT[m][n][2]), sigm(accT[m][n][3]));
	v_mul_f32_e32 v2, 0xbfb8aa3b, v11
	v_exp_f32_e32 v9, v2
	s_nop 0
	v_pk_add_f32 v[8:9], v[8:9], 1.0 op_sel_hi:[1,0]
	s_nop 0
	v_div_scale_f32 v2, s[20:21], v9, v9, 1.0
	v_rcp_f32_e32 v10, v2
	s_nop 0
	v_fma_f32 v11, -v2, v10, 1.0
	v_fmac_f32_e32 v10, v11, v10
	v_div_scale_f32 v11, vcc, 1.0, v9, 1.0
	v_mul_f32_e32 v12, v11, v10
	v_fma_f32 v13, -v2, v12, v11
	v_fmac_f32_e32 v12, v13, v10
	v_fma_f32 v2, -v2, v12, v11
	v_div_fmas_f32 v2, v2, v10, v12
	v_div_fixup_f32 v2, v2, v9, 1.0
	v_div_scale_f32 v9, s[20:21], v8, v8, 1.0
	v_rcp_f32_e32 v10, v9
	s_nop 0
	v_fma_f32 v11, -v9, v10, 1.0
	v_fmac_f32_e32 v10, v11, v10
	v_div_scale_f32 v11, vcc, 1.0, v8, 1.0
	v_mul_f32_e32 v12, v11, v10
	v_fma_f32 v13, -v9, v12, v11
	v_fmac_f32_e32 v12, v13, v10
	v_fma_f32 v9, -v9, v12, v11
	v_div_fmas_f32 v9, v9, v10, v12
	v_div_fixup_f32 v8, v9, v8, 1.0
	v_cvt_pk_bf16_f32 v221, v8, v2
	v_mul_f32_e32 v2, 0xbfb8aa3b, v4
	v_exp_f32_e32 v4, v2
	v_mul_f32_e32 v2, 0xbfb8aa3b, v5
	v_exp_f32_e32 v5, v2
	s_nop 0
	v_pk_add_f32 v[4:5], v[4:5], 1.0 op_sel_hi:[1,0]
	s_nop 0
	v_div_scale_f32 v2, s[20:21], v5, v5, 1.0
	v_rcp_f32_e32 v8, v2
	s_nop 0
	v_fma_f32 v9, -v2, v8, 1.0
	v_fmac_f32_e32 v8, v9, v8
	v_div_scale_f32 v9, vcc, 1.0, v5, 1.0
	v_mul_f32_e32 v10, v9, v8
	v_fma_f32 v11, -v2, v10, v9
	v_fmac_f32_e32 v10, v11, v8
	v_fma_f32 v2, -v2, v10, v9
	v_div_fmas_f32 v2, v2, v8, v10
	v_div_fixup_f32 v2, v2, v5, 1.0
	v_div_scale_f32 v5, s[20:21], v4, v4, 1.0
	v_rcp_f32_e32 v8, v5
	s_nop 0
	v_fma_f32 v9, -v5, v8, 1.0
	v_fmac_f32_e32 v8, v9, v8
	v_div_scale_f32 v9, vcc, 1.0, v4, 1.0
	v_mul_f32_e32 v10, v9, v8
	v_fma_f32 v11, -v5, v10, v9
	v_fmac_f32_e32 v10, v11, v8
	v_fma_f32 v5, -v5, v10, v9
	v_div_fmas_f32 v5, v5, v8, v10
	v_div_fixup_f32 v4, v5, v4, 1.0
	v_cvt_pk_bf16_f32 v222, v4, v2
	v_mul_f32_e32 v2, 0xbfb8aa3b, v6
	v_exp_f32_e32 v4, v2
	v_mul_f32_e32 v2, 0xbfb8aa3b, v7
	v_exp_f32_e32 v5, v2
	s_nop 0
	v_pk_add_f32 v[4:5], v[4:5], 1.0 op_sel_hi:[1,0]
	s_nop 0
	v_div_scale_f32 v2, s[20:21], v5, v5, 1.0
	v_rcp_f32_e32 v6, v2
	s_nop 0
	v_fma_f32 v7, -v2, v6, 1.0
	v_fmac_f32_e32 v6, v7, v6
	v_div_scale_f32 v7, vcc, 1.0, v5, 1.0
	v_mul_f32_e32 v8, v7, v6
	v_fma_f32 v9, -v2, v8, v7
	v_fmac_f32_e32 v8, v9, v6
	v_fma_f32 v2, -v2, v8, v7
	v_div_fmas_f32 v2, v2, v6, v8
	v_div_fixup_f32 v2, v2, v5, 1.0
	v_div_scale_f32 v5, s[20:21], v4, v4, 1.0
	v_rcp_f32_e32 v6, v5
	s_add_u32 s20, s10, s13
	s_addc_u32 s21, s11, 0
	s_add_u32 s12, s12, s38
	v_fma_f32 v7, -v5, v6, 1.0
	v_fmac_f32_e32 v6, v7, v6
	v_div_scale_f32 v7, vcc, 1.0, v4, 1.0
	v_mul_f32_e32 v8, v7, v6
	v_fma_f32 v9, -v5, v8, v7
	v_fmac_f32_e32 v8, v9, v6
	v_fma_f32 v5, -v5, v8, v7
	v_div_fmas_f32 v5, v5, v6, v8
	v_div_fixup_f32 v4, v5, v4, 1.0
	v_mov_b32_e32 v8, v178
	v_cvt_pk_bf16_f32 v223, v4, v2
	s_addc_u32 s13, 0, s39
	v_ashrrev_i32_e32 v4, 3, v8
	v_xor_b32_e32 v2, v4, v8
	v_ashrrev_i32_e32 v5, 31, v4
	v_lshlrev_b64 v[6:7], 11, v[4:5]
	v_lshlrev_b32_e32 v2, 4, v2
	s_lshl_b64 s[12:13], s[12:13], 9
	v_lshl_add_u64 v[6:7], s[20:21], 0, v[6:7]
	v_and_b32_e32 v2, 0x70, v2
	s_add_u32 s12, s54, s12
	v_and_b32_e32 v9, 15, v8
	v_lshl_add_u64 v[158:159], v[6:7], 0, v[2:3]
	v_lshlrev_b32_e32 v227, 4, v8
	v_lshrrev_b32_e32 v6, 1, v8
	s_addc_u32 s13, s55, s13
	v_lshlrev_b64 v[4:5], 9, v[4:5]
	v_and_or_b32 v6, v6, s19, v9
	v_readfirstlane_b32 s43, v227
	v_add_u32_e32 v9, 0x1000, v227
	v_lshl_add_u64 v[4:5], s[12:13], 0, v[4:5]
	v_lshlrev_b32_e32 v225, 7, v6
	v_lshlrev_b32_e32 v6, 7, v8
	s_mov_b32 m0, s43
	v_readfirstlane_b32 s12, v9
	v_add_u32_e32 v9, 0x2000, v227
	v_and_b32_e32 v60, 0x2780, v6
	global_load_lds_dwordx4 v[158:159], off
	v_lshl_add_u64 v[6:7], v[158:159], 0, s[14:15]
	s_mov_b32 m0, s12
	v_readfirstlane_b32 s13, v9
	v_add_u32_e32 v9, 0x3000, v227
	global_load_lds_dwordx4 v[6:7], off
	v_lshl_add_u64 v[6:7], v[158:159], 0, s[4:5]
	s_mov_b32 m0, s13
	v_readfirstlane_b32 s20, v9
	v_lshl_add_u64 v[160:161], v[4:5], 0, v[2:3]
	v_add_u32_e32 v2, 0x4000, v227
	global_load_lds_dwordx4 v[6:7], off
	v_lshl_add_u64 v[6:7], v[158:159], 0, s[94:95]
	s_mov_b32 m0, s20
	v_readfirstlane_b32 s21, v2
	v_add_u32_e32 v2, 0x5000, v227
	global_load_lds_dwordx4 v[6:7], off
	s_mov_b32 m0, s21
	v_readfirstlane_b32 s24, v2
	v_add_u32_e32 v2, 0x6000, v227
	global_load_lds_dwordx4 v[160:161], off
	v_lshl_add_u64 v[4:5], v[160:161], 0, s[30:31]
	s_mov_b32 m0, s24
	v_readfirstlane_b32 s25, v2
	v_add_u32_e32 v2, 0x7000, v227
	global_load_lds_dwordx4 v[4:5], off
	v_lshl_add_u64 v[4:5], v[160:161], 0, s[64:65]
	s_mov_b32 m0, s25
	v_readfirstlane_b32 s42, v2
	v_lshrrev_b32_e32 v10, 4, v8
	v_and_b32_e32 v11, 7, v8
	global_load_lds_dwordx4 v[4:5], off
	v_lshl_add_u64 v[4:5], v[160:161], 0, s[66:67]
	s_mov_b32 m0, s42
	v_bfe_u32 v2, v8, 4, 2
	global_load_lds_dwordx4 v[4:5], off
	v_bitop3_b32 v4, v10, v11, 3 bitop3:0x6c
	v_lshlrev_b32_e32 v20, 4, v4
	v_bitop3_b32 v2, v2, v11, 4 bitop3:0x36
	v_lshlrev_b32_e32 v228, 4, v2
	v_or_b32_e32 v2, v60, v20
	v_or_b32_e32 v224, v225, v20
	s_waitcnt vmcnt(0) lgkmcnt(0)
	s_barrier
; DEVI f32x4 mfma16(bf16x8 a, bf16x8 b, f32x4 c) { return __builtin_amdgcn_mfma_f32_16x16x32_bf16(a, b, c, 0, 0, 0); }
; template <int NTW, bool SPLIT = false, bool HALFA = false>
; DEVI void gemm_core2(f32x4 (&acc)[4][NTW], const bf* __restrict__ A, int lda, const bf* __restrict__ Bt, int ldb, int K, char* smem) {
;     ...
;       if (HALFA) {
; #pragma unroll
;         for (int ks = 0; ks < 2; ++ks) {
;           const int swz = ks ? sw1 : sw0;
;           bf16x8 bfr[NTW];
; #pragma unroll
;           for (int n = 0; n < NTW; ++n) bfr[n] = *reinterpret_cast<const bf16x8*>(bbase + so + n * 16 * 128 + swz);
; #pragma unroll
;           for (int mh = 0; mh < 2; ++mh) {
;             bf16x8 af[2];
; #pragma unroll
;             for (int m = 0; m < 2; ++m) af[m] = *reinterpret_cast<const bf16x8*>(abase + so + (mh * 2 + m) * 16 * 128 + swz);
;             if (ks == 1 && mh == 1) {
; #pragma unroll
;               for (int i = 0; i < 4; ++i) glds16(Ap + i * sa + k1, dbase + sn + i * 4096);
; #pragma unroll
;               for (int i = 0; i < NBL; ++i) glds16(Bp + i * sb + k1, dbase + sn + ASZ + i * 4096);
;             }
; #pragma unroll
;             for (int m = 0; m < 2; ++m)
; #pragma unroll
;               for (int n = 0; n < NTW; ++n) acc[mh * 2 + m][n] = mfma16(af[m], bfr[n], acc[mh * 2 + m][n]);
;           }
;         }
	ds_read_b128 v[4:7], v2 offset:16384
	ds_read_b128 v[8:11], v2 offset:18432
	ds_read_b128 v[12:15], v2 offset:20480
	ds_read_b128 v[16:19], v2 offset:22528
	ds_read_b128 v[20:23], v224
	ds_read_b128 v[24:27], v224 offset:2048
	s_waitcnt lgkmcnt(0)
	v_mfma_f32_16x16x32_bf16 v[84:87], v[24:27], v[4:7], 0
	v_or_b32_e32 v226, v60, v228
	v_or_b32_e32 v225, v225, v228
	v_add_u32_e32 v232, 0x8000, v227
	v_mfma_f32_16x16x32_bf16 v[162:165], v[24:27], v[8:11], 0
	v_readfirstlane_b32 s50, v232
	v_lshl_add_u64 v[90:91], v[158:159], 0, s[36:37]
	s_mov_b32 m0, s50
	v_mfma_f32_16x16x32_bf16 v[192:195], v[24:27], v[12:15], 0
	v_add_u32_e32 v233, 0xc000, v227
	v_lshl_add_u64 v[88:89], v[160:161], 0, s[36:37]
	v_readfirstlane_b32 s45, v233
	v_mfma_f32_16x16x32_bf16 v[196:199], v[24:27], v[16:19], 0
	ds_read_b128 v[24:27], v224 offset:4096
	ds_read_b128 v[44:47], v224 offset:6144
	v_mfma_f32_16x16x32_bf16 v[28:31], v[20:23], v[4:7], 0
	s_waitcnt lgkmcnt(1)
	v_mfma_f32_16x16x32_bf16 v[52:55], v[24:27], v[4:7], 0
	v_mfma_f32_16x16x32_bf16 v[56:59], v[24:27], v[8:11], 0
	v_mfma_f32_16x16x32_bf16 v[64:67], v[24:27], v[12:15], 0
	v_mfma_f32_16x16x32_bf16 v[68:71], v[24:27], v[16:19], 0
	s_waitcnt lgkmcnt(0)
	v_mfma_f32_16x16x32_bf16 v[72:75], v[44:47], v[4:7], 0
	v_mfma_f32_16x16x32_bf16 v[48:51], v[44:47], v[8:11], 0
	v_mfma_f32_16x16x32_bf16 v[40:43], v[44:47], v[12:15], 0
	v_mfma_f32_16x16x32_bf16 v[4:7], v[44:47], v[16:19], 0
	ds_read_b128 v[80:83], v226 offset:16384
	ds_read_b128 v[76:79], v226 offset:18432
	ds_read_b128 v[60:63], v226 offset:20480
	ds_read_b128 v[44:47], v226 offset:22528
	ds_read_b128 v[24:27], v225
	ds_read_b128 v[228:231], v225 offset:2048
	v_mfma_f32_16x16x32_bf16 v[32:35], v[20:23], v[8:11], 0
	v_mfma_f32_16x16x32_bf16 v[36:39], v[20:23], v[12:15], 0
	v_mfma_f32_16x16x32_bf16 v[20:23], v[20:23], v[16:19], 0
	s_waitcnt lgkmcnt(1)
	v_mfma_f32_16x16x32_bf16 v[12:15], v[24:27], v[76:79], v[32:35]
	s_waitcnt lgkmcnt(0)
	v_mfma_f32_16x16x32_bf16 v[32:35], v[228:231], v[60:63], v[192:195]
	s_nop 2
	v_add_u32_e32 v192, 0x9000, v227
	v_mfma_f32_16x16x32_bf16 v[8:11], v[24:27], v[80:83], v[28:31]
	v_readfirstlane_b32 s22, v192
	v_add_u32_e32 v192, 0xa000, v227
	v_mfma_f32_16x16x32_bf16 v[16:19], v[24:27], v[60:63], v[36:39]
	v_readfirstlane_b32 s44, v192
	v_add_u32_e32 v192, 0xb000, v227
	v_mfma_f32_16x16x32_bf16 v[20:23], v[24:27], v[44:47], v[20:23]
	v_readfirstlane_b32 s46, v192
	v_mfma_f32_16x16x32_bf16 v[24:27], v[228:231], v[80:83], v[84:87]
	v_mfma_f32_16x16x32_bf16 v[28:31], v[228:231], v[76:79], v[162:165]
	s_nop 2
	ds_read_b128 v[162:165], v225 offset:4096
	ds_read_b128 v[84:87], v225 offset:6144
	global_load_lds_dwordx4 v[90:91], off
	v_lshl_add_u64 v[90:91], v[158:159], 0, s[0:1]
	s_mov_b32 m0, s22
	v_mfma_f32_16x16x32_bf16 v[36:39], v[228:231], v[44:47], v[196:199]
	global_load_lds_dwordx4 v[90:91], off
	v_lshl_add_u64 v[90:91], v[158:159], 0, s[88:89]
	s_mov_b32 m0, s44
	s_waitcnt lgkmcnt(0)
	v_mfma_f32_16x16x32_bf16 v[52:55], v[162:165], v[80:83], v[52:55]
	global_load_lds_dwordx4 v[90:91], off
	v_lshl_add_u64 v[90:91], v[158:159], 0, s[90:91]
	s_mov_b32 m0, s46
	v_mfma_f32_16x16x32_bf16 v[56:59], v[162:165], v[76:79], v[56:59]
	global_load_lds_dwordx4 v[90:91], off
	v_add_u32_e32 v90, 0xd000, v227
	s_mov_b32 m0, s45
	v_readfirstlane_b32 s47, v90
	v_add_u32_e32 v90, 0xe000, v227
	global_load_lds_dwordx4 v[88:89], off
	v_lshl_add_u64 v[88:89], v[160:161], 0, s[68:69]
	s_mov_b32 m0, s47
	v_readfirstlane_b32 s48, v90
	v_add_u32_e32 v90, 0xf000, v227
	global_load_lds_dwordx4 v[88:89], off
	v_lshl_add_u64 v[88:89], v[160:161], 0, s[70:71]
	s_mov_b32 m0, s48
	v_readfirstlane_b32 s49, v90
	global_load_lds_dwordx4 v[88:89], off
	v_lshl_add_u64 v[88:89], v[160:161], 0, s[72:73]
	s_mov_b32 m0, s49
	v_mfma_f32_16x16x32_bf16 v[64:67], v[162:165], v[60:63], v[64:67]
	global_load_lds_dwordx4 v[88:89], off
	v_mfma_f32_16x16x32_bf16 v[68:71], v[162:165], v[44:47], v[68:71]
	v_mfma_f32_16x16x32_bf16 v[80:83], v[84:87], v[80:83], v[72:75]
	v_mfma_f32_16x16x32_bf16 v[48:51], v[84:87], v[76:79], v[48:51]
	v_mfma_f32_16x16x32_bf16 v[40:43], v[84:87], v[60:63], v[40:43]
	v_mfma_f32_16x16x32_bf16 v[4:7], v[84:87], v[44:47], v[4:7]
	s_setprio 0
	s_waitcnt vmcnt(0) lgkmcnt(0)
	s_barrier
; DEVI f32x4 mfma16(bf16x8 a, bf16x8 b, f32x4 c) { return __builtin_amdgcn_mfma_f32_16x16x32_bf16(a, b, c, 0, 0, 0); }
; template <int NTW, bool SPLIT = false, bool HALFA = false>
; DEVI void gemm_core2(f32x4 (&acc)[4][NTW], const bf* __restrict__ A, int lda, const bf* __restrict__ Bt, int ldb, int K, char* smem) {
;     ...
;       if (HALFA) {
; #pragma unroll
;         for (int ks = 0; ks < 2; ++ks) {
;           const int swz = ks ? sw1 : sw0;
;           bf16x8 bfr[NTW];
; #pragma unroll
;           for (int n = 0; n < NTW; ++n) bfr[n] = *reinterpret_cast<const bf16x8*>(bbase + so + n * 16 * 128 + swz);
; #pragma unroll
;           for (int mh = 0; mh < 2; ++mh) {
;             bf16x8 af[2];
; #pragma unroll
;             for (int m = 0; m < 2; ++m) af[m] = *reinterpret_cast<const bf16x8*>(abase + so + (mh * 2 + m) * 16 * 128 + swz);
;             if (ks == 1 && mh == 1) {
; #pragma unroll
;               for (int i = 0; i < 4; ++i) glds16(Ap + i * sa + k1, dbase + sn + i * 4096);
; #pragma unroll
;               for (int i = 0; i < NBL; ++i) glds16(Bp + i * sb + k1, dbase + sn + ASZ + i * 4096);
;             }
; #pragma unroll
;             for (int m = 0; m < 2; ++m)
; #pragma unroll
;               for (int n = 0; n < NTW; ++n) acc[mh * 2 + m][n] = mfma16(af[m], bfr[n], acc[mh * 2 + m][n]);
;           }
;         }
	ds_read_b128 v[44:47], v2 offset:49152
	ds_read_b128 v[60:63], v2 offset:51200
	ds_read_b128 v[192:195], v2 offset:53248
	ds_read_b128 v[196:199], v2 offset:55296
	ds_read_b128 v[72:75], v224 offset:32768
	ds_read_b128 v[76:79], v224 offset:34816
	s_waitcnt lgkmcnt(1)
	v_mfma_f32_16x16x32_bf16 v[8:11], v[72:75], v[44:47], v[8:11]
	s_mov_b64 s[28:29], 0x100
	v_lshl_add_u64 v[164:165], v[158:159], 0, s[28:29]
	v_lshl_add_u64 v[162:163], v[160:161], 0, s[28:29]
	s_waitcnt lgkmcnt(0)
	v_mfma_f32_16x16x32_bf16 v[228:231], v[76:79], v[44:47], v[24:27]
	s_mov_b32 m0, s43
	s_mov_b64 s[28:29], 0x10100
	v_mfma_f32_16x16x32_bf16 v[232:235], v[76:79], v[60:63], v[28:31]
	ds_read_b128 v[24:27], v224 offset:36864
	s_nop 1
	ds_read_b128 v[28:31], v224 offset:38912
	v_mfma_f32_16x16x32_bf16 v[12:15], v[72:75], v[60:63], v[12:15]
	v_mfma_f32_16x16x32_bf16 v[16:19], v[72:75], v[192:195], v[16:19]
	v_mfma_f32_16x16x32_bf16 v[20:23], v[72:75], v[196:199], v[20:23]
	v_mfma_f32_16x16x32_bf16 v[236:239], v[76:79], v[192:195], v[32:35]
	v_mfma_f32_16x16x32_bf16 v[240:243], v[76:79], v[196:199], v[36:39]
	s_waitcnt lgkmcnt(1)
	v_mfma_f32_16x16x32_bf16 v[88:91], v[24:27], v[44:47], v[52:55]
	v_mfma_f32_16x16x32_bf16 v[84:87], v[24:27], v[60:63], v[56:59]
	v_mfma_f32_16x16x32_bf16 v[76:79], v[24:27], v[192:195], v[64:67]
	v_mfma_f32_16x16x32_bf16 v[72:75], v[24:27], v[196:199], v[68:71]
	s_waitcnt lgkmcnt(0)
	v_mfma_f32_16x16x32_bf16 v[64:67], v[28:31], v[44:47], v[80:83]
	v_mfma_f32_16x16x32_bf16 v[56:59], v[28:31], v[60:63], v[48:51]
	v_mfma_f32_16x16x32_bf16 v[44:47], v[28:31], v[192:195], v[40:43]
	v_mfma_f32_16x16x32_bf16 v[36:39], v[28:31], v[196:199], v[4:7]
	ds_read_b128 v[68:71], v226 offset:49152
	ds_read_b128 v[60:63], v226 offset:51200
	ds_read_b128 v[48:51], v226 offset:53248
	ds_read_b128 v[40:43], v226 offset:55296
	ds_read_b128 v[4:7], v225 offset:32768
	ds_read_b128 v[52:55], v225 offset:34816
	s_waitcnt lgkmcnt(1)
	v_mfma_f32_16x16x32_bf16 v[32:35], v[4:7], v[68:71], v[8:11]
	v_mfma_f32_16x16x32_bf16 v[28:31], v[4:7], v[60:63], v[12:15]
	v_mfma_f32_16x16x32_bf16 v[24:27], v[4:7], v[48:51], v[16:19]
	v_mfma_f32_16x16x32_bf16 v[20:23], v[4:7], v[40:43], v[20:23]
	s_waitcnt lgkmcnt(0)
	v_mfma_f32_16x16x32_bf16 v[4:7], v[52:55], v[68:71], v[228:231]
	v_mfma_f32_16x16x32_bf16 v[8:11], v[52:55], v[60:63], v[232:235]
	v_mfma_f32_16x16x32_bf16 v[12:15], v[52:55], v[48:51], v[236:239]
	v_mfma_f32_16x16x32_bf16 v[16:19], v[52:55], v[40:43], v[240:243]
	ds_read_b128 v[80:83], v225 offset:36864
	ds_read_b128 v[52:55], v225 offset:38912
	global_load_lds_dwordx4 v[164:165], off
	v_lshl_add_u64 v[164:165], v[158:159], 0, s[28:29]
	s_mov_b32 m0, s12
	s_mov_b64 s[28:29], 0x20100
	global_load_lds_dwordx4 v[164:165], off
	v_lshl_add_u64 v[164:165], v[158:159], 0, s[28:29]
	s_mov_b32 m0, s13
	s_mov_b64 s[28:29], 0x30100
	global_load_lds_dwordx4 v[164:165], off
	v_lshl_add_u64 v[164:165], v[158:159], 0, s[28:29]
	s_mov_b32 m0, s20
	s_waitcnt lgkmcnt(0)
	v_mfma_f32_16x16x32_bf16 v[88:91], v[80:83], v[68:71], v[88:91]
	global_load_lds_dwordx4 v[164:165], off
	s_mov_b32 m0, s21
	v_mfma_f32_16x16x32_bf16 v[84:87], v[80:83], v[60:63], v[84:87]
	global_load_lds_dwordx4 v[162:163], off
	v_lshl_add_u64 v[162:163], v[160:161], 0, s[74:75]
	s_mov_b32 m0, s24
	v_mfma_f32_16x16x32_bf16 v[76:79], v[80:83], v[48:51], v[76:79]
	global_load_lds_dwordx4 v[162:163], off
	v_lshl_add_u64 v[162:163], v[160:161], 0, s[76:77]
	s_mov_b32 m0, s25
	v_mfma_f32_16x16x32_bf16 v[72:75], v[80:83], v[40:43], v[72:75]
	global_load_lds_dwordx4 v[162:163], off
	v_lshl_add_u64 v[162:163], v[160:161], 0, s[78:79]
	s_mov_b32 m0, s42
	v_mfma_f32_16x16x32_bf16 v[64:67], v[52:55], v[68:71], v[64:67]
	global_load_lds_dwordx4 v[162:163], off
	v_mfma_f32_16x16x32_bf16 v[56:59], v[52:55], v[60:63], v[56:59]
	v_mfma_f32_16x16x32_bf16 v[44:47], v[52:55], v[48:51], v[44:47]
	v_mfma_f32_16x16x32_bf16 v[36:39], v[52:55], v[40:43], v[36:39]
	s_setprio 0
	s_waitcnt vmcnt(0) lgkmcnt(0)
	s_barrier
	ds_read_b128 v[40:43], v224
	ds_read_b128 v[48:51], v2 offset:16384
	ds_read_b128 v[52:55], v2 offset:18432
	ds_read_b128 v[60:63], v224 offset:2048
	ds_read_b128 v[68:71], v2 offset:20480
	ds_read_b128 v[80:83], v2 offset:22528
	s_waitcnt lgkmcnt(4)
	v_mfma_f32_16x16x32_bf16 v[32:35], v[40:43], v[48:51], v[32:35]
	s_mov_b64 s[28:29], 0x180
	s_mov_b32 m0, s50
	v_lshl_add_u64 v[192:193], v[158:159], 0, s[28:29]
	s_waitcnt lgkmcnt(3)
	v_mfma_f32_16x16x32_bf16 v[28:31], v[40:43], v[52:55], v[28:31]
	v_lshl_add_u64 v[194:195], v[160:161], 0, s[28:29]
	s_mov_b64 s[28:29], 0x10180
	v_lshl_add_u64 v[196:197], v[158:159], 0, s[28:29]
	s_waitcnt lgkmcnt(1)
	v_mfma_f32_16x16x32_bf16 v[24:27], v[40:43], v[68:71], v[24:27]
	s_mov_b64 s[28:29], 0x20180
	v_lshl_add_u64 v[198:199], v[158:159], 0, s[28:29]
	s_mov_b64 s[28:29], 0x30180
	s_waitcnt lgkmcnt(0)
	v_mfma_f32_16x16x32_bf16 v[20:23], v[40:43], v[80:83], v[20:23]
	v_lshl_add_u64 v[158:159], v[158:159], 0, s[28:29]
	s_mov_b64 s[28:29], 0x4180
	v_lshl_add_u64 v[228:229], v[160:161], 0, s[28:29]
	v_mfma_f32_16x16x32_bf16 v[4:7], v[60:63], v[48:51], v[4:7]
	s_mov_b64 s[28:29], 0x8180
	v_lshl_add_u64 v[230:231], v[160:161], 0, s[28:29]
	s_mov_b64 s[28:29], 0xc180
	v_mfma_f32_16x16x32_bf16 v[8:11], v[60:63], v[52:55], v[8:11]
	v_lshl_add_u64 v[160:161], v[160:161], 0, s[28:29]
	v_mfma_f32_16x16x32_bf16 v[12:15], v[60:63], v[68:71], v[12:15]
	v_mfma_f32_16x16x32_bf16 v[16:19], v[60:63], v[80:83], v[16:19]
	ds_read_b128 v[40:43], v224 offset:4096
	ds_read_b128 v[60:63], v224 offset:6144
	s_waitcnt lgkmcnt(1)
	v_mfma_f32_16x16x32_bf16 v[84:87], v[40:43], v[52:55], v[84:87]
	s_waitcnt lgkmcnt(0)
; DEVI f32x4 mfma16(bf16x8 a, bf16x8 b, f32x4 c) { return __builtin_amdgcn_mfma_f32_16x16x32_bf16(a, b, c, 0, 0, 0); }
; template <int NTW, bool SPLIT = false, bool HALFA = false>
; DEVI void gemm_core2(f32x4 (&acc)[4][NTW], const bf* __restrict__ A, int lda, const bf* __restrict__ Bt, int ldb, int K, char* smem) {
;     ...
;       if (HALFA) {
; #pragma unroll
;         for (int ks = 0; ks < 2; ++ks) {
;           const int swz = ks ? sw1 : sw0;
;           bf16x8 bfr[NTW];
; #pragma unroll
;           for (int n = 0; n < NTW; ++n) bfr[n] = *reinterpret_cast<const bf16x8*>(bbase + so + n * 16 * 128 + swz);
; #pragma unroll
;           for (int mh = 0; mh < 2; ++mh) {
;             bf16x8 af[2];
; #pragma unroll
;             for (int m = 0; m < 2; ++m) af[m] = *reinterpret_cast<const bf16x8*>(abase + so + (mh * 2 + m) * 16 * 128 + swz);
;             if (ks == 1 && mh == 1) {
; #pragma unroll
;               for (int i = 0; i < 4; ++i) glds16(Ap + i * sa + k1, dbase + sn + i * 4096);
; #pragma unroll
;               for (int i = 0; i < NBL; ++i) glds16(Bp + i * sb + k1, dbase + sn + ASZ + i * 4096);
;             }
; #pragma unroll
;             for (int m = 0; m < 2; ++m)
; #pragma unroll
;               for (int n = 0; n < NTW; ++n) acc[mh * 2 + m][n] = mfma16(af[m], bfr[n], acc[mh * 2 + m][n]);
;           }
;         }
	v_mfma_f32_16x16x32_bf16 v[52:55], v[60:63], v[52:55], v[56:59]
	s_nop 2
	ds_read_b128 v[56:59], v225
	v_mfma_f32_16x16x32_bf16 v[88:91], v[40:43], v[48:51], v[88:91]
	v_mfma_f32_16x16x32_bf16 v[76:79], v[40:43], v[68:71], v[76:79]
	v_mfma_f32_16x16x32_bf16 v[40:43], v[40:43], v[80:83], v[72:75]
	v_mfma_f32_16x16x32_bf16 v[48:51], v[60:63], v[48:51], v[64:67]
	v_mfma_f32_16x16x32_bf16 v[44:47], v[60:63], v[68:71], v[44:47]
	v_mfma_f32_16x16x32_bf16 v[36:39], v[60:63], v[80:83], v[36:39]
	ds_read_b128 v[60:63], v226 offset:16384
	ds_read_b128 v[64:67], v226 offset:18432
	ds_read_b128 v[68:71], v225 offset:2048
	ds_read_b128 v[72:75], v226 offset:20480
	ds_read_b128 v[80:83], v226 offset:22528
	ds_read_b128 v[162:165], v225 offset:6144
	s_waitcnt lgkmcnt(5)
	v_mfma_f32_16x16x32_bf16 v[32:35], v[56:59], v[60:63], v[32:35]
	s_waitcnt lgkmcnt(4)
	v_mfma_f32_16x16x32_bf16 v[28:31], v[56:59], v[64:67], v[28:31]
	s_waitcnt lgkmcnt(2)
	v_mfma_f32_16x16x32_bf16 v[24:27], v[56:59], v[72:75], v[24:27]
	s_waitcnt lgkmcnt(1)
	v_mfma_f32_16x16x32_bf16 v[20:23], v[56:59], v[80:83], v[20:23]
	ds_read_b128 v[56:59], v225 offset:4096
	global_load_lds_dwordx4 v[192:193], off
	s_mov_b32 m0, s22
	v_mfma_f32_16x16x32_bf16 v[4:7], v[68:71], v[60:63], v[4:7]
	global_load_lds_dwordx4 v[196:197], off
	s_mov_b32 m0, s44
	v_mfma_f32_16x16x32_bf16 v[8:11], v[68:71], v[64:67], v[8:11]
	global_load_lds_dwordx4 v[198:199], off
	s_mov_b32 m0, s46
	v_mfma_f32_16x16x32_bf16 v[12:15], v[68:71], v[72:75], v[12:15]
	global_load_lds_dwordx4 v[158:159], off
	s_mov_b32 m0, s45
	v_mfma_f32_16x16x32_bf16 v[16:19], v[68:71], v[80:83], v[16:19]
	global_load_lds_dwordx4 v[194:195], off
	s_mov_b32 m0, s47
	s_waitcnt lgkmcnt(0)
	v_mfma_f32_16x16x32_bf16 v[68:71], v[56:59], v[60:63], v[88:91]
	global_load_lds_dwordx4 v[228:229], off
	s_mov_b32 m0, s48
	v_mfma_f32_16x16x32_bf16 v[84:87], v[56:59], v[64:67], v[84:87]
	global_load_lds_dwordx4 v[230:231], off
	s_mov_b32 m0, s49
	v_mfma_f32_16x16x32_bf16 v[76:79], v[56:59], v[72:75], v[76:79]
	global_load_lds_dwordx4 v[160:161], off
	v_mfma_f32_16x16x32_bf16 v[40:43], v[56:59], v[80:83], v[40:43]
	v_mfma_f32_16x16x32_bf16 v[48:51], v[162:165], v[60:63], v[48:51]
	v_mfma_f32_16x16x32_bf16 v[52:55], v[162:165], v[64:67], v[52:55]
	v_mfma_f32_16x16x32_bf16 v[44:47], v[162:165], v[72:75], v[44:47]
	v_mfma_f32_16x16x32_bf16 v[36:39], v[162:165], v[80:83], v[36:39]
	s_setprio 0
	s_waitcnt vmcnt(0) lgkmcnt(0)
	s_barrier
	ds_read_b128 v[56:59], v224 offset:32768
	ds_read_b128 v[60:63], v2 offset:49152
	ds_read_b128 v[64:67], v2 offset:51200
	ds_read_b128 v[72:75], v2 offset:53248
	ds_read_b128 v[80:83], v2 offset:55296
	s_waitcnt lgkmcnt(3)
	v_mfma_f32_16x16x32_bf16 v[32:35], v[56:59], v[60:63], v[32:35]
	s_mov_b32 m0, s43
	s_waitcnt lgkmcnt(2)
	v_mfma_f32_16x16x32_bf16 v[28:31], v[56:59], v[64:67], v[28:31]
	s_waitcnt lgkmcnt(1)
	v_mfma_f32_16x16x32_bf16 v[24:27], v[56:59], v[72:75], v[24:27]
	s_waitcnt lgkmcnt(0)
	v_mfma_f32_16x16x32_bf16 v[20:23], v[56:59], v[80:83], v[20:23]
	ds_read_b128 v[56:59], v224 offset:34816
	s_waitcnt lgkmcnt(0)
	v_mfma_f32_16x16x32_bf16 v[4:7], v[56:59], v[60:63], v[4:7]
	v_mfma_f32_16x16x32_bf16 v[8:11], v[56:59], v[64:67], v[8:11]
	v_mfma_f32_16x16x32_bf16 v[12:15], v[56:59], v[72:75], v[12:15]
	v_mfma_f32_16x16x32_bf16 v[16:19], v[56:59], v[80:83], v[16:19]
	ds_read_b128 v[56:59], v224 offset:36864
	s_waitcnt lgkmcnt(0)
	v_mfma_f32_16x16x32_bf16 v[68:71], v[56:59], v[60:63], v[68:71]
	v_mfma_f32_16x16x32_bf16 v[84:87], v[56:59], v[64:67], v[84:87]
	v_mfma_f32_16x16x32_bf16 v[76:79], v[56:59], v[72:75], v[76:79]
	v_mfma_f32_16x16x32_bf16 v[40:43], v[56:59], v[80:83], v[40:43]
	ds_read_b128 v[56:59], v224 offset:38912
	s_waitcnt lgkmcnt(0)
	v_mfma_f32_16x16x32_bf16 v[48:51], v[56:59], v[60:63], v[48:51]
	ds_read_b128 v[60:63], v225 offset:32768
	v_mfma_f32_16x16x32_bf16 v[52:55], v[56:59], v[64:67], v[52:55]
	ds_read_b128 v[64:67], v226 offset:51200
	v_mfma_f32_16x16x32_bf16 v[44:47], v[56:59], v[72:75], v[44:47]
	ds_read_b128 v[72:75], v226 offset:53248
	v_mfma_f32_16x16x32_bf16 v[36:39], v[56:59], v[80:83], v[36:39]
	ds_read_b128 v[56:59], v226 offset:49152
	ds_read_b128 v[80:83], v226 offset:55296
	s_waitcnt lgkmcnt(1)
	v_mfma_f32_16x16x32_bf16 v[32:35], v[60:63], v[56:59], v[32:35]
	v_mfma_f32_16x16x32_bf16 v[28:31], v[60:63], v[64:67], v[28:31]
	v_mfma_f32_16x16x32_bf16 v[24:27], v[60:63], v[72:75], v[24:27]
	s_waitcnt lgkmcnt(0)
	v_mfma_f32_16x16x32_bf16 v[20:23], v[60:63], v[80:83], v[20:23]
	ds_read_b128 v[60:63], v225 offset:34816
	s_waitcnt lgkmcnt(0)
	v_mfma_f32_16x16x32_bf16 v[88:91], v[60:63], v[56:59], v[4:7]
	s_nop 2
	ds_read_b128 v[4:7], v225 offset:36864
	v_mfma_f32_16x16x32_bf16 v[8:11], v[60:63], v[64:67], v[8:11]
	v_mfma_f32_16x16x32_bf16 v[12:15], v[60:63], v[72:75], v[12:15]
	v_mfma_f32_16x16x32_bf16 v[16:19], v[60:63], v[80:83], v[16:19]
	ds_read_b128 v[60:63], v225 offset:38912
	global_load_lds_dwordx4 v[192:193], off
	s_mov_b32 m0, s12
	s_waitcnt lgkmcnt(0)
; DEVI f32x4 mfma16(bf16x8 a, bf16x8 b, f32x4 c) { return __builtin_amdgcn_mfma_f32_16x16x32_bf16(a, b, c, 0, 0, 0); }
; template <int NTW, bool SPLIT = false, bool HALFA = false>
; DEVI void gemm_core2(f32x4 (&acc)[4][NTW], const bf* __restrict__ A, int lda, const bf* __restrict__ Bt, int ldb, int K, char* smem) {
;     ...
;       if (HALFA) {
; #pragma unroll
;         for (int ks = 0; ks < 2; ++ks) {
;           const int swz = ks ? sw1 : sw0;
;           bf16x8 bfr[NTW];
; #pragma unroll
;           for (int n = 0; n < NTW; ++n) bfr[n] = *reinterpret_cast<const bf16x8*>(bbase + so + n * 16 * 128 + swz);
; #pragma unroll
;           for (int mh = 0; mh < 2; ++mh) {
;             bf16x8 af[2];
; #pragma unroll
;             for (int m = 0; m < 2; ++m) af[m] = *reinterpret_cast<const bf16x8*>(abase + so + (mh * 2 + m) * 16 * 128 + swz);
;             if (ks == 1 && mh == 1) {
; #pragma unroll
;               for (int i = 0; i < 4; ++i) glds16(Ap + i * sa + k1, dbase + sn + i * 4096);
; #pragma unroll
;               for (int i = 0; i < NBL; ++i) glds16(Bp + i * sb + k1, dbase + sn + ASZ + i * 4096);
;             }
; #pragma unroll
;             for (int m = 0; m < 2; ++m)
; #pragma unroll
;               for (int n = 0; n < NTW; ++n) acc[mh * 2 + m][n] = mfma16(af[m], bfr[n], acc[mh * 2 + m][n]);
;           }
;         }
; template <int NTW>
; DEVI void merge_tile(const P& p, long row0, int n0, char* smem) {
;     ...
;         accM[m][n][0] += __uint_as_float(pg[m][n][0] << 16) * accT[m][n][0];
;         accM[m][n][1] += __uint_as_float(pg[m][n][0] & 0xffff0000u) * accT[m][n][1];
;         accM[m][n][2] += __uint_as_float(pg[m][n][1] << 16) * accT[m][n][2];
;         accM[m][n][3] += __uint_as_float(pg[m][n][1] & 0xffff0000u) * accT[m][n][3];
;       }
	v_mfma_f32_16x16x32_bf16 v[68:71], v[4:7], v[56:59], v[68:71]
	global_load_lds_dwordx4 v[196:197], off
	s_mov_b32 m0, s13
	v_mfma_f32_16x16x32_bf16 v[84:87], v[4:7], v[64:67], v[84:87]
	global_load_lds_dwordx4 v[198:199], off
	s_mov_b32 m0, s20
	v_mfma_f32_16x16x32_bf16 v[76:79], v[4:7], v[72:75], v[76:79]
	global_load_lds_dwordx4 v[158:159], off
	s_mov_b32 m0, s21
	v_mfma_f32_16x16x32_bf16 v[40:43], v[4:7], v[80:83], v[40:43]
	global_load_lds_dwordx4 v[194:195], off
	s_mov_b32 m0, s24
	v_mfma_f32_16x16x32_bf16 v[48:51], v[60:63], v[56:59], v[48:51]
	global_load_lds_dwordx4 v[228:229], off
	s_mov_b32 m0, s25
	v_mfma_f32_16x16x32_bf16 v[52:55], v[60:63], v[64:67], v[52:55]
	global_load_lds_dwordx4 v[230:231], off
	s_mov_b32 m0, s42
	v_mfma_f32_16x16x32_bf16 v[44:47], v[60:63], v[72:75], v[44:47]
	global_load_lds_dwordx4 v[160:161], off
	v_mfma_f32_16x16x32_bf16 v[4:7], v[60:63], v[80:83], v[36:39]
	s_setprio 0
	s_nop 1
	v_lshlrev_b32_e32 v36, 16, v166
	v_and_b32_e32 v37, 0xffff0000, v166
	v_pk_fma_f32 v[156:157], v[32:33], v[36:37], v[156:157]
	v_lshlrev_b32_e32 v32, 16, v167
	v_and_b32_e32 v33, 0xffff0000, v167
	v_pk_fma_f32 v[154:155], v[34:35], v[32:33], v[154:155]
	v_lshlrev_b32_e32 v32, 16, v168
	v_and_b32_e32 v33, 0xffff0000, v168
	v_pk_fma_f32 v[150:151], v[28:29], v[32:33], v[150:151]
	v_lshlrev_b32_e32 v28, 16, v169
	v_and_b32_e32 v29, 0xffff0000, v169
	v_pk_fma_f32 v[148:149], v[30:31], v[28:29], v[148:149]
	v_lshlrev_b32_e32 v28, 16, v170
	v_and_b32_e32 v29, 0xffff0000, v170
	v_pk_fma_f32 v[146:147], v[24:25], v[28:29], v[146:147]
	v_lshlrev_b32_e32 v24, 16, v171
	v_and_b32_e32 v25, 0xffff0000, v171
	v_pk_fma_f32 v[144:145], v[26:27], v[24:25], v[144:145]
	v_lshlrev_b32_e32 v24, 16, v172
	v_and_b32_e32 v25, 0xffff0000, v172
	v_pk_fma_f32 v[142:143], v[20:21], v[24:25], v[142:143]
	v_lshlrev_b32_e32 v20, 16, v173
	v_and_b32_e32 v21, 0xffff0000, v173
	v_pk_fma_f32 v[140:141], v[22:23], v[20:21], v[140:141]
	v_lshlrev_b32_e32 v20, 16, v174
	v_and_b32_e32 v21, 0xffff0000, v174
	v_pk_fma_f32 v[138:139], v[88:89], v[20:21], v[138:139]
	v_lshlrev_b32_e32 v20, 16, v175
	v_and_b32_e32 v21, 0xffff0000, v175
	v_pk_fma_f32 v[136:137], v[90:91], v[20:21], v[136:137]
	v_lshlrev_b32_e32 v20, 16, v176
	v_and_b32_e32 v21, 0xffff0000, v176
	v_pk_fma_f32 v[134:135], v[8:9], v[20:21], v[134:135]
	v_lshlrev_b32_e32 v8, 16, v177
	v_and_b32_e32 v9, 0xffff0000, v177
	v_pk_fma_f32 v[132:133], v[10:11], v[8:9], v[132:133]
	v_lshlrev_b32_e32 v8, 16, v204
	v_and_b32_e32 v9, 0xffff0000, v204
	v_pk_fma_f32 v[130:131], v[12:13], v[8:9], v[130:131]
	v_lshlrev_b32_e32 v8, 16, v205
	v_and_b32_e32 v9, 0xffff0000, v205
	v_pk_fma_f32 v[128:129], v[14:15], v[8:9], v[128:129]
	v_lshlrev_b32_e32 v8, 16, v206
	v_and_b32_e32 v9, 0xffff0000, v206
	v_pk_fma_f32 v[126:127], v[16:17], v[8:9], v[126:127]
	v_lshlrev_b32_e32 v8, 16, v207
	v_and_b32_e32 v9, 0xffff0000, v207
	v_pk_fma_f32 v[124:125], v[18:19], v[8:9], v[124:125]
	v_lshlrev_b32_e32 v8, 16, v208
	v_and_b32_e32 v9, 0xffff0000, v208
	v_pk_fma_f32 v[122:123], v[68:69], v[8:9], v[122:123]
	v_lshlrev_b32_e32 v8, 16, v209
	v_and_b32_e32 v9, 0xffff0000, v209
	v_pk_fma_f32 v[120:121], v[70:71], v[8:9], v[120:121]
	v_lshlrev_b32_e32 v8, 16, v210
	v_and_b32_e32 v9, 0xffff0000, v210
	v_pk_fma_f32 v[118:119], v[84:85], v[8:9], v[118:119]
	v_lshlrev_b32_e32 v8, 16, v211
	v_and_b32_e32 v9, 0xffff0000, v211
	v_pk_fma_f32 v[116:117], v[86:87], v[8:9], v[116:117]
	v_lshlrev_b32_e32 v8, 16, v212
	v_and_b32_e32 v9, 0xffff0000, v212
	v_pk_fma_f32 v[114:115], v[76:77], v[8:9], v[114:115]
	v_lshlrev_b32_e32 v8, 16, v213
	v_and_b32_e32 v9, 0xffff0000, v213
	v_pk_fma_f32 v[112:113], v[78:79], v[8:9], v[112:113]
	v_lshlrev_b32_e32 v8, 16, v214
	v_and_b32_e32 v9, 0xffff0000, v214
	v_pk_fma_f32 v[110:111], v[40:41], v[8:9], v[110:111]
	v_lshlrev_b32_e32 v8, 16, v215
	v_and_b32_e32 v9, 0xffff0000, v215
	v_pk_fma_f32 v[108:109], v[42:43], v[8:9], v[108:109]
	v_lshlrev_b32_e32 v8, 16, v216
	v_and_b32_e32 v9, 0xffff0000, v216
	v_pk_fma_f32 v[106:107], v[48:49], v[8:9], v[106:107]
	v_lshlrev_b32_e32 v8, 16, v217
	v_and_b32_e32 v9, 0xffff0000, v217
	v_pk_fma_f32 v[104:105], v[50:51], v[8:9], v[104:105]
	v_lshlrev_b32_e32 v8, 16, v218
	v_and_b32_e32 v9, 0xffff0000, v218
	v_pk_fma_f32 v[102:103], v[52:53], v[8:9], v[102:103]
	v_lshlrev_b32_e32 v8, 16, v219
	v_and_b32_e32 v9, 0xffff0000, v219
	v_pk_fma_f32 v[100:101], v[54:55], v[8:9], v[100:101]
	v_lshlrev_b32_e32 v8, 16, v220
	v_and_b32_e32 v9, 0xffff0000, v220
	v_pk_fma_f32 v[98:99], v[44:45], v[8:9], v[98:99]
	v_lshlrev_b32_e32 v8, 16, v221
	v_and_b32_e32 v9, 0xffff0000, v221
	v_pk_fma_f32 v[96:97], v[46:47], v[8:9], v[96:97]
	v_lshlrev_b32_e32 v8, 16, v222
	v_and_b32_e32 v9, 0xffff0000, v222
	v_pk_fma_f32 v[94:95], v[4:5], v[8:9], v[94:95]
	v_lshlrev_b32_e32 v4, 16, v223
	v_and_b32_e32 v5, 0xffff0000, v223
	s_add_i32 s3, s3, 1
	s_cmp_lg_u32 s3, 4
	v_pk_fma_f32 v[92:93], v[6:7], v[4:5], v[92:93]
	s_waitcnt vmcnt(0) lgkmcnt(0)
	s_barrier
	s_cbranch_scc1 .LBB0_214
; DEVI int get_tid() { int t = threadIdx.x; asm volatile("" : "+v"(t)); return t; }
; template <int BN>
; DEVI void tile_store(const char* smem, bf* __restrict__ C, long ldc, long row0, int col0) {
;   constexpr int LDT = BN + 8;
;   const int tid = get_tid();
;   const int r = tid >> 1, half = tid & 1;
; #pragma unroll
;   for (int c = 0; c < BN / 16; ++c) {
;     u32x4 v = *reinterpret_cast<const u32x4*>(smem + (r * LDT + half * (BN / 2) + c * 8) * 2);
;     *reinterpret_cast<u32x4*>(C + (row0 + r) * ldc + col0 + half * (BN / 2) + c * 8) = v;
;   }
; }
; template <int NTW>
; DEVI void merge_tile(const P& p, long row0, int n0, char* smem) {
;     ...
;   bf* tl = reinterpret_cast<bf*>(smem);
; #pragma unroll
;   for (int m = 0; m < 4; ++m)
; #pragma unroll
;     for (int n = 0; n < NTW; ++n) {
;       const int cl = wc * 16 * NTW + n * 16 + l15;
; #pragma unroll
;       for (int j = 0; j < 4; ++j) tl[(wr * 64 + m * 16 + quad * 4 + j) * LDT + cl] = f2bf(accM[m][n][j]);
;     }
;   __syncthreads();
;   tile_store<BN>(smem, p.UZ, DM, row0, n0);
;   __syncthreads();
; DEVI void phase_merge(const P& p, char* smem) {
;   for (int v = blockIdx.x; v < 256 * 8; v += gridDim.x) {
;     int mtl, nt;
;     lat_tile_map(v, 8, mtl, nt);
;     merge_tile<4>(p, lat_row0(mtl), nt * 128, smem);
	v_and_b32_e32 v2, 0x4f, v1
	v_lshrrev_b32_e32 v4, 1, v1
	v_lshrrev_b32_e32 v1, 2, v1
	v_and_b32_e32 v1, 12, v1
	v_and_or_b32 v1, v4, s23, v1
	v_mul_lo_u32 v1, v1, s16
	v_lshl_add_u32 v1, v2, 1, v1
	v_cvt_pk_bf16_f32 v2, v157, s0
	ds_write_b16 v1, v2 offset:272
	v_cvt_pk_bf16_f32 v2, v154, s0
	ds_write_b16 v1, v2 offset:544
	v_cvt_pk_bf16_f32 v2, v155, s0
	ds_write_b16 v1, v2 offset:816
	v_cvt_pk_bf16_f32 v2, v150, s0
	ds_write_b16 v1, v2 offset:32
	v_cvt_pk_bf16_f32 v2, v151, s0
	ds_write_b16 v1, v2 offset:304
	v_cvt_pk_bf16_f32 v2, v148, s0
	ds_write_b16 v1, v2 offset:576
	v_cvt_pk_bf16_f32 v2, v149, s0
	ds_write_b16 v1, v2 offset:848
	v_cvt_pk_bf16_f32 v2, v146, s0
	ds_write_b16 v1, v2 offset:64
	v_cvt_pk_bf16_f32 v2, v147, s0
	ds_write_b16 v1, v2 offset:336
	v_cvt_pk_bf16_f32 v2, v144, s0
	ds_write_b16 v1, v2 offset:608
	v_cvt_pk_bf16_f32 v2, v145, s0
	ds_write_b16 v1, v2 offset:880
	v_cvt_pk_bf16_f32 v2, v142, s0
	ds_write_b16 v1, v2 offset:96
	v_cvt_pk_bf16_f32 v2, v143, s0
	ds_write_b16 v1, v2 offset:368
	v_cvt_pk_bf16_f32 v2, v140, s0
	ds_write_b16 v1, v2 offset:640
	v_cvt_pk_bf16_f32 v2, v141, s0
	ds_write_b16 v1, v2 offset:912
	v_cvt_pk_bf16_f32 v2, v138, s0
	ds_write_b16 v1, v2 offset:4352
	v_cvt_pk_bf16_f32 v2, v139, s0
	ds_write_b16 v1, v2 offset:4624
	v_cvt_pk_bf16_f32 v2, v136, s0
	ds_write_b16 v1, v2 offset:4896
	v_cvt_pk_bf16_f32 v2, v137, s0
	ds_write_b16 v1, v2 offset:5168
	v_cvt_pk_bf16_f32 v2, v134, s0
	ds_write_b16 v1, v2 offset:4384
	v_cvt_pk_bf16_f32 v2, v135, s0
	ds_write_b16 v1, v2 offset:4656
	v_cvt_pk_bf16_f32 v2, v132, s0
	ds_write_b16 v1, v2 offset:4928
	v_cvt_pk_bf16_f32 v2, v133, s0
	ds_write_b16 v1, v2 offset:5200
	v_cvt_pk_bf16_f32 v2, v130, s0
	ds_write_b16 v1, v2 offset:4416
	v_cvt_pk_bf16_f32 v2, v131, s0
	ds_write_b16 v1, v2 offset:4688
	v_cvt_pk_bf16_f32 v2, v128, s0
	ds_write_b16 v1, v2 offset:4960
	v_cvt_pk_bf16_f32 v2, v129, s0
	ds_write_b16 v1, v2 offset:5232
	v_cvt_pk_bf16_f32 v2, v126, s0
	ds_write_b16 v1, v2 offset:4448
	v_cvt_pk_bf16_f32 v2, v127, s0
	ds_write_b16 v1, v2 offset:4720
	v_cvt_pk_bf16_f32 v2, v124, s0
	ds_write_b16 v1, v2 offset:4992
	v_cvt_pk_bf16_f32 v2, v125, s0
	ds_write_b16 v1, v2 offset:5264
	v_cvt_pk_bf16_f32 v2, v122, s0
	ds_write_b16 v1, v2 offset:8704
	v_cvt_pk_bf16_f32 v2, v123, s0
	ds_write_b16 v1, v2 offset:8976
	v_cvt_pk_bf16_f32 v2, v120, s0
	ds_write_b16 v1, v2 offset:9248
	v_cvt_pk_bf16_f32 v2, v121, s0
	ds_write_b16 v1, v2 offset:9520
	v_cvt_pk_bf16_f32 v2, v118, s0
	ds_write_b16 v1, v2 offset:8736
	v_cvt_pk_bf16_f32 v2, v119, s0
	ds_write_b16 v1, v2 offset:9008
	v_cvt_pk_bf16_f32 v2, v116, s0
	ds_write_b16 v1, v2 offset:9280
	v_cvt_pk_bf16_f32 v2, v117, s0
	ds_write_b16 v1, v2 offset:9552
	v_cvt_pk_bf16_f32 v2, v114, s0
	ds_write_b16 v1, v2 offset:8768
	v_cvt_pk_bf16_f32 v2, v115, s0
	ds_write_b16 v1, v2 offset:9040
	v_cvt_pk_bf16_f32 v2, v112, s0
	ds_write_b16 v1, v2 offset:9312
	v_cvt_pk_bf16_f32 v2, v113, s0
	ds_write_b16 v1, v2 offset:9584
	v_cvt_pk_bf16_f32 v2, v110, s0
	ds_write_b16 v1, v2 offset:8800
	v_cvt_pk_bf16_f32 v2, v111, s0
	ds_write_b16 v1, v2 offset:9072
	v_cvt_pk_bf16_f32 v2, v108, s0
	ds_write_b16 v1, v2 offset:9344
	v_cvt_pk_bf16_f32 v2, v109, s0
	ds_write_b16 v1, v2 offset:9616
	v_cvt_pk_bf16_f32 v2, v106, s0
	ds_write_b16 v1, v2 offset:13056
	v_cvt_pk_bf16_f32 v2, v107, s0
	ds_write_b16 v1, v2 offset:13328
	v_cvt_pk_bf16_f32 v2, v104, s0
	ds_write_b16 v1, v2 offset:13600
	v_cvt_pk_bf16_f32 v2, v105, s0
	ds_write_b16 v1, v2 offset:13872
	v_cvt_pk_bf16_f32 v2, v102, s0
	ds_write_b16 v1, v2 offset:13088
	v_cvt_pk_bf16_f32 v2, v103, s0
	ds_write_b16 v1, v2 offset:13360
	v_cvt_pk_bf16_f32 v2, v100, s0
	ds_write_b16 v1, v2 offset:13632
	v_cvt_pk_bf16_f32 v2, v101, s0
	ds_write_b16 v1, v2 offset:13904
	v_cvt_pk_bf16_f32 v2, v98, s0
	ds_write_b16 v1, v2 offset:13120
	v_cvt_pk_bf16_f32 v2, v99, s0
	ds_write_b16 v1, v2 offset:13392
	v_cvt_pk_bf16_f32 v2, v96, s0
	ds_write_b16 v1, v2 offset:13664
	v_cvt_pk_bf16_f32 v2, v97, s0
	ds_write_b16 v1, v2 offset:13936
	v_cvt_pk_bf16_f32 v2, v94, s0
	ds_write_b16 v1, v2 offset:13152
	v_cvt_pk_bf16_f32 v2, v95, s0
	ds_write_b16 v1, v2 offset:13424
	v_cvt_pk_bf16_f32 v2, v92, s0
	v_cvt_pk_bf16_f32 v4, v156, s0
	ds_write_b16 v1, v2 offset:13696
	v_cvt_pk_bf16_f32 v2, v93, s0
	ds_write_b16 v1, v4
	ds_write_b16 v1, v2 offset:13968
	v_mov_b32_e32 v1, v178
	s_waitcnt lgkmcnt(0)
	s_barrier
	v_readlane_b32 s64, v251, 58
	v_ashrrev_i32_e32 v4, 1, v1
	v_ashrrev_i32_e32 v5, 31, v4
	v_mul_lo_u32 v6, v4, s83
	v_lshlrev_b32_e32 v1, 6, v1
	v_lshl_add_u64 v[4:5], s[34:35], 0, v[4:5]
	v_and_b32_e32 v1, 64, v1
	v_lshlrev_b64 v[4:5], 11, v[4:5]
	v_readlane_b32 s66, v251, 60
	v_readlane_b32 s67, v251, 61
	v_lshlrev_b32_e32 v2, 1, v1
	v_add_lshl_u32 v1, v6, v1, 1
	v_lshl_add_u64 v[4:5], s[66:67], 0, v[4:5]
	v_lshl_add_u64 v[16:17], s[38:39], 1, v[4:5]
	ds_read_b128 v[4:7], v1
	ds_read_b128 v[8:11], v1 offset:16
	ds_read_b128 v[12:15], v1 offset:32
	v_lshl_add_u64 v[24:25], v[16:17], 0, v[2:3]
	ds_read_b128 v[16:19], v1 offset:48
	s_waitcnt lgkmcnt(3)
	global_store_dwordx4 v[24:25], v[4:7], off
	s_waitcnt lgkmcnt(2)
	global_store_dwordx4 v[24:25], v[8:11], off offset:16
	s_waitcnt lgkmcnt(1)
	global_store_dwordx4 v[24:25], v[12:15], off offset:32
	ds_read_b128 v[4:7], v1 offset:64
	ds_read_b128 v[8:11], v1 offset:80
	ds_read_b128 v[12:15], v1 offset:96
	ds_read_b128 v[20:23], v1 offset:112
	v_readlane_b32 s10, v252, 59
	s_add_i32 s2, s2, s10
	v_readlane_b32 s65, v251, 59
	v_readlane_b32 s70, v252, 0
	v_readlane_b32 s71, v252, 1
	s_cmpk_gt_i32 s2, 0x7ff
	v_readlane_b32 s68, v251, 62
	v_readlane_b32 s69, v251, 63
	v_readlane_b32 s72, v252, 2
	v_readlane_b32 s73, v252, 3
	v_readlane_b32 s74, v252, 4
	v_readlane_b32 s75, v252, 5
	v_readlane_b32 s76, v252, 6
	v_readlane_b32 s77, v252, 7
	v_readlane_b32 s78, v252, 8
	v_readlane_b32 s79, v252, 9
	s_waitcnt lgkmcnt(4)
	global_store_dwordx4 v[24:25], v[16:19], off offset:48
	s_waitcnt lgkmcnt(3)
	global_store_dwordx4 v[24:25], v[4:7], off offset:64
	s_waitcnt lgkmcnt(2)
	global_store_dwordx4 v[24:25], v[8:11], off offset:80
	s_waitcnt lgkmcnt(1)
	global_store_dwordx4 v[24:25], v[12:15], off offset:96
	s_waitcnt lgkmcnt(0)
	global_store_dwordx4 v[24:25], v[20:23], off offset:112
	s_barrier
	v_readlane_b32 s11, v252, 60
	s_cbranch_scc0 .LBB0_213

; DEVI f32x4 mfma16(bf16x8 a, bf16x8 b, f32x4 c) { return __builtin_amdgcn_mfma_f32_16x16x32_bf16(a, b, c, 0, 0, 0); }
; template <int NTW, bool SPLIT = false, bool HALFA = false>
; DEVI void gemm_core2(f32x4 (&acc)[4][NTW], const bf* __restrict__ A, int lda, const bf* __restrict__ Bt, int ldb, int K, char* smem) {
;     ...
;       for (int ks = 0; ks < 2; ++ks) {
;         const int swz = ks ? sw1 : sw0;
;         bf16x8 af[4], bfr[NTW];
; #pragma unroll
;         for (int m = 0; m < 4; ++m) af[m] = *reinterpret_cast<const bf16x8*>(abase + so + m * 16 * 128 + swz);
; #pragma unroll
;         for (int n = 0; n < NTW; ++n) bfr[n] = *reinterpret_cast<const bf16x8*>(bbase + so + n * 16 * 128 + swz);
;         if (ks == 1) {
; #pragma unroll
;           for (int i = 0; i < 4; ++i) glds16(Ap + i * sa + k1, dbase + sn + i * 4096);
; #pragma unroll
;           for (int i = 0; i < NBL; ++i) glds16(Bp + i * sb + k1, dbase + sn + ASZ + i * 4096);
;         }
;         __builtin_amdgcn_s_setprio(1);
; #pragma unroll
;         for (int m = 0; m < 4; ++m)
; #pragma unroll
;           for (int n = 0; n < NTW; ++n) acc[m][n] = mfma16(af[m], bfr[n], acc[m][n]);
;         __builtin_amdgcn_s_setprio(0);
;       }
;     }
;     __builtin_amdgcn_s_setprio(0);
;     __syncthreads();
.LBB0_221:
	v_add_u32_e32 v87, v50, v51
	v_add_u32_e32 v91, v49, v51
	ds_read_b128 v[92:95], v87 offset:18432
	ds_read_b128 v[96:99], v87 offset:16384
	ds_read_b128 v[100:103], v91 offset:6144
	ds_read_b128 v[104:107], v91 offset:4096
	ds_read_b128 v[108:111], v91 offset:2048
	ds_read_b128 v[112:115], v91
	v_lshl_add_u64 v[88:89], v[42:43], 0, s[10:11]
	v_lshl_add_u64 v[118:119], v[40:41], 0, s[10:11]
	s_mov_b64 s[22:23], 0x4b0080
	v_lshl_add_u64 v[116:117], v[88:89], 0, s[36:37]
	v_lshl_add_u64 v[120:121], v[118:119], 0, s[22:23]
	s_setprio 1
	s_waitcnt lgkmcnt(0)
	v_mfma_f32_16x16x32_bf16 v[32:35], v[112:115], v[96:99], v[32:35]
	v_mfma_f32_16x16x32_bf16 v[28:31], v[112:115], v[92:95], v[28:31]
	v_mfma_f32_16x16x32_bf16 v[24:27], v[108:111], v[96:99], v[24:27]
	v_mfma_f32_16x16x32_bf16 v[20:23], v[108:111], v[92:95], v[20:23]
	v_mfma_f32_16x16x32_bf16 v[16:19], v[104:107], v[96:99], v[16:19]
	v_mfma_f32_16x16x32_bf16 v[12:15], v[104:107], v[92:95], v[12:15]
	v_mfma_f32_16x16x32_bf16 v[8:11], v[100:103], v[96:99], v[8:11]
	v_mfma_f32_16x16x32_bf16 v[4:7], v[100:103], v[92:95], v[4:7]
	s_setprio 0
	v_add_u32_e32 v124, 0x6000, v44
	v_add_u32_e32 v122, v49, v86
	v_readfirstlane_b32 s18, v124
	v_add_u32_e32 v124, 0x7000, v44
	v_add_u32_e32 v123, v50, v86
	s_mov_b32 m0, s18
	v_readfirstlane_b32 s18, v124
	v_add_u32_e32 v124, 0x8000, v44
	ds_read_b128 v[92:95], v122
	ds_read_b128 v[96:99], v122 offset:2048
	ds_read_b128 v[100:103], v122 offset:4096
	ds_read_b128 v[104:107], v122 offset:6144
	ds_read_b128 v[108:111], v123 offset:16384
	ds_read_b128 v[112:115], v123 offset:18432
	global_load_lds_dwordx4 v[116:117], off
	v_lshl_add_u64 v[116:117], v[88:89], 0, s[0:1]
	s_mov_b32 m0, s18
	v_readfirstlane_b32 s18, v124
	global_load_lds_dwordx4 v[116:117], off
	v_lshl_add_u64 v[116:117], v[88:89], 0, s[88:89]
	s_mov_b32 m0, s18
	v_lshl_add_u64 v[88:89], v[88:89], 0, s[90:91]
	global_load_lds_dwordx4 v[116:117], off
	v_add_u32_e32 v116, 0x9000, v44
	s_mov_b64 s[22:23], 0x4c0080
	v_readfirstlane_b32 s18, v116
	s_mov_b32 m0, s18
	v_add_u32_e32 v116, 0xb000, v44
	global_load_lds_dwordx4 v[88:89], off
	v_add_u32_e32 v88, 0xa000, v44
	s_nop 0
	v_readfirstlane_b32 s18, v88
	s_mov_b32 m0, s18
	v_readfirstlane_b32 s18, v116
	global_load_lds_dwordx4 v[120:121], off
	v_lshl_add_u64 v[88:89], v[118:119], 0, s[22:23]
	s_mov_b32 m0, s18
	s_nop 0
	global_load_lds_dwordx4 v[88:89], off
	s_setprio 2
	s_waitcnt lgkmcnt(0)
	v_mfma_f32_16x16x32_bf16 v[32:35], v[92:95], v[108:111], v[32:35]
	v_mfma_f32_16x16x32_bf16 v[28:31], v[92:95], v[112:115], v[28:31]
	v_mfma_f32_16x16x32_bf16 v[24:27], v[96:99], v[108:111], v[24:27]
	v_mfma_f32_16x16x32_bf16 v[20:23], v[96:99], v[112:115], v[20:23]
	v_mfma_f32_16x16x32_bf16 v[16:19], v[100:103], v[108:111], v[16:19]
	v_mfma_f32_16x16x32_bf16 v[12:15], v[100:103], v[112:115], v[12:15]
	v_mfma_f32_16x16x32_bf16 v[8:11], v[104:107], v[108:111], v[8:11]
	v_mfma_f32_16x16x32_bf16 v[4:7], v[104:107], v[112:115], v[4:7]
	s_setprio 0
	s_setprio 0
	s_waitcnt vmcnt(0)
	s_barrier
	ds_read_b128 v[92:95], v87 offset:43008
	ds_read_b128 v[96:99], v87 offset:40960
	ds_read_b128 v[100:103], v91 offset:30720
	ds_read_b128 v[104:107], v91 offset:28672
	ds_read_b128 v[108:111], v91 offset:26624
	ds_read_b128 v[112:115], v91 offset:24576
	s_min_u32 s18, s17, 0x3c0
	s_lshl_b32 s96, s18, 1
	v_lshl_add_u64 v[88:89], v[36:37], 0, s[96:97]
	v_lshl_add_u64 v[116:117], v[38:39], 0, s[96:97]
	s_setprio 1
	s_waitcnt lgkmcnt(0)
	v_mfma_f32_16x16x32_bf16 v[32:35], v[112:115], v[96:99], v[32:35]
	v_mfma_f32_16x16x32_bf16 v[28:31], v[112:115], v[92:95], v[28:31]
	v_mfma_f32_16x16x32_bf16 v[24:27], v[108:111], v[96:99], v[24:27]
	v_mfma_f32_16x16x32_bf16 v[20:23], v[108:111], v[92:95], v[20:23]
	v_mfma_f32_16x16x32_bf16 v[16:19], v[104:107], v[96:99], v[16:19]
	v_mfma_f32_16x16x32_bf16 v[12:15], v[104:107], v[92:95], v[12:15]
	v_mfma_f32_16x16x32_bf16 v[8:11], v[100:103], v[96:99], v[8:11]
	v_mfma_f32_16x16x32_bf16 v[4:7], v[100:103], v[92:95], v[4:7]
	s_setprio 0
	v_readfirstlane_b32 s18, v44
	s_mov_b32 m0, s18
	v_readfirstlane_b32 s18, v45
	ds_read_b128 v[92:95], v122 offset:24576
	ds_read_b128 v[96:99], v122 offset:26624
	ds_read_b128 v[100:103], v122 offset:28672
	ds_read_b128 v[104:107], v122 offset:30720
	ds_read_b128 v[108:111], v123 offset:40960
	ds_read_b128 v[112:115], v123 offset:43008
	global_load_lds_dwordx4 v[88:89], off
	v_lshl_add_u64 v[118:119], v[88:89], 0, s[14:15]
	s_mov_b32 m0, s18
	v_readfirstlane_b32 s18, v46
	global_load_lds_dwordx4 v[118:119], off
	v_lshl_add_u64 v[118:119], v[88:89], 0, s[4:5]
	s_mov_b32 m0, s18
	v_readfirstlane_b32 s18, v47
	global_load_lds_dwordx4 v[118:119], off
	v_lshl_add_u64 v[88:89], v[88:89], 0, s[94:95]
	s_mov_b32 m0, s18
	v_readfirstlane_b32 s18, v2
	global_load_lds_dwordx4 v[88:89], off
	s_mov_b32 m0, s18
	v_readfirstlane_b32 s18, v48
	global_load_lds_dwordx4 v[116:117], off
	v_lshl_add_u64 v[88:89], v[116:117], 0, s[14:15]
	s_mov_b32 m0, s18
	s_nop 0
	global_load_lds_dwordx4 v[88:89], off
	s_setprio 1
	s_waitcnt lgkmcnt(0)
	v_mfma_f32_16x16x32_bf16 v[32:35], v[92:95], v[108:111], v[32:35]
	v_mfma_f32_16x16x32_bf16 v[28:31], v[92:95], v[112:115], v[28:31]
	v_mfma_f32_16x16x32_bf16 v[24:27], v[96:99], v[108:111], v[24:27]
	v_mfma_f32_16x16x32_bf16 v[20:23], v[96:99], v[112:115], v[20:23]
	v_mfma_f32_16x16x32_bf16 v[16:19], v[100:103], v[108:111], v[16:19]
	v_mfma_f32_16x16x32_bf16 v[12:15], v[100:103], v[112:115], v[12:15]
	v_mfma_f32_16x16x32_bf16 v[8:11], v[104:107], v[108:111], v[8:11]
	v_mfma_f32_16x16x32_bf16 v[4:7], v[104:107], v[112:115], v[4:7]
	s_setprio 0
	s_setprio 0
	s_add_u32 s10, s10, 0x100
	s_addc_u32 s11, s11, 0
	s_addk_i32 s17, 0x80
	s_cmpk_lg_i32 s10, 0x800
	s_waitcnt vmcnt(0)
	s_barrier
; DEVI unsigned pack2(float a, float b) { f32x2_t v = {a, b}; bf16x2_t r = __builtin_convertvector(v, bf16x2_t); return *reinterpret_cast<unsigned*>(&r); }
; DEVI float sigm(float x) { return 1.f / (1.f + __expf(-x)); }
; template <int NTW>
; DEVI void merge_tile(const P& p, long row0, int n0, char* smem) {
;     ...
; #pragma unroll
;       for (int m = 0; m < 4; ++m)
; #pragma unroll
;         for (int n = 0; n < NTW; ++n) {
;           pg[m][n][0] = pack2(sigm(accT[m][n][0]), sigm(accT[m][n][1]));
;           pg[m][n][1] = pack2(sigm(accT[m][n][2]), sigm(accT[m][n][3]));
;         }
	s_cbranch_scc1 .LBB0_221
	v_mul_f32_e32 v2, 0xbfb8aa3b, v32
	v_exp_f32_e32 v32, v2
	v_mul_f32_e32 v2, 0xbfb8aa3b, v33
	v_exp_f32_e32 v33, v2
	v_readlane_b32 s48, v252, 27
	v_readlane_b32 s54, v252, 33
	v_readlane_b32 s55, v252, 34
	v_pk_add_f32 v[32:33], v[32:33], 1.0 op_sel_hi:[1,0]
	v_readlane_b32 s49, v252, 28
	v_div_scale_f32 v2, s[10:11], v33, v33, 1.0
	v_rcp_f32_e32 v36, v2
	v_readlane_b32 s50, v252, 29
	v_readlane_b32 s51, v252, 30
	v_readlane_b32 s52, v252, 31
	v_fma_f32 v37, -v2, v36, 1.0
	v_fmac_f32_e32 v36, v37, v36
	v_div_scale_f32 v37, vcc, 1.0, v33, 1.0
	v_mul_f32_e32 v38, v37, v36
	v_fma_f32 v39, -v2, v38, v37
	v_fmac_f32_e32 v38, v39, v36
	v_fma_f32 v2, -v2, v38, v37
	v_div_fmas_f32 v2, v2, v36, v38
	v_div_fixup_f32 v2, v2, v33, 1.0
	v_div_scale_f32 v33, s[10:11], v32, v32, 1.0
	v_rcp_f32_e32 v36, v33
	v_readlane_b32 s53, v252, 32
	v_readlane_b32 s56, v252, 35
	v_readlane_b32 s57, v252, 36
	v_fma_f32 v37, -v33, v36, 1.0
	v_fmac_f32_e32 v36, v37, v36
	v_div_scale_f32 v37, vcc, 1.0, v32, 1.0
	v_mul_f32_e32 v38, v37, v36
	v_fma_f32 v39, -v33, v38, v37
	v_fmac_f32_e32 v38, v39, v36
	v_fma_f32 v33, -v33, v38, v37
	v_div_fmas_f32 v33, v33, v36, v38
	v_div_fixup_f32 v32, v33, v32, 1.0
	v_cvt_pk_bf16_f32 v91, v32, v2
	v_mul_f32_e32 v2, 0xbfb8aa3b, v34
	v_exp_f32_e32 v32, v2
	v_mul_f32_e32 v2, 0xbfb8aa3b, v35
	v_exp_f32_e32 v33, v2
	v_readlane_b32 s58, v252, 37
	v_readlane_b32 s59, v252, 38
	v_readlane_b32 s60, v252, 39
	v_pk_add_f32 v[32:33], v[32:33], 1.0 op_sel_hi:[1,0]
	v_readlane_b32 s61, v252, 40
	v_div_scale_f32 v2, s[10:11], v33, v33, 1.0
	v_rcp_f32_e32 v34, v2
	v_readlane_b32 s62, v252, 41
	v_readlane_b32 s63, v252, 42
	v_fma_f32 v35, -v2, v34, 1.0
	v_fmac_f32_e32 v34, v35, v34
	v_div_scale_f32 v35, vcc, 1.0, v33, 1.0
	v_mul_f32_e32 v36, v35, v34
	v_fma_f32 v37, -v2, v36, v35
	v_fmac_f32_e32 v36, v37, v34
	v_fma_f32 v2, -v2, v36, v35
	v_div_fmas_f32 v2, v2, v34, v36
	v_div_fixup_f32 v2, v2, v33, 1.0
	v_div_scale_f32 v33, s[10:11], v32, v32, 1.0
	v_rcp_f32_e32 v34, v33
	s_nop 0
	v_fma_f32 v35, -v33, v34, 1.0
	v_fmac_f32_e32 v34, v35, v34
	v_div_scale_f32 v35, vcc, 1.0, v32, 1.0
	v_mul_f32_e32 v36, v35, v34
	v_fma_f32 v37, -v33, v36, v35
	v_fmac_f32_e32 v36, v37, v34
	v_fma_f32 v33, -v33, v36, v35
	v_div_fmas_f32 v33, v33, v34, v36
	v_div_fixup_f32 v32, v33, v32, 1.0
	v_cvt_pk_bf16_f32 v92, v32, v2
	v_mul_f32_e32 v2, 0xbfb8aa3b, v28
	v_exp_f32_e32 v28, v2
	v_mul_f32_e32 v2, 0xbfb8aa3b, v29
	v_exp_f32_e32 v29, v2
	s_nop 0
	v_pk_add_f32 v[28:29], v[28:29], 1.0 op_sel_hi:[1,0]
	s_nop 0
	v_div_scale_f32 v2, s[10:11], v29, v29, 1.0
	v_rcp_f32_e32 v32, v2
	s_nop 0
	v_fma_f32 v33, -v2, v32, 1.0
	v_fmac_f32_e32 v32, v33, v32
	v_div_scale_f32 v33, vcc, 1.0, v29, 1.0
	v_mul_f32_e32 v34, v33, v32
	v_fma_f32 v35, -v2, v34, v33
	v_fmac_f32_e32 v34, v35, v32
	v_fma_f32 v2, -v2, v34, v33
	v_div_fmas_f32 v2, v2, v32, v34
	v_div_fixup_f32 v2, v2, v29, 1.0
	v_div_scale_f32 v29, s[10:11], v28, v28, 1.0
	v_rcp_f32_e32 v32, v29
	s_nop 0
	v_fma_f32 v33, -v29, v32, 1.0
	v_fmac_f32_e32 v32, v33, v32
	v_div_scale_f32 v33, vcc, 1.0, v28, 1.0
	v_mul_f32_e32 v34, v33, v32
	v_fma_f32 v35, -v29, v34, v33
	v_fmac_f32_e32 v34, v35, v32
	v_fma_f32 v29, -v29, v34, v33
	v_div_fmas_f32 v29, v29, v32, v34
	v_div_fixup_f32 v28, v29, v28, 1.0
	v_cvt_pk_bf16_f32 v93, v28, v2
	v_mul_f32_e32 v2, 0xbfb8aa3b, v30
	v_exp_f32_e32 v28, v2
	v_mul_f32_e32 v2, 0xbfb8aa3b, v31
	v_exp_f32_e32 v29, v2
	s_nop 0
	v_pk_add_f32 v[28:29], v[28:29], 1.0 op_sel_hi:[1,0]
	s_nop 0
	v_div_scale_f32 v2, s[10:11], v29, v29, 1.0
	v_rcp_f32_e32 v30, v2
	s_nop 0
	v_fma_f32 v31, -v2, v30, 1.0
	v_fmac_f32_e32 v30, v31, v30
	v_div_scale_f32 v31, vcc, 1.0, v29, 1.0
	v_mul_f32_e32 v32, v31, v30
	v_fma_f32 v33, -v2, v32, v31
	v_fmac_f32_e32 v32, v33, v30
	v_fma_f32 v2, -v2, v32, v31
	v_div_fmas_f32 v2, v2, v30, v32
	v_div_fixup_f32 v2, v2, v29, 1.0
	v_div_scale_f32 v29, s[10:11], v28, v28, 1.0
	v_rcp_f32_e32 v30, v29
	s_nop 0
	v_fma_f32 v31, -v29, v30, 1.0
	v_fmac_f32_e32 v30, v31, v30
	v_div_scale_f32 v31, vcc, 1.0, v28, 1.0
	v_mul_f32_e32 v32, v31, v30
	v_fma_f32 v33, -v29, v32, v31
	v_fmac_f32_e32 v32, v33, v30
	v_fma_f32 v29, -v29, v32, v31
	v_div_fmas_f32 v29, v29, v30, v32
	v_div_fixup_f32 v28, v29, v28, 1.0
	v_cvt_pk_bf16_f32 v94, v28, v2
	v_mul_f32_e32 v2, 0xbfb8aa3b, v24
	v_exp_f32_e32 v24, v2
	v_mul_f32_e32 v2, 0xbfb8aa3b, v25
	v_exp_f32_e32 v25, v2
	s_nop 0
	v_pk_add_f32 v[24:25], v[24:25], 1.0 op_sel_hi:[1,0]
	s_nop 0
	v_div_scale_f32 v2, s[10:11], v25, v25, 1.0
	v_rcp_f32_e32 v28, v2
	s_nop 0
	v_fma_f32 v29, -v2, v28, 1.0
	v_fmac_f32_e32 v28, v29, v28
	v_div_scale_f32 v29, vcc, 1.0, v25, 1.0
	v_mul_f32_e32 v30, v29, v28
	v_fma_f32 v31, -v2, v30, v29
	v_fmac_f32_e32 v30, v31, v28
	v_fma_f32 v2, -v2, v30, v29
	v_div_fmas_f32 v2, v2, v28, v30
	v_div_fixup_f32 v2, v2, v25, 1.0
	v_div_scale_f32 v25, s[10:11], v24, v24, 1.0
	v_rcp_f32_e32 v28, v25
	s_nop 0
	v_fma_f32 v29, -v25, v28, 1.0
	v_fmac_f32_e32 v28, v29, v28
	v_div_scale_f32 v29, vcc, 1.0, v24, 1.0
	v_mul_f32_e32 v30, v29, v28
	v_fma_f32 v31, -v25, v30, v29
	v_fmac_f32_e32 v30, v31, v28
	v_fma_f32 v25, -v25, v30, v29
	v_div_fmas_f32 v25, v25, v28, v30
	v_div_fixup_f32 v24, v25, v24, 1.0
	v_cvt_pk_bf16_f32 v95, v24, v2
	v_mul_f32_e32 v2, 0xbfb8aa3b, v26
	v_exp_f32_e32 v24, v2
	v_mul_f32_e32 v2, 0xbfb8aa3b, v27
	v_exp_f32_e32 v25, v2
	s_nop 0
	v_pk_add_f32 v[24:25], v[24:25], 1.0 op_sel_hi:[1,0]
	s_nop 0
	v_div_scale_f32 v2, s[10:11], v25, v25, 1.0
	v_rcp_f32_e32 v26, v2
	s_nop 0
	v_fma_f32 v27, -v2, v26, 1.0
	v_fmac_f32_e32 v26, v27, v26
	v_div_scale_f32 v27, vcc, 1.0, v25, 1.0
	v_mul_f32_e32 v28, v27, v26
	v_fma_f32 v29, -v2, v28, v27
; DEVI unsigned pack2(float a, float b) { f32x2_t v = {a, b}; bf16x2_t r = __builtin_convertvector(v, bf16x2_t); return *reinterpret_cast<unsigned*>(&r); }
; DEVI float sigm(float x) { return 1.f / (1.f + __expf(-x)); }
; template <int NTW>
; DEVI void merge_tile(const P& p, long row0, int n0, char* smem) {
;     ...
; #pragma unroll
;       for (int m = 0; m < 4; ++m)
; #pragma unroll
;         for (int n = 0; n < NTW; ++n) {
;           pg[m][n][0] = pack2(sigm(accT[m][n][0]), sigm(accT[m][n][1]));
;           pg[m][n][1] = pack2(sigm(accT[m][n][2]), sigm(accT[m][n][3]));
;         }
	v_fmac_f32_e32 v28, v29, v26
	v_fma_f32 v2, -v2, v28, v27
	v_div_fmas_f32 v2, v2, v26, v28
	v_div_fixup_f32 v2, v2, v25, 1.0
	v_div_scale_f32 v25, s[10:11], v24, v24, 1.0
	v_rcp_f32_e32 v26, v25
	s_nop 0
	v_fma_f32 v27, -v25, v26, 1.0
	v_fmac_f32_e32 v26, v27, v26
	v_div_scale_f32 v27, vcc, 1.0, v24, 1.0
	v_mul_f32_e32 v28, v27, v26
	v_fma_f32 v29, -v25, v28, v27
	v_fmac_f32_e32 v28, v29, v26
	v_fma_f32 v25, -v25, v28, v27
	v_div_fmas_f32 v25, v25, v26, v28
	v_div_fixup_f32 v24, v25, v24, 1.0
	v_cvt_pk_bf16_f32 v96, v24, v2
	v_mul_f32_e32 v2, 0xbfb8aa3b, v20
	v_exp_f32_e32 v20, v2
	v_mul_f32_e32 v2, 0xbfb8aa3b, v21
	v_exp_f32_e32 v21, v2
	s_nop 0
	v_pk_add_f32 v[20:21], v[20:21], 1.0 op_sel_hi:[1,0]
	s_nop 0
	v_div_scale_f32 v2, s[10:11], v21, v21, 1.0
	v_rcp_f32_e32 v24, v2
	s_nop 0
	v_fma_f32 v25, -v2, v24, 1.0
	v_fmac_f32_e32 v24, v25, v24
	v_div_scale_f32 v25, vcc, 1.0, v21, 1.0
	v_mul_f32_e32 v26, v25, v24
	v_fma_f32 v27, -v2, v26, v25
	v_fmac_f32_e32 v26, v27, v24
	v_fma_f32 v2, -v2, v26, v25
	v_div_fmas_f32 v2, v2, v24, v26
	v_div_fixup_f32 v2, v2, v21, 1.0
	v_div_scale_f32 v21, s[10:11], v20, v20, 1.0
	v_rcp_f32_e32 v24, v21
	s_nop 0
	v_fma_f32 v25, -v21, v24, 1.0
	v_fmac_f32_e32 v24, v25, v24
	v_div_scale_f32 v25, vcc, 1.0, v20, 1.0
	v_mul_f32_e32 v26, v25, v24
	v_fma_f32 v27, -v21, v26, v25
	v_fmac_f32_e32 v26, v27, v24
	v_fma_f32 v21, -v21, v26, v25
	v_div_fmas_f32 v21, v21, v24, v26
	v_div_fixup_f32 v20, v21, v20, 1.0
	v_cvt_pk_bf16_f32 v97, v20, v2
	v_mul_f32_e32 v2, 0xbfb8aa3b, v22
	v_exp_f32_e32 v20, v2
	v_mul_f32_e32 v2, 0xbfb8aa3b, v23
	v_exp_f32_e32 v21, v2
	s_nop 0
	v_pk_add_f32 v[20:21], v[20:21], 1.0 op_sel_hi:[1,0]
	s_nop 0
	v_div_scale_f32 v2, s[10:11], v21, v21, 1.0
	v_rcp_f32_e32 v22, v2
	s_nop 0
	v_fma_f32 v23, -v2, v22, 1.0
	v_fmac_f32_e32 v22, v23, v22
	v_div_scale_f32 v23, vcc, 1.0, v21, 1.0
	v_mul_f32_e32 v24, v23, v22
	v_fma_f32 v25, -v2, v24, v23
	v_fmac_f32_e32 v24, v25, v22
	v_fma_f32 v2, -v2, v24, v23
	v_div_fmas_f32 v2, v2, v22, v24
	v_div_fixup_f32 v2, v2, v21, 1.0
	v_div_scale_f32 v21, s[10:11], v20, v20, 1.0
	v_rcp_f32_e32 v22, v21
	s_nop 0
	v_fma_f32 v23, -v21, v22, 1.0
	v_fmac_f32_e32 v22, v23, v22
	v_div_scale_f32 v23, vcc, 1.0, v20, 1.0
	v_mul_f32_e32 v24, v23, v22
	v_fma_f32 v25, -v21, v24, v23
	v_fmac_f32_e32 v24, v25, v22
	v_fma_f32 v21, -v21, v24, v23
	v_div_fmas_f32 v21, v21, v22, v24
	v_div_fixup_f32 v20, v21, v20, 1.0
	v_cvt_pk_bf16_f32 v98, v20, v2
	v_mul_f32_e32 v2, 0xbfb8aa3b, v16
	v_exp_f32_e32 v16, v2
	v_mul_f32_e32 v2, 0xbfb8aa3b, v17
	v_exp_f32_e32 v17, v2
	s_nop 0
	v_pk_add_f32 v[16:17], v[16:17], 1.0 op_sel_hi:[1,0]
	s_nop 0
	v_div_scale_f32 v2, s[10:11], v17, v17, 1.0
	v_rcp_f32_e32 v20, v2
	s_nop 0
	v_fma_f32 v21, -v2, v20, 1.0
	v_fmac_f32_e32 v20, v21, v20
	v_div_scale_f32 v21, vcc, 1.0, v17, 1.0
	v_mul_f32_e32 v22, v21, v20
	v_fma_f32 v23, -v2, v22, v21
	v_fmac_f32_e32 v22, v23, v20
	v_fma_f32 v2, -v2, v22, v21
	v_div_fmas_f32 v2, v2, v20, v22
	v_div_fixup_f32 v2, v2, v17, 1.0
	v_div_scale_f32 v17, s[10:11], v16, v16, 1.0
	v_rcp_f32_e32 v20, v17
	s_nop 0
	v_fma_f32 v21, -v17, v20, 1.0
	v_fmac_f32_e32 v20, v21, v20
	v_div_scale_f32 v21, vcc, 1.0, v16, 1.0
	v_mul_f32_e32 v22, v21, v20
	v_fma_f32 v23, -v17, v22, v21
	v_fmac_f32_e32 v22, v23, v20
	v_fma_f32 v17, -v17, v22, v21
	v_div_fmas_f32 v17, v17, v20, v22
	v_div_fixup_f32 v16, v17, v16, 1.0
	v_cvt_pk_bf16_f32 v99, v16, v2
	v_mul_f32_e32 v2, 0xbfb8aa3b, v18
	v_exp_f32_e32 v16, v2
	v_mul_f32_e32 v2, 0xbfb8aa3b, v19
	v_exp_f32_e32 v17, v2
	s_nop 0
	v_pk_add_f32 v[16:17], v[16:17], 1.0 op_sel_hi:[1,0]
	s_nop 0
	v_div_scale_f32 v2, s[10:11], v17, v17, 1.0
	v_rcp_f32_e32 v18, v2
	s_nop 0
	v_fma_f32 v19, -v2, v18, 1.0
	v_fmac_f32_e32 v18, v19, v18
	v_div_scale_f32 v19, vcc, 1.0, v17, 1.0
	v_mul_f32_e32 v20, v19, v18
	v_fma_f32 v21, -v2, v20, v19
	v_fmac_f32_e32 v20, v21, v18
	v_fma_f32 v2, -v2, v20, v19
	v_div_fmas_f32 v2, v2, v18, v20
	v_div_fixup_f32 v2, v2, v17, 1.0
	v_div_scale_f32 v17, s[10:11], v16, v16, 1.0
	v_rcp_f32_e32 v18, v17
	s_nop 0
	v_fma_f32 v19, -v17, v18, 1.0
	v_fmac_f32_e32 v18, v19, v18
	v_div_scale_f32 v19, vcc, 1.0, v16, 1.0
	v_mul_f32_e32 v20, v19, v18
	v_fma_f32 v21, -v17, v20, v19
	v_fmac_f32_e32 v20, v21, v18
	v_fma_f32 v17, -v17, v20, v19
	v_div_fmas_f32 v17, v17, v18, v20
	v_div_fixup_f32 v16, v17, v16, 1.0
	v_cvt_pk_bf16_f32 v100, v16, v2
	v_mul_f32_e32 v2, 0xbfb8aa3b, v12
	v_exp_f32_e32 v12, v2
	v_mul_f32_e32 v2, 0xbfb8aa3b, v13
	v_exp_f32_e32 v13, v2
	s_nop 0
	v_pk_add_f32 v[12:13], v[12:13], 1.0 op_sel_hi:[1,0]
	s_nop 0
	v_div_scale_f32 v2, s[10:11], v13, v13, 1.0
	v_rcp_f32_e32 v16, v2
	s_nop 0
	v_fma_f32 v17, -v2, v16, 1.0
	v_fmac_f32_e32 v16, v17, v16
	v_div_scale_f32 v17, vcc, 1.0, v13, 1.0
	v_mul_f32_e32 v18, v17, v16
	v_fma_f32 v19, -v2, v18, v17
	v_fmac_f32_e32 v18, v19, v16
	v_fma_f32 v2, -v2, v18, v17
	v_div_fmas_f32 v2, v2, v16, v18
	v_div_fixup_f32 v2, v2, v13, 1.0
	v_div_scale_f32 v13, s[10:11], v12, v12, 1.0
	v_rcp_f32_e32 v16, v13
	s_nop 0
	v_fma_f32 v17, -v13, v16, 1.0
	v_fmac_f32_e32 v16, v17, v16
	v_div_scale_f32 v17, vcc, 1.0, v12, 1.0
	v_mul_f32_e32 v18, v17, v16
	v_fma_f32 v19, -v13, v18, v17
	v_fmac_f32_e32 v18, v19, v16
	v_fma_f32 v13, -v13, v18, v17
	v_div_fmas_f32 v13, v13, v16, v18
	v_div_fixup_f32 v12, v13, v12, 1.0
	v_cvt_pk_bf16_f32 v101, v12, v2
	v_mul_f32_e32 v2, 0xbfb8aa3b, v14
	v_exp_f32_e32 v12, v2
	v_mul_f32_e32 v2, 0xbfb8aa3b, v15
	v_exp_f32_e32 v13, v2
	s_nop 0
	v_pk_add_f32 v[12:13], v[12:13], 1.0 op_sel_hi:[1,0]
	s_nop 0
	v_div_scale_f32 v2, s[10:11], v13, v13, 1.0
	v_rcp_f32_e32 v14, v2
	s_nop 0
	v_fma_f32 v15, -v2, v14, 1.0
	v_fmac_f32_e32 v14, v15, v14
; DEVI unsigned pack2(float a, float b) { f32x2_t v = {a, b}; bf16x2_t r = __builtin_convertvector(v, bf16x2_t); return *reinterpret_cast<unsigned*>(&r); }
; DEVI float sigm(float x) { return 1.f / (1.f + __expf(-x)); }
; DEVI int get_tid() { int t = threadIdx.x; asm volatile("" : "+v"(t)); return t; }
; template <int NTW, bool SPLIT = false, bool HALFA = false>
; DEVI void gemm_core2(f32x4 (&acc)[4][NTW], const bf* __restrict__ A, int lda, const bf* __restrict__ Bt, int ldb, int K, char* smem) {
;     ...
;   const int tid = get_tid(), lane = tid & 63, w = tid >> 6, wr = w >> 1, wc = w & 1, l15 = lane & 15, quad = lane >> 4;
;   const int lr = tid >> 3, pch = tid & 7;
;   const int lch = pch ^ (lr & 7);
;   const int nk = K >> 6;
;   const bf* Ap = A + (long)lr * lda + lch * 8;
;   const bf* Bp = Bt + (long)lr * ldb + lch * 8;
;   const long sa = (long)32 * lda, sb = (long)32 * ldb;
;   char* dbase = smem + tid * 16;
;   const int sw0 = ((quad ^ (l15 & 7)) << 4), sw1 = (((4 + quad) ^ (l15 & 7)) << 4);
;   const char* abase = smem + (wr * 64 + l15) * 128;
;   const char* bbase = smem + ASZ + (wc * 16 * NTW + l15) * 128;
; #pragma unroll
;   for (int i = 0; i < 4; ++i) glds16(Ap + i * sa, dbase + i * 4096);
; #pragma unroll
;   for (int i = 0; i < NBL; ++i) glds16(Bp + i * sb, dbase + ASZ + i * 4096);
;   __syncthreads();
; template <int NTW>
; DEVI void merge_tile(const P& p, long row0, int n0, char* smem) {
;     ...
;           pg[m][n][0] = pack2(sigm(accT[m][n][0]), sigm(accT[m][n][1]));
;           pg[m][n][1] = pack2(sigm(accT[m][n][2]), sigm(accT[m][n][3]));
	v_div_scale_f32 v15, vcc, 1.0, v13, 1.0
	v_mul_f32_e32 v16, v15, v14
	v_fma_f32 v17, -v2, v16, v15
	v_fmac_f32_e32 v16, v17, v14
	v_fma_f32 v2, -v2, v16, v15
	v_div_fmas_f32 v2, v2, v14, v16
	v_div_fixup_f32 v2, v2, v13, 1.0
	v_div_scale_f32 v13, s[10:11], v12, v12, 1.0
	v_rcp_f32_e32 v14, v13
	s_nop 0
	v_fma_f32 v15, -v13, v14, 1.0
	v_fmac_f32_e32 v14, v15, v14
	v_div_scale_f32 v15, vcc, 1.0, v12, 1.0
	v_mul_f32_e32 v16, v15, v14
	v_fma_f32 v17, -v13, v16, v15
	v_fmac_f32_e32 v16, v17, v14
	v_fma_f32 v13, -v13, v16, v15
	v_div_fmas_f32 v13, v13, v14, v16
	v_div_fixup_f32 v12, v13, v12, 1.0
	v_cvt_pk_bf16_f32 v102, v12, v2
	v_mul_f32_e32 v2, 0xbfb8aa3b, v8
	v_exp_f32_e32 v8, v2
	v_mul_f32_e32 v2, 0xbfb8aa3b, v9
	v_exp_f32_e32 v9, v2
	s_nop 0
	v_pk_add_f32 v[8:9], v[8:9], 1.0 op_sel_hi:[1,0]
	s_nop 0
	v_div_scale_f32 v2, s[10:11], v9, v9, 1.0
	v_rcp_f32_e32 v12, v2
	s_nop 0
	v_fma_f32 v13, -v2, v12, 1.0
	v_fmac_f32_e32 v12, v13, v12
	v_div_scale_f32 v13, vcc, 1.0, v9, 1.0
	v_mul_f32_e32 v14, v13, v12
	v_fma_f32 v15, -v2, v14, v13
	v_fmac_f32_e32 v14, v15, v12
	v_fma_f32 v2, -v2, v14, v13
	v_div_fmas_f32 v2, v2, v12, v14
	v_div_fixup_f32 v2, v2, v9, 1.0
	v_div_scale_f32 v9, s[10:11], v8, v8, 1.0
	v_rcp_f32_e32 v12, v9
	s_nop 0
	v_fma_f32 v13, -v9, v12, 1.0
	v_fmac_f32_e32 v12, v13, v12
	v_div_scale_f32 v13, vcc, 1.0, v8, 1.0
	v_mul_f32_e32 v14, v13, v12
	v_fma_f32 v15, -v9, v14, v13
	v_fmac_f32_e32 v14, v15, v12
	v_fma_f32 v9, -v9, v14, v13
	v_div_fmas_f32 v9, v9, v12, v14
	v_div_fixup_f32 v8, v9, v8, 1.0
	v_cvt_pk_bf16_f32 v103, v8, v2
	v_mul_f32_e32 v2, 0xbfb8aa3b, v10
	v_exp_f32_e32 v8, v2
	v_mul_f32_e32 v2, 0xbfb8aa3b, v11
	v_exp_f32_e32 v9, v2
	s_nop 0
	v_pk_add_f32 v[8:9], v[8:9], 1.0 op_sel_hi:[1,0]
	s_nop 0
	v_div_scale_f32 v2, s[10:11], v9, v9, 1.0
	v_rcp_f32_e32 v10, v2
	s_nop 0
	v_fma_f32 v11, -v2, v10, 1.0
	v_fmac_f32_e32 v10, v11, v10
	v_div_scale_f32 v11, vcc, 1.0, v9, 1.0
	v_mul_f32_e32 v12, v11, v10
	v_fma_f32 v13, -v2, v12, v11
	v_fmac_f32_e32 v12, v13, v10
	v_fma_f32 v2, -v2, v12, v11
	v_div_fmas_f32 v2, v2, v10, v12
	v_div_fixup_f32 v2, v2, v9, 1.0
	v_div_scale_f32 v9, s[10:11], v8, v8, 1.0
	v_rcp_f32_e32 v10, v9
	s_nop 0
	v_fma_f32 v11, -v9, v10, 1.0
	v_fmac_f32_e32 v10, v11, v10
	v_div_scale_f32 v11, vcc, 1.0, v8, 1.0
	v_mul_f32_e32 v12, v11, v10
	v_fma_f32 v13, -v9, v12, v11
	v_fmac_f32_e32 v12, v13, v10
	v_fma_f32 v9, -v9, v12, v11
	v_div_fmas_f32 v9, v9, v10, v12
	v_div_fixup_f32 v8, v9, v8, 1.0
	v_cvt_pk_bf16_f32 v104, v8, v2
	v_mul_f32_e32 v2, 0xbfb8aa3b, v4
	v_exp_f32_e32 v4, v2
	v_mul_f32_e32 v2, 0xbfb8aa3b, v5
	v_exp_f32_e32 v5, v2
	s_nop 0
	v_pk_add_f32 v[4:5], v[4:5], 1.0 op_sel_hi:[1,0]
	s_nop 0
	v_div_scale_f32 v2, s[10:11], v5, v5, 1.0
	v_rcp_f32_e32 v8, v2
	s_nop 0
	v_fma_f32 v9, -v2, v8, 1.0
	v_fmac_f32_e32 v8, v9, v8
	v_div_scale_f32 v9, vcc, 1.0, v5, 1.0
	v_mul_f32_e32 v10, v9, v8
	v_fma_f32 v11, -v2, v10, v9
	v_fmac_f32_e32 v10, v11, v8
	v_fma_f32 v2, -v2, v10, v9
	v_div_fmas_f32 v2, v2, v8, v10
	v_div_fixup_f32 v2, v2, v5, 1.0
	v_div_scale_f32 v5, s[10:11], v4, v4, 1.0
	v_rcp_f32_e32 v8, v5
	s_nop 0
	v_fma_f32 v9, -v5, v8, 1.0
	v_fmac_f32_e32 v8, v9, v8
	v_div_scale_f32 v9, vcc, 1.0, v4, 1.0
	v_mul_f32_e32 v10, v9, v8
	v_fma_f32 v11, -v5, v10, v9
	v_fmac_f32_e32 v10, v11, v8
	v_fma_f32 v5, -v5, v10, v9
	v_div_fmas_f32 v5, v5, v8, v10
	v_div_fixup_f32 v4, v5, v4, 1.0
	v_cvt_pk_bf16_f32 v105, v4, v2
	v_mul_f32_e32 v2, 0xbfb8aa3b, v6
	v_exp_f32_e32 v4, v2
	v_mul_f32_e32 v2, 0xbfb8aa3b, v7
	v_exp_f32_e32 v5, v2
	s_nop 0
	v_pk_add_f32 v[4:5], v[4:5], 1.0 op_sel_hi:[1,0]
	s_nop 0
	v_div_scale_f32 v2, s[10:11], v5, v5, 1.0
	v_rcp_f32_e32 v6, v2
	s_nop 0
	v_fma_f32 v7, -v2, v6, 1.0
	v_fmac_f32_e32 v6, v7, v6
	v_div_scale_f32 v7, vcc, 1.0, v5, 1.0
	v_mul_f32_e32 v8, v7, v6
	v_fma_f32 v9, -v2, v8, v7
	v_fmac_f32_e32 v8, v9, v6
	v_fma_f32 v2, -v2, v8, v7
	v_div_fmas_f32 v2, v2, v6, v8
	v_div_fixup_f32 v2, v2, v5, 1.0
	v_div_scale_f32 v5, s[10:11], v4, v4, 1.0
	v_rcp_f32_e32 v6, v5
	s_lshl_b32 s10, s21, 9
	s_add_u32 s10, s13, s10
	s_addc_u32 s11, s20, 0
	v_fma_f32 v7, -v5, v6, 1.0
	v_fmac_f32_e32 v6, v7, v6
	v_div_scale_f32 v7, vcc, 1.0, v4, 1.0
	v_mul_f32_e32 v8, v7, v6
	v_fma_f32 v9, -v5, v8, v7
	v_fmac_f32_e32 v8, v9, v6
	v_fma_f32 v5, -v5, v8, v7
	v_div_fmas_f32 v5, v5, v6, v8
	v_div_fixup_f32 v4, v5, v4, 1.0
	v_mov_b32_e32 v8, v178
	v_cvt_pk_bf16_f32 v106, v4, v2
	s_add_u32 s22, s24, s40
	s_addc_u32 s23, 0, s41
	v_ashrrev_i32_e32 v4, 3, v8
	v_xor_b32_e32 v2, v4, v8
	v_ashrrev_i32_e32 v5, 31, v4
	s_lshl_b64 s[22:23], s[22:23], 9
	v_lshlrev_b64 v[6:7], 11, v[4:5]
	v_lshlrev_b32_e32 v2, 4, v2
	s_add_u32 s22, s54, s22
	v_lshl_add_u64 v[6:7], s[10:11], 0, v[6:7]
	v_and_b32_e32 v2, 0x70, v2
	s_addc_u32 s23, s55, s23
	v_and_b32_e32 v9, 15, v8
	v_lshl_add_u64 v[86:87], v[6:7], 0, v[2:3]
	v_lshlrev_b64 v[4:5], 9, v[4:5]
	v_lshlrev_b32_e32 v118, 4, v8
	v_lshrrev_b32_e32 v6, 1, v8
	v_lshl_add_u64 v[4:5], s[22:23], 0, v[4:5]
	v_and_or_b32 v7, v6, s19, v9
	v_and_or_b32 v6, v6, 32, v9
	v_readfirstlane_b32 s22, v118
	v_add_u32_e32 v9, 0x1000, v118
	s_mov_b32 m0, s22
	v_readfirstlane_b32 s10, v9
	v_add_u32_e32 v9, 0x2000, v118
	v_lshlrev_b32_e32 v41, 7, v7
	v_lshlrev_b32_e32 v42, 7, v6
	global_load_lds_dwordx4 v[86:87], off
	v_lshl_add_u64 v[6:7], v[86:87], 0, s[14:15]
	s_mov_b32 m0, s10
	v_readfirstlane_b32 s11, v9
	v_add_u32_e32 v9, 0x3000, v118
	v_lshl_add_u64 v[88:89], v[4:5], 0, v[2:3]
	v_add_u32_e32 v2, 0x4000, v118
	v_lshrrev_b32_e32 v10, 4, v8
	v_and_b32_e32 v40, 7, v8
	global_load_lds_dwordx4 v[6:7], off
	v_lshl_add_u64 v[6:7], v[86:87], 0, s[4:5]
	s_mov_b32 m0, s11
	v_readfirstlane_b32 s24, v9
	v_readfirstlane_b32 s25, v2
	v_add_u32_e32 v2, 0x5000, v118
	global_load_lds_dwordx4 v[6:7], off
	v_lshl_add_u64 v[6:7], v[86:87], 0, s[94:95]
	s_mov_b32 m0, s24
	v_readfirstlane_b32 s46, v2
	v_bitop3_b32 v2, v10, v40, 3 bitop3:0x6c
	global_load_lds_dwordx4 v[6:7], off
	s_mov_b32 m0, s25
	v_lshlrev_b32_e32 v2, 4, v2
	global_load_lds_dwordx4 v[88:89], off
	v_lshl_add_u64 v[4:5], v[88:89], 0, s[30:31]
	s_mov_b32 m0, s46
	v_or_b32_e32 v107, v42, v2
	v_or_b32_e32 v2, v41, v2
	global_load_lds_dwordx4 v[4:5], off
	v_bfe_u32 v43, v8, 4, 2
	s_waitcnt vmcnt(0) lgkmcnt(0)
	s_barrier
; DEVI f32x4 mfma16(bf16x8 a, bf16x8 b, f32x4 c) { return __builtin_amdgcn_mfma_f32_16x16x32_bf16(a, b, c, 0, 0, 0); }
; template <int NTW, bool SPLIT = false, bool HALFA = false>
; DEVI void gemm_core2(f32x4 (&acc)[4][NTW], const bf* __restrict__ A, int lda, const bf* __restrict__ Bt, int ldb, int K, char* smem) {
;     ...
;       if (HALFA) {
; #pragma unroll
;         for (int ks = 0; ks < 2; ++ks) {
;           const int swz = ks ? sw1 : sw0;
;           bf16x8 bfr[NTW];
; #pragma unroll
;           for (int n = 0; n < NTW; ++n) bfr[n] = *reinterpret_cast<const bf16x8*>(bbase + so + n * 16 * 128 + swz);
; #pragma unroll
;           for (int mh = 0; mh < 2; ++mh) {
;             bf16x8 af[2];
; #pragma unroll
;             for (int m = 0; m < 2; ++m) af[m] = *reinterpret_cast<const bf16x8*>(abase + so + (mh * 2 + m) * 16 * 128 + swz);
;             if (ks == 1 && mh == 1) {
; #pragma unroll
;               for (int i = 0; i < 4; ++i) glds16(Ap + i * sa + k1, dbase + sn + i * 4096);
; #pragma unroll
;               for (int i = 0; i < NBL; ++i) glds16(Bp + i * sb + k1, dbase + sn + ASZ + i * 4096);
;             }
; #pragma unroll
;             for (int m = 0; m < 2; ++m)
; #pragma unroll
;               for (int n = 0; n < NTW; ++n) acc[mh * 2 + m][n] = mfma16(af[m], bfr[n], acc[mh * 2 + m][n]);
;           }
	ds_read_b128 v[4:7], v107 offset:16384
	ds_read_b128 v[8:11], v107 offset:18432
	ds_read_b128 v[12:15], v2
	ds_read_b128 v[16:19], v2 offset:2048
	s_waitcnt lgkmcnt(0)
	v_mfma_f32_16x16x32_bf16 v[44:47], v[16:19], v[4:7], 0
	v_add_u32_e32 v119, 0x6000, v118
	v_lshl_add_u64 v[114:115], v[86:87], 0, s[36:37]
	v_readfirstlane_b32 s18, v119
	v_mfma_f32_16x16x32_bf16 v[48:51], v[16:19], v[8:11], 0
	ds_read_b128 v[16:19], v2 offset:4096
	ds_read_b128 v[28:31], v2 offset:6144
	s_mov_b32 m0, s18
	v_add_u32_e32 v120, 0xa000, v118
	v_mfma_f32_16x16x32_bf16 v[20:23], v[12:15], v[4:7], 0
	v_readfirstlane_b32 s50, v120
	v_lshl_add_u64 v[116:117], v[88:89], 0, s[36:37]
	v_mfma_f32_16x16x32_bf16 v[12:15], v[12:15], v[8:11], 0
	s_waitcnt lgkmcnt(1)
	v_mfma_f32_16x16x32_bf16 v[36:39], v[16:19], v[4:7], 0
	v_mfma_f32_16x16x32_bf16 v[32:35], v[16:19], v[8:11], 0
	s_waitcnt lgkmcnt(0)
	v_mfma_f32_16x16x32_bf16 v[24:27], v[28:31], v[4:7], 0
	v_mfma_f32_16x16x32_bf16 v[4:7], v[28:31], v[8:11], 0
	v_bitop3_b32 v8, v43, v40, 4 bitop3:0x36
	v_lshlrev_b32_e32 v8, 4, v8
	v_or_b32_e32 v108, v41, v8
	v_or_b32_e32 v109, v42, v8
	ds_read_b128 v[110:113], v108 offset:2048
	ds_read_b128 v[16:19], v108
	ds_read_b128 v[28:31], v109 offset:18432
	ds_read_b128 v[40:43], v109 offset:16384
	s_waitcnt lgkmcnt(0)
	v_mfma_f32_16x16x32_bf16 v[8:11], v[16:19], v[40:43], v[20:23]
	v_mfma_f32_16x16x32_bf16 v[12:15], v[16:19], v[28:31], v[12:15]
	v_mfma_f32_16x16x32_bf16 v[16:19], v[110:113], v[40:43], v[44:47]
	v_mfma_f32_16x16x32_bf16 v[20:23], v[110:113], v[28:31], v[48:51]
	v_add_u32_e32 v112, 0x7000, v118
	s_nop 1
	ds_read_b128 v[48:51], v108 offset:4096
	ds_read_b128 v[44:47], v108 offset:6144
	v_readfirstlane_b32 s47, v112
	v_add_u32_e32 v112, 0x8000, v118
	global_load_lds_dwordx4 v[114:115], off
	v_lshl_add_u64 v[110:111], v[86:87], 0, s[0:1]
	s_mov_b32 m0, s47
	v_readfirstlane_b32 s48, v112
	v_add_u32_e32 v112, 0x9000, v118
	global_load_lds_dwordx4 v[110:111], off
	v_lshl_add_u64 v[110:111], v[86:87], 0, s[88:89]
	s_mov_b32 m0, s48
	v_readfirstlane_b32 s49, v112
	global_load_lds_dwordx4 v[110:111], off
	v_lshl_add_u64 v[110:111], v[86:87], 0, s[90:91]
	s_mov_b32 m0, s49
	v_add_u32_e32 v112, 0xb000, v118
	global_load_lds_dwordx4 v[110:111], off
	s_mov_b32 m0, s50
	v_readfirstlane_b32 s51, v112
	global_load_lds_dwordx4 v[116:117], off
	v_lshl_add_u64 v[110:111], v[88:89], 0, s[64:65]
	s_mov_b32 m0, s51
	s_waitcnt lgkmcnt(0)
	v_mfma_f32_16x16x32_bf16 v[36:39], v[48:51], v[40:43], v[36:39]
	global_load_lds_dwordx4 v[110:111], off
	v_mfma_f32_16x16x32_bf16 v[32:35], v[48:51], v[28:31], v[32:35]
	v_mfma_f32_16x16x32_bf16 v[24:27], v[44:47], v[40:43], v[24:27]
	v_mfma_f32_16x16x32_bf16 v[4:7], v[44:47], v[28:31], v[4:7]
	s_setprio 0
	s_waitcnt vmcnt(0) lgkmcnt(0)
	s_barrier
	ds_read_b128 v[28:31], v107 offset:40960
	ds_read_b128 v[40:43], v107 offset:43008
	ds_read_b128 v[44:47], v2 offset:24576
	ds_read_b128 v[48:51], v2 offset:26624
	s_waitcnt lgkmcnt(1)
	v_mfma_f32_16x16x32_bf16 v[8:11], v[44:47], v[28:31], v[8:11]
	s_mov_b64 s[28:29], 0x100
	v_lshl_add_u64 v[114:115], v[86:87], 0, s[28:29]
	v_lshl_add_u64 v[116:117], v[88:89], 0, s[28:29]
	v_mfma_f32_16x16x32_bf16 v[12:15], v[44:47], v[40:43], v[12:15]
	s_mov_b32 m0, s22
	s_mov_b64 s[28:29], 0x10100
	s_waitcnt lgkmcnt(0)
	v_mfma_f32_16x16x32_bf16 v[16:19], v[48:51], v[28:31], v[16:19]
	v_mfma_f32_16x16x32_bf16 v[44:47], v[48:51], v[40:43], v[20:23]
	s_nop 2
	ds_read_b128 v[20:23], v2 offset:28672
	ds_read_b128 v[48:51], v2 offset:30720
	s_waitcnt lgkmcnt(1)
	v_mfma_f32_16x16x32_bf16 v[36:39], v[20:23], v[28:31], v[36:39]
	v_mfma_f32_16x16x32_bf16 v[32:35], v[20:23], v[40:43], v[32:35]
	s_waitcnt lgkmcnt(0)
	v_mfma_f32_16x16x32_bf16 v[24:27], v[48:51], v[28:31], v[24:27]
	v_mfma_f32_16x16x32_bf16 v[20:23], v[48:51], v[40:43], v[4:7]
	ds_read_b128 v[28:31], v108 offset:26624
	ds_read_b128 v[40:43], v108 offset:24576
	ds_read_b128 v[48:51], v109 offset:43008
	ds_read_b128 v[110:113], v109 offset:40960
	s_waitcnt lgkmcnt(0)
	v_mfma_f32_16x16x32_bf16 v[4:7], v[40:43], v[110:113], v[8:11]
	v_mfma_f32_16x16x32_bf16 v[8:11], v[40:43], v[48:51], v[12:15]
	v_mfma_f32_16x16x32_bf16 v[12:15], v[28:31], v[110:113], v[16:19]
	v_mfma_f32_16x16x32_bf16 v[16:19], v[28:31], v[48:51], v[44:47]
	ds_read_b128 v[28:31], v108 offset:28672
	ds_read_b128 v[40:43], v108 offset:30720
	global_load_lds_dwordx4 v[114:115], off
	v_lshl_add_u64 v[44:45], v[86:87], 0, s[28:29]
	s_mov_b32 m0, s10
	s_mov_b64 s[28:29], 0x20100
	global_load_lds_dwordx4 v[44:45], off
	v_lshl_add_u64 v[44:45], v[86:87], 0, s[28:29]
	s_mov_b32 m0, s11
	s_mov_b64 s[28:29], 0x30100
	global_load_lds_dwordx4 v[44:45], off
	v_lshl_add_u64 v[44:45], v[86:87], 0, s[28:29]
	s_mov_b32 m0, s24
	s_waitcnt lgkmcnt(0)
	v_mfma_f32_16x16x32_bf16 v[24:27], v[40:43], v[110:113], v[24:27]
	global_load_lds_dwordx4 v[44:45], off
	s_mov_b32 m0, s25
	v_lshl_add_u64 v[44:45], v[88:89], 0, s[66:67]
	global_load_lds_dwordx4 v[116:117], off
	s_mov_b32 m0, s46
	v_mfma_f32_16x16x32_bf16 v[114:117], v[28:31], v[110:113], v[36:39]
	global_load_lds_dwordx4 v[44:45], off
	v_mfma_f32_16x16x32_bf16 v[28:31], v[28:31], v[48:51], v[32:35]
	v_mfma_f32_16x16x32_bf16 v[20:23], v[40:43], v[48:51], v[20:23]
	s_setprio 0
	s_mov_b64 s[28:29], 0x180
	v_lshl_add_u64 v[46:47], v[86:87], 0, s[28:29]
	v_lshl_add_u64 v[36:37], v[88:89], 0, s[28:29]
	s_mov_b64 s[28:29], 0x10180
	v_lshl_add_u64 v[40:41], v[86:87], 0, s[28:29]
	s_mov_b64 s[28:29], 0x20180
	v_lshl_add_u64 v[42:43], v[86:87], 0, s[28:29]
	s_mov_b64 s[28:29], 0x30180
	s_waitcnt vmcnt(0) lgkmcnt(0)
	s_barrier
; DEVI f32x4 mfma16(bf16x8 a, bf16x8 b, f32x4 c) { return __builtin_amdgcn_mfma_f32_16x16x32_bf16(a, b, c, 0, 0, 0); }
; template <int NTW, bool SPLIT = false, bool HALFA = false>
; DEVI void gemm_core2(f32x4 (&acc)[4][NTW], const bf* __restrict__ A, int lda, const bf* __restrict__ Bt, int ldb, int K, char* smem) {
;     ...
;       if (HALFA) {
; #pragma unroll
;         for (int ks = 0; ks < 2; ++ks) {
;           const int swz = ks ? sw1 : sw0;
;           bf16x8 bfr[NTW];
; #pragma unroll
;           for (int n = 0; n < NTW; ++n) bfr[n] = *reinterpret_cast<const bf16x8*>(bbase + so + n * 16 * 128 + swz);
; #pragma unroll
;           for (int mh = 0; mh < 2; ++mh) {
;             bf16x8 af[2];
; #pragma unroll
;             for (int m = 0; m < 2; ++m) af[m] = *reinterpret_cast<const bf16x8*>(abase + so + (mh * 2 + m) * 16 * 128 + swz);
;             if (ks == 1 && mh == 1) {
; #pragma unroll
;               for (int i = 0; i < 4; ++i) glds16(Ap + i * sa + k1, dbase + sn + i * 4096);
; #pragma unroll
;               for (int i = 0; i < NBL; ++i) glds16(Bp + i * sb + k1, dbase + sn + ASZ + i * 4096);
;             }
; #pragma unroll
;             for (int m = 0; m < 2; ++m)
; #pragma unroll
;               for (int n = 0; n < NTW; ++n) acc[mh * 2 + m][n] = mfma16(af[m], bfr[n], acc[mh * 2 + m][n]);
;           }
; template <int NTW>
; DEVI void merge_tile(const P& p, long row0, int n0, char* smem) {
;     ...
;     for (int m = 0; m < 4; ++m)
; #pragma unroll
;       for (int n = 0; n < NTW; ++n) {
;         accM[m][n][0] += __uint_as_float(pg[m][n][0] << 16) * accT[m][n][0];
;         accM[m][n][1] += __uint_as_float(pg[m][n][0] & 0xffff0000u) * accT[m][n][1];
;         accM[m][n][2] += __uint_as_float(pg[m][n][1] << 16) * accT[m][n][2];
;         accM[m][n][3] += __uint_as_float(pg[m][n][1] & 0xffff0000u) * accT[m][n][3];
;       }
	v_lshl_add_u64 v[44:45], v[86:87], 0, s[28:29]
	v_lshl_add_u64 v[38:39], v[88:89], 0, s[68:69]
	ds_read_b128 v[32:35], v107 offset:16384
	ds_read_b128 v[48:51], v107 offset:18432
	ds_read_b128 v[86:89], v2
	ds_read_b128 v[110:113], v2 offset:2048
	s_waitcnt lgkmcnt(1)
	v_mfma_f32_16x16x32_bf16 v[4:7], v[86:89], v[32:35], v[4:7]
	s_mov_b32 m0, s18
	v_mfma_f32_16x16x32_bf16 v[8:11], v[86:89], v[48:51], v[8:11]
	s_waitcnt lgkmcnt(0)
	v_mfma_f32_16x16x32_bf16 v[12:15], v[110:113], v[32:35], v[12:15]
	v_mfma_f32_16x16x32_bf16 v[16:19], v[110:113], v[48:51], v[16:19]
	ds_read_b128 v[86:89], v2 offset:4096
	ds_read_b128 v[110:113], v2 offset:6144
	s_waitcnt lgkmcnt(1)
	v_mfma_f32_16x16x32_bf16 v[114:117], v[86:89], v[32:35], v[114:117]
	v_mfma_f32_16x16x32_bf16 v[86:89], v[86:89], v[48:51], v[28:31]
	s_waitcnt lgkmcnt(0)
	v_mfma_f32_16x16x32_bf16 v[28:31], v[110:113], v[32:35], v[24:27]
	v_mfma_f32_16x16x32_bf16 v[20:23], v[110:113], v[48:51], v[20:23]
	ds_read_b128 v[32:35], v108 offset:2048
	ds_read_b128 v[48:51], v108
	ds_read_b128 v[24:27], v109 offset:18432
	ds_read_b128 v[110:113], v109 offset:16384
	s_waitcnt lgkmcnt(0)
	v_mfma_f32_16x16x32_bf16 v[4:7], v[48:51], v[110:113], v[4:7]
	v_mfma_f32_16x16x32_bf16 v[8:11], v[48:51], v[24:27], v[8:11]
	v_mfma_f32_16x16x32_bf16 v[12:15], v[32:35], v[110:113], v[12:15]
	v_mfma_f32_16x16x32_bf16 v[16:19], v[32:35], v[24:27], v[16:19]
	ds_read_b128 v[48:51], v108 offset:4096
	ds_read_b128 v[32:35], v108 offset:6144
	global_load_lds_dwordx4 v[46:47], off
	s_mov_b32 m0, s47
	s_waitcnt lgkmcnt(0)
	v_mfma_f32_16x16x32_bf16 v[114:117], v[48:51], v[110:113], v[114:117]
	global_load_lds_dwordx4 v[40:41], off
	s_mov_b32 m0, s48
	v_mfma_f32_16x16x32_bf16 v[48:51], v[48:51], v[24:27], v[86:89]
	global_load_lds_dwordx4 v[42:43], off
	s_mov_b32 m0, s49
	v_mfma_f32_16x16x32_bf16 v[28:31], v[32:35], v[110:113], v[28:31]
	global_load_lds_dwordx4 v[44:45], off
	s_mov_b32 m0, s50
	v_mfma_f32_16x16x32_bf16 v[20:23], v[32:35], v[24:27], v[20:23]
	global_load_lds_dwordx4 v[36:37], off
	s_mov_b32 m0, s51
	s_nop 0
	global_load_lds_dwordx4 v[38:39], off
	s_setprio 0
	s_waitcnt vmcnt(0) lgkmcnt(0)
	s_barrier
	ds_read_b128 v[24:27], v107 offset:40960
	ds_read_b128 v[32:35], v107 offset:43008
	ds_read_b128 v[86:89], v2 offset:24576
	ds_read_b128 v[110:113], v2 offset:26624
	s_waitcnt lgkmcnt(1)
	v_mfma_f32_16x16x32_bf16 v[4:7], v[86:89], v[24:27], v[4:7]
	s_mov_b32 m0, s22
	v_mfma_f32_16x16x32_bf16 v[8:11], v[86:89], v[32:35], v[8:11]
	s_waitcnt lgkmcnt(0)
	v_mfma_f32_16x16x32_bf16 v[12:15], v[110:113], v[24:27], v[12:15]
	v_mfma_f32_16x16x32_bf16 v[16:19], v[110:113], v[32:35], v[16:19]
	ds_read_b128 v[86:89], v2 offset:28672
	ds_read_b128 v[110:113], v2 offset:30720
	s_waitcnt lgkmcnt(1)
	v_mfma_f32_16x16x32_bf16 v[114:117], v[86:89], v[24:27], v[114:117]
	v_mfma_f32_16x16x32_bf16 v[48:51], v[86:89], v[32:35], v[48:51]
	s_waitcnt lgkmcnt(0)
	v_mfma_f32_16x16x32_bf16 v[24:27], v[110:113], v[24:27], v[28:31]
	v_mfma_f32_16x16x32_bf16 v[20:23], v[110:113], v[32:35], v[20:23]
	s_nop 1
	ds_read_b128 v[28:31], v108 offset:26624
	ds_read_b128 v[32:35], v108 offset:24576
	ds_read_b128 v[86:89], v109 offset:43008
	ds_read_b128 v[110:113], v109 offset:40960
	s_waitcnt lgkmcnt(0)
	v_mfma_f32_16x16x32_bf16 v[118:121], v[32:35], v[110:113], v[4:7]
	v_mfma_f32_16x16x32_bf16 v[12:15], v[28:31], v[110:113], v[12:15]
	v_mfma_f32_16x16x32_bf16 v[4:7], v[28:31], v[86:89], v[16:19]
	s_nop 2
	ds_read_b128 v[16:19], v108 offset:28672
	ds_read_b128 v[28:31], v108 offset:30720
	global_load_lds_dwordx4 v[46:47], off
	s_mov_b32 m0, s10
	v_mfma_f32_16x16x32_bf16 v[8:11], v[32:35], v[86:89], v[8:11]
	global_load_lds_dwordx4 v[40:41], off
	s_mov_b32 m0, s11
	s_waitcnt lgkmcnt(0)
	v_mfma_f32_16x16x32_bf16 v[32:35], v[16:19], v[110:113], v[114:117]
	global_load_lds_dwordx4 v[42:43], off
	s_mov_b32 m0, s24
	v_mfma_f32_16x16x32_bf16 v[16:19], v[16:19], v[86:89], v[48:51]
	global_load_lds_dwordx4 v[44:45], off
	s_mov_b32 m0, s25
	v_mfma_f32_16x16x32_bf16 v[24:27], v[28:31], v[110:113], v[24:27]
	global_load_lds_dwordx4 v[36:37], off
	s_mov_b32 m0, s46
	v_mfma_f32_16x16x32_bf16 v[20:23], v[28:31], v[86:89], v[20:23]
	global_load_lds_dwordx4 v[38:39], off
	s_setprio 0
	v_lshlrev_b32_e32 v28, 16, v91
	v_and_b32_e32 v29, 0xffff0000, v91
	v_pk_fma_f32 v[82:83], v[118:119], v[28:29], v[82:83]
	v_lshlrev_b32_e32 v28, 16, v92
	v_and_b32_e32 v29, 0xffff0000, v92
	v_pk_fma_f32 v[80:81], v[120:121], v[28:29], v[80:81]
	v_lshlrev_b32_e32 v28, 16, v93
	v_and_b32_e32 v29, 0xffff0000, v93
	v_pk_fma_f32 v[78:79], v[8:9], v[28:29], v[78:79]
	v_lshlrev_b32_e32 v8, 16, v94
	v_and_b32_e32 v9, 0xffff0000, v94
	v_pk_fma_f32 v[76:77], v[10:11], v[8:9], v[76:77]
	v_lshlrev_b32_e32 v8, 16, v95
	v_and_b32_e32 v9, 0xffff0000, v95
	v_pk_fma_f32 v[74:75], v[12:13], v[8:9], v[74:75]
	v_lshlrev_b32_e32 v8, 16, v96
	v_and_b32_e32 v9, 0xffff0000, v96
	v_pk_fma_f32 v[72:73], v[14:15], v[8:9], v[72:73]
	v_lshlrev_b32_e32 v8, 16, v97
	v_and_b32_e32 v9, 0xffff0000, v97
	v_pk_fma_f32 v[70:71], v[4:5], v[8:9], v[70:71]
	v_lshlrev_b32_e32 v4, 16, v98
	v_and_b32_e32 v5, 0xffff0000, v98
	v_pk_fma_f32 v[68:69], v[6:7], v[4:5], v[68:69]
	v_lshlrev_b32_e32 v4, 16, v99
	v_and_b32_e32 v5, 0xffff0000, v99
	v_pk_fma_f32 v[66:67], v[32:33], v[4:5], v[66:67]
	v_lshlrev_b32_e32 v4, 16, v100
	v_and_b32_e32 v5, 0xffff0000, v100
	v_pk_fma_f32 v[64:65], v[34:35], v[4:5], v[64:65]
	v_lshlrev_b32_e32 v4, 16, v101
	v_and_b32_e32 v5, 0xffff0000, v101
	v_pk_fma_f32 v[62:63], v[16:17], v[4:5], v[62:63]
	v_lshlrev_b32_e32 v4, 16, v102
	v_and_b32_e32 v5, 0xffff0000, v102
	v_pk_fma_f32 v[60:61], v[18:19], v[4:5], v[60:61]
	v_lshlrev_b32_e32 v4, 16, v103
	v_and_b32_e32 v5, 0xffff0000, v103
	v_pk_fma_f32 v[58:59], v[24:25], v[4:5], v[58:59]
	v_lshlrev_b32_e32 v4, 16, v104
	v_and_b32_e32 v5, 0xffff0000, v104
	s_add_i32 s21, s21, 1
	v_pk_fma_f32 v[56:57], v[26:27], v[4:5], v[56:57]
	v_lshlrev_b32_e32 v4, 16, v105
	v_and_b32_e32 v5, 0xffff0000, v105
	s_add_u32 s42, s42, 0x200000
	v_pk_fma_f32 v[54:55], v[20:21], v[4:5], v[54:55]
	v_lshlrev_b32_e32 v4, 16, v106
	v_and_b32_e32 v5, 0xffff0000, v106
	s_addc_u32 s43, s43, 0
	s_cmp_lg_u32 s21, 4
	v_pk_fma_f32 v[52:53], v[22:23], v[4:5], v[52:53]
	s_waitcnt vmcnt(0) lgkmcnt(0)
	s_barrier
; DEVI int get_tid() { int t = threadIdx.x; asm volatile("" : "+v"(t)); return t; }
; template <int BN>
; DEVI void tile_store(const char* smem, bf* __restrict__ C, long ldc, long row0, int col0) {
;   constexpr int LDT = BN + 8;
;   const int tid = get_tid();
;   const int r = tid >> 1, half = tid & 1;
; #pragma unroll
;   for (int c = 0; c < BN / 16; ++c) {
;     u32x4 v = *reinterpret_cast<const u32x4*>(smem + (r * LDT + half * (BN / 2) + c * 8) * 2);
;     *reinterpret_cast<u32x4*>(C + (row0 + r) * ldc + col0 + half * (BN / 2) + c * 8) = v;
;   }
; }
; template <int NTW>
; DEVI void merge_tile(const P& p, long row0, int n0, char* smem) {
;     ...
;   bf* tl = reinterpret_cast<bf*>(smem);
; #pragma unroll
;   for (int m = 0; m < 4; ++m)
; #pragma unroll
;     for (int n = 0; n < NTW; ++n) {
;       const int cl = wc * 16 * NTW + n * 16 + l15;
; #pragma unroll
;       for (int j = 0; j < 4; ++j) tl[(wr * 64 + m * 16 + quad * 4 + j) * LDT + cl] = f2bf(accM[m][n][j]);
;     }
;   __syncthreads();
;   tile_store<BN>(smem, p.UZ, DM, row0, n0);
;   __syncthreads();
	s_cbranch_scc1 .LBB0_220
	v_and_b32_e32 v2, 15, v1
	v_lshrrev_b32_e32 v5, 2, v1
	v_lshrrev_b32_e32 v4, 1, v1
	v_and_b32_e32 v5, 12, v5
	v_lshlrev_b32_e32 v2, 1, v2
	v_and_or_b32 v4, v4, s27, v5
	v_and_or_b32 v2, v1, 64, v2
	s_movk_i32 s10, 0x90
	v_cvt_pk_bf16_f32 v1, v82, s0
	v_mad_u64_u32 v[4:5], s[10:11], v4, s10, v[2:3]
	ds_write_b16 v4, v1
	v_cvt_pk_bf16_f32 v1, v83, s0
	ds_write_b16 v4, v1 offset:144
	v_cvt_pk_bf16_f32 v1, v80, s0
	ds_write_b16 v4, v1 offset:288
	v_cvt_pk_bf16_f32 v1, v81, s0
	ds_write_b16 v4, v1 offset:432
	v_cvt_pk_bf16_f32 v1, v78, s0
	ds_write_b16 v4, v1 offset:32
	v_cvt_pk_bf16_f32 v1, v79, s0
	ds_write_b16 v4, v1 offset:176
	v_cvt_pk_bf16_f32 v1, v76, s0
	ds_write_b16 v4, v1 offset:320
	v_cvt_pk_bf16_f32 v1, v77, s0
	ds_write_b16 v4, v1 offset:464
	v_cvt_pk_bf16_f32 v1, v74, s0
	ds_write_b16 v4, v1 offset:2304
	v_cvt_pk_bf16_f32 v1, v75, s0
	ds_write_b16 v4, v1 offset:2448
	v_cvt_pk_bf16_f32 v1, v72, s0
	ds_write_b16 v4, v1 offset:2592
	v_cvt_pk_bf16_f32 v1, v73, s0
	ds_write_b16 v4, v1 offset:2736
	v_cvt_pk_bf16_f32 v1, v70, s0
	ds_write_b16 v4, v1 offset:2336
	v_cvt_pk_bf16_f32 v1, v71, s0
	ds_write_b16 v4, v1 offset:2480
	v_cvt_pk_bf16_f32 v1, v68, s0
	ds_write_b16 v4, v1 offset:2624
	v_cvt_pk_bf16_f32 v1, v69, s0
	ds_write_b16 v4, v1 offset:2768
	v_cvt_pk_bf16_f32 v1, v66, s0
	ds_write_b16 v4, v1 offset:4608
	v_cvt_pk_bf16_f32 v1, v67, s0
	ds_write_b16 v4, v1 offset:4752
	v_cvt_pk_bf16_f32 v1, v64, s0
	ds_write_b16 v4, v1 offset:4896
	v_cvt_pk_bf16_f32 v1, v65, s0
	ds_write_b16 v4, v1 offset:5040
	v_cvt_pk_bf16_f32 v1, v62, s0
	ds_write_b16 v4, v1 offset:4640
	v_cvt_pk_bf16_f32 v1, v63, s0
	ds_write_b16 v4, v1 offset:4784
	v_cvt_pk_bf16_f32 v1, v60, s0
	ds_write_b16 v4, v1 offset:4928
	v_cvt_pk_bf16_f32 v1, v61, s0
	ds_write_b16 v4, v1 offset:5072
	v_cvt_pk_bf16_f32 v1, v58, s0
	ds_write_b16 v4, v1 offset:6912
	v_cvt_pk_bf16_f32 v1, v59, s0
	ds_write_b16 v4, v1 offset:7056
	v_cvt_pk_bf16_f32 v1, v56, s0
	ds_write_b16 v4, v1 offset:7200
	v_cvt_pk_bf16_f32 v1, v57, s0
	ds_write_b16 v4, v1 offset:7344
	v_cvt_pk_bf16_f32 v1, v54, s0
	ds_write_b16 v4, v1 offset:6944
	v_cvt_pk_bf16_f32 v1, v55, s0
	ds_write_b16 v4, v1 offset:7088
	v_cvt_pk_bf16_f32 v1, v52, s0
	ds_write_b16 v4, v1 offset:7232
	v_cvt_pk_bf16_f32 v1, v53, s0
	ds_write_b16 v4, v1 offset:7376
	v_mov_b32_e32 v1, v178
	s_waitcnt lgkmcnt(0)
	s_barrier
	s_movk_i32 s10, 0x48
	v_ashrrev_i32_e32 v4, 1, v1
	v_ashrrev_i32_e32 v5, 31, v4
	v_mul_lo_u32 v6, v4, s10
	v_lshlrev_b32_e32 v1, 5, v1
	v_lshl_add_u64 v[4:5], v[4:5], 0, s[38:39]
	v_readlane_b32 s64, v251, 58
	v_and_b32_e32 v1, 32, v1
	v_lshlrev_b64 v[4:5], 11, v[4:5]
	v_readlane_b32 s66, v251, 60
	v_readlane_b32 s67, v251, 61
	v_readlane_b32 s10, v252, 59
	v_lshlrev_b32_e32 v2, 1, v1
	v_lshl_add_u64 v[4:5], s[66:67], 0, v[4:5]
	v_add_lshl_u32 v1, v6, v1, 1
	v_readlane_b32 s11, v252, 60
	v_lshl_add_u64 v[20:21], s[40:41], 1, v[4:5]
	ds_read_b128 v[4:7], v1
	ds_read_b128 v[8:11], v1 offset:16
	ds_read_b128 v[12:15], v1 offset:32
	ds_read_b128 v[16:19], v1 offset:48
	v_readlane_b32 s11, v254, 56
	s_add_i32 s12, s12, s10
	s_add_i32 s3, s3, s11
	s_add_i32 s2, s2, s10
	v_readlane_b32 s10, v254, 52
	v_readlane_b32 s11, v254, 53
	s_xor_b64 s[34:35], s[34:35], s[10:11]
	v_readlane_b32 s65, v251, 59
	v_readlane_b32 s70, v252, 0
	v_readlane_b32 s71, v252, 1
	v_lshl_add_u64 v[20:21], v[20:21], 0, v[2:3]
	s_cmp_gt_i32 s12, 63
	v_readlane_b32 s68, v251, 62
	v_readlane_b32 s69, v251, 63
	v_readlane_b32 s72, v252, 2
	v_readlane_b32 s73, v252, 3
	v_readlane_b32 s74, v252, 4
	v_readlane_b32 s75, v252, 5
	v_readlane_b32 s76, v252, 6
	v_readlane_b32 s77, v252, 7
	v_readlane_b32 s78, v252, 8
	v_readlane_b32 s79, v252, 9
	s_waitcnt lgkmcnt(3)
	global_store_dwordx4 v[20:21], v[4:7], off
	s_waitcnt lgkmcnt(2)
	global_store_dwordx4 v[20:21], v[8:11], off offset:16
	s_waitcnt lgkmcnt(1)
	global_store_dwordx4 v[20:21], v[12:15], off offset:32
	s_waitcnt lgkmcnt(0)
	global_store_dwordx4 v[20:21], v[16:19], off offset:48
	s_barrier
	s_cbranch_scc0 .LBB0_219
